# K-loop MMA blocks: accumulate chains ordered so that consecutive chains reuse the same A-operand registers (four chains per A fragment pair)
# speedup vs baseline: 1.0164x; 1.0072x over previous
.LBB0_322:
	s_ashr_i32 s43, s42, 31
	s_lshl_b64 s[46:47], s[42:43], 19
	s_add_u32 s46, s12, s46
	s_addc_u32 s47, s13, s47
	s_and_b64 s[48:49], s[4:5], exec
	s_cselect_b32 s18, s47, s7
	s_cselect_b32 s43, s46, s6
	s_ashr_i32 s45, s44, 31
	s_lshl_b64 s[48:49], s[44:45], 19
	s_add_u32 s48, s59, s48
	s_addc_u32 s49, s60, s49
	s_and_b64 s[50:51], s[4:5], exec
	s_cselect_b32 s45, s49, s9
	s_cselect_b32 s55, s48, s8
	s_add_u32 s6, s6, 0x40080
	s_addc_u32 s7, s7, 0
	s_add_u32 s56, s8, 0x100
	s_addc_u32 s57, s9, 0
	s_mov_b32 s78, -2
	ds_read_b128 v[96:99], v209
	ds_read_b128 v[100:103], v209 offset:1024
	ds_read_b128 v[120:123], v209 offset:2048
	ds_read_b128 v[124:127], v209 offset:3072
	ds_read_b128 v[144:147], v210
	ds_read_b128 v[148:151], v210 offset:1024
	ds_read_b128 v[152:155], v210 offset:2048
	ds_read_b128 v[156:159], v210 offset:3072
	s_add_u32 s8, s6, 0xfffc0080
	s_addc_u32 s9, s7, -1
	s_cmp_eq_u32 s78, 12
	s_cselect_b32 s51, s18, s9
	s_cselect_b32 s50, s43, s8
	s_cselect_b32 s9, s45, s57
	s_cselect_b32 s8, s55, s56
	v_lshl_add_u64 v[206:207], s[6:7], 0, v[170:171]
	s_add_i32 m0, s17, 0xc000
	ds_read_b128 v[178:181], v211
	ds_read_b128 v[182:185], v211 offset:1024
	ds_read_b128 v[186:189], v211 offset:2048
	ds_read_b128 v[190:193], v211 offset:3072
	ds_read_b128 v[194:197], v211 offset:4096
	ds_read_b128 v[198:201], v211 offset:5120
	ds_read_b128 v[202:205], v211 offset:6144
	ds_read_b128 v[218:221], v211 offset:7168
	global_load_lds_dwordx4 v[206:207], off
	s_add_i32 m0, s17, 0xe000
	v_lshl_add_u64 v[206:207], s[6:7], 0, v[172:173]
	global_load_lds_dwordx4 v[206:207], off
	s_waitcnt vmcnt(8) lgkmcnt(0)
	s_barrier
	s_setprio 1
	v_mfma_f32_16x16x32_bf16 v[140:143], v[96:99], v[178:181], 0
	v_mfma_f32_16x16x32_bf16 v[140:143], v[100:103], v[182:185], v[140:143]
	v_mfma_f32_16x16x32_bf16 v[116:119], v[96:99], v[186:189], 0
	v_mfma_f32_16x16x32_bf16 v[116:119], v[100:103], v[190:193], v[116:119]
	v_mfma_f32_16x16x32_bf16 v[92:95], v[96:99], v[194:197], 0
	v_mfma_f32_16x16x32_bf16 v[92:95], v[100:103], v[198:201], v[92:95]
	v_mfma_f32_16x16x32_bf16 v[76:79], v[96:99], v[202:205], 0
	v_mfma_f32_16x16x32_bf16 v[76:79], v[100:103], v[218:221], v[76:79]
	v_mfma_f32_16x16x32_bf16 v[136:139], v[120:123], v[178:181], 0
	v_mfma_f32_16x16x32_bf16 v[136:139], v[124:127], v[182:185], v[136:139]
	v_mfma_f32_16x16x32_bf16 v[112:115], v[120:123], v[186:189], 0
	v_mfma_f32_16x16x32_bf16 v[112:115], v[124:127], v[190:193], v[112:115]
	v_mfma_f32_16x16x32_bf16 v[88:91], v[120:123], v[194:197], 0
	v_mfma_f32_16x16x32_bf16 v[88:91], v[124:127], v[198:201], v[88:91]
	v_mfma_f32_16x16x32_bf16 v[72:75], v[120:123], v[202:205], 0
	v_mfma_f32_16x16x32_bf16 v[72:75], v[124:127], v[218:221], v[72:75]
	v_mfma_f32_16x16x32_bf16 v[132:135], v[144:147], v[178:181], 0
	v_mfma_f32_16x16x32_bf16 v[132:135], v[148:151], v[182:185], v[132:135]
	v_mfma_f32_16x16x32_bf16 v[108:111], v[144:147], v[186:189], 0
	v_mfma_f32_16x16x32_bf16 v[108:111], v[148:151], v[190:193], v[108:111]
	v_mfma_f32_16x16x32_bf16 v[84:87], v[144:147], v[194:197], 0
	v_mfma_f32_16x16x32_bf16 v[84:87], v[148:151], v[198:201], v[84:87]
	v_mfma_f32_16x16x32_bf16 v[68:71], v[144:147], v[202:205], 0
	v_mfma_f32_16x16x32_bf16 v[68:71], v[148:151], v[218:221], v[68:71]
	v_mfma_f32_16x16x32_bf16 v[128:131], v[152:155], v[178:181], 0
	v_mfma_f32_16x16x32_bf16 v[128:131], v[156:159], v[182:185], v[128:131]
	v_mfma_f32_16x16x32_bf16 v[104:107], v[152:155], v[186:189], 0
	v_mfma_f32_16x16x32_bf16 v[104:107], v[156:159], v[190:193], v[104:107]
	s_setprio 2
	s_barrier
	v_mfma_f32_16x16x32_bf16 v[80:83], v[152:155], v[194:197], 0
	v_mfma_f32_16x16x32_bf16 v[80:83], v[156:159], v[198:201], v[80:83]
	v_mfma_f32_16x16x32_bf16 v[64:67], v[152:155], v[202:205], 0
	v_mfma_f32_16x16x32_bf16 v[64:67], v[156:159], v[218:221], v[64:67]
	s_setprio 2
	s_add_i32 s79, s73, s61
	v_lshl_add_u64 v[206:207], s[8:9], 0, v[162:163]
	s_mov_b32 m0, s79
	ds_read_b128 v[178:181], v211 offset:16384
	ds_read_b128 v[182:185], v211 offset:17408
	ds_read_b128 v[186:189], v211 offset:18432
	ds_read_b128 v[190:193], v211 offset:19456
	ds_read_b128 v[194:197], v211 offset:20480
	ds_read_b128 v[198:201], v211 offset:21504
	ds_read_b128 v[202:205], v211 offset:22528
	ds_read_b128 v[218:221], v211 offset:23552
	global_load_lds_dwordx4 v[206:207], off
	s_add_i32 m0, s79, 0x2000
	s_add_u32 s80, s8, 0x40000
	v_lshl_add_u64 v[222:223], s[8:9], 0, v[166:167]
	s_addc_u32 s81, s9, 0
	s_add_i32 s79, s74, s61
	global_load_lds_dwordx4 v[222:223], off
	v_lshl_add_u64 v[224:225], s[80:81], 0, v[162:163]
	s_mov_b32 m0, s79
	v_lshl_add_u64 v[226:227], s[50:51], 0, v[164:165]
	global_load_lds_dwordx4 v[224:225], off
	s_add_i32 m0, s79, 0x2000
	v_lshl_add_u64 v[224:225], s[80:81], 0, v[166:167]
	global_load_lds_dwordx4 v[224:225], off
	s_mov_b32 m0, s17
	v_lshl_add_u64 v[224:225], s[50:51], 0, v[160:161]
	global_load_lds_dwordx4 v[224:225], off
	s_mov_b32 m0, s62
	s_nop 0
	global_load_lds_dwordx4 v[226:227], off
	s_waitcnt vmcnt(8) lgkmcnt(0)
	s_barrier
	s_setprio 1
	v_mfma_f32_16x16x32_bf16 v[60:63], v[96:99], v[178:181], 0
	v_mfma_f32_16x16x32_bf16 v[60:63], v[100:103], v[182:185], v[60:63]
	v_mfma_f32_16x16x32_bf16 v[44:47], v[96:99], v[186:189], 0
	v_mfma_f32_16x16x32_bf16 v[44:47], v[100:103], v[190:193], v[44:47]
	v_mfma_f32_16x16x32_bf16 v[28:31], v[96:99], v[194:197], 0
	v_mfma_f32_16x16x32_bf16 v[28:31], v[100:103], v[198:201], v[28:31]
	v_mfma_f32_16x16x32_bf16 v[12:15], v[96:99], v[202:205], 0
	v_mfma_f32_16x16x32_bf16 v[12:15], v[100:103], v[218:221], v[12:15]
	v_mfma_f32_16x16x32_bf16 v[56:59], v[120:123], v[178:181], 0
	v_mfma_f32_16x16x32_bf16 v[56:59], v[124:127], v[182:185], v[56:59]
	v_mfma_f32_16x16x32_bf16 v[40:43], v[120:123], v[186:189], 0
	v_mfma_f32_16x16x32_bf16 v[40:43], v[124:127], v[190:193], v[40:43]
	v_mfma_f32_16x16x32_bf16 v[24:27], v[120:123], v[194:197], 0
	v_mfma_f32_16x16x32_bf16 v[24:27], v[124:127], v[198:201], v[24:27]
	v_mfma_f32_16x16x32_bf16 v[8:11], v[120:123], v[202:205], 0
	v_mfma_f32_16x16x32_bf16 v[8:11], v[124:127], v[218:221], v[8:11]
	v_mfma_f32_16x16x32_bf16 v[52:55], v[144:147], v[178:181], 0
	v_mfma_f32_16x16x32_bf16 v[52:55], v[148:151], v[182:185], v[52:55]
	v_mfma_f32_16x16x32_bf16 v[36:39], v[144:147], v[186:189], 0
	v_mfma_f32_16x16x32_bf16 v[36:39], v[148:151], v[190:193], v[36:39]
	v_mfma_f32_16x16x32_bf16 v[20:23], v[144:147], v[194:197], 0
	v_mfma_f32_16x16x32_bf16 v[20:23], v[148:151], v[198:201], v[20:23]
	v_mfma_f32_16x16x32_bf16 v[4:7], v[144:147], v[202:205], 0
	v_mfma_f32_16x16x32_bf16 v[4:7], v[148:151], v[218:221], v[4:7]
	v_mfma_f32_16x16x32_bf16 v[48:51], v[152:155], v[178:181], 0
	v_mfma_f32_16x16x32_bf16 v[48:51], v[156:159], v[182:185], v[48:51]
	v_mfma_f32_16x16x32_bf16 v[32:35], v[152:155], v[186:189], 0
	v_mfma_f32_16x16x32_bf16 v[32:35], v[156:159], v[190:193], v[32:35]
	s_setprio 2
	s_barrier
	v_mfma_f32_16x16x32_bf16 v[16:19], v[152:155], v[194:197], 0
	v_mfma_f32_16x16x32_bf16 v[16:19], v[156:159], v[198:201], v[16:19]
	v_mfma_f32_16x16x32_bf16 v[0:3], v[152:155], v[202:205], 0
	v_mfma_f32_16x16x32_bf16 v[0:3], v[156:159], v[218:221], v[0:3]
	s_setprio 0
	s_add_i32 s79, 0, 0x18000
	s_add_i32 s80, 0, 0x1c000
	v_add_u32_e32 v124, s79, v208
	v_add_u32_e32 v156, s80, v208
	ds_read_b128 v[96:99], v124
	ds_read_b128 v[100:103], v124 offset:1024
	ds_read_b128 v[120:123], v124 offset:2048
	ds_read_b128 v[124:127], v124 offset:3072
	ds_read_b128 v[144:147], v156
	ds_read_b128 v[148:151], v156 offset:1024
	ds_read_b128 v[152:155], v156 offset:2048
	ds_read_b128 v[156:159], v156 offset:3072
	s_add_u32 s50, s50, 0x40000
	s_addc_u32 s51, s51, 0
	s_mov_b32 m0, s63
	v_lshl_add_u64 v[228:229], s[50:51], 0, v[160:161]
	ds_read_b128 v[178:181], v211 offset:32768
	ds_read_b128 v[182:185], v211 offset:33792
	ds_read_b128 v[186:189], v211 offset:34816
	ds_read_b128 v[190:193], v211 offset:35840
	ds_read_b128 v[194:197], v211 offset:36864
	ds_read_b128 v[198:201], v211 offset:37888
	ds_read_b128 v[202:205], v211 offset:38912
	ds_read_b128 v[218:221], v211 offset:39936
	global_load_lds_dwordx4 v[228:229], off
	s_mov_b32 m0, s64
	v_lshl_add_u64 v[228:229], s[50:51], 0, v[164:165]
	global_load_lds_dwordx4 v[228:229], off
	s_waitcnt vmcnt(8) lgkmcnt(0)
	s_barrier
	s_setprio 1
	v_mfma_f32_16x16x32_bf16 v[140:143], v[96:99], v[178:181], v[140:143]
	v_mfma_f32_16x16x32_bf16 v[140:143], v[100:103], v[182:185], v[140:143]
	v_mfma_f32_16x16x32_bf16 v[116:119], v[96:99], v[186:189], v[116:119]
	v_mfma_f32_16x16x32_bf16 v[116:119], v[100:103], v[190:193], v[116:119]
	v_mfma_f32_16x16x32_bf16 v[92:95], v[96:99], v[194:197], v[92:95]
	v_mfma_f32_16x16x32_bf16 v[92:95], v[100:103], v[198:201], v[92:95]
	v_mfma_f32_16x16x32_bf16 v[76:79], v[96:99], v[202:205], v[76:79]
	v_mfma_f32_16x16x32_bf16 v[76:79], v[100:103], v[218:221], v[76:79]
	v_mfma_f32_16x16x32_bf16 v[136:139], v[120:123], v[178:181], v[136:139]
	v_mfma_f32_16x16x32_bf16 v[136:139], v[124:127], v[182:185], v[136:139]
	v_mfma_f32_16x16x32_bf16 v[112:115], v[120:123], v[186:189], v[112:115]
	v_mfma_f32_16x16x32_bf16 v[112:115], v[124:127], v[190:193], v[112:115]
	v_mfma_f32_16x16x32_bf16 v[88:91], v[120:123], v[194:197], v[88:91]
	v_mfma_f32_16x16x32_bf16 v[88:91], v[124:127], v[198:201], v[88:91]
	v_mfma_f32_16x16x32_bf16 v[72:75], v[120:123], v[202:205], v[72:75]
	v_mfma_f32_16x16x32_bf16 v[72:75], v[124:127], v[218:221], v[72:75]
	v_mfma_f32_16x16x32_bf16 v[132:135], v[144:147], v[178:181], v[132:135]
	v_mfma_f32_16x16x32_bf16 v[132:135], v[148:151], v[182:185], v[132:135]
	v_mfma_f32_16x16x32_bf16 v[108:111], v[144:147], v[186:189], v[108:111]
	v_mfma_f32_16x16x32_bf16 v[108:111], v[148:151], v[190:193], v[108:111]
	v_mfma_f32_16x16x32_bf16 v[84:87], v[144:147], v[194:197], v[84:87]
	v_mfma_f32_16x16x32_bf16 v[84:87], v[148:151], v[198:201], v[84:87]
	v_mfma_f32_16x16x32_bf16 v[68:71], v[144:147], v[202:205], v[68:71]
	v_mfma_f32_16x16x32_bf16 v[68:71], v[148:151], v[218:221], v[68:71]
	v_mfma_f32_16x16x32_bf16 v[128:131], v[152:155], v[178:181], v[128:131]
	v_mfma_f32_16x16x32_bf16 v[128:131], v[156:159], v[182:185], v[128:131]
	v_mfma_f32_16x16x32_bf16 v[104:107], v[152:155], v[186:189], v[104:107]
	v_mfma_f32_16x16x32_bf16 v[104:107], v[156:159], v[190:193], v[104:107]
	s_setprio 2
	s_barrier
	v_mfma_f32_16x16x32_bf16 v[80:83], v[152:155], v[194:197], v[80:83]
	v_mfma_f32_16x16x32_bf16 v[80:83], v[156:159], v[198:201], v[80:83]
	v_mfma_f32_16x16x32_bf16 v[64:67], v[152:155], v[202:205], v[64:67]
	v_mfma_f32_16x16x32_bf16 v[64:67], v[156:159], v[218:221], v[64:67]
	s_setprio 2
	s_add_i32 s50, s79, s61
	v_lshl_add_u64 v[206:207], v[206:207], 0, s[36:37]
	s_mov_b32 m0, s50
	ds_read_b128 v[178:181], v211 offset:49152
	ds_read_b128 v[182:185], v211 offset:50176
	ds_read_b128 v[186:189], v211 offset:51200
	ds_read_b128 v[190:193], v211 offset:52224
	ds_read_b128 v[194:197], v211 offset:53248
	ds_read_b128 v[198:201], v211 offset:54272
	ds_read_b128 v[202:205], v211 offset:55296
	ds_read_b128 v[218:221], v211 offset:56320
	global_load_lds_dwordx4 v[206:207], off
	s_add_i32 m0, s50, 0x2000
	s_add_u32 s8, s8, 0x40080
	v_lshl_add_u64 v[206:207], v[222:223], 0, s[36:37]
	s_addc_u32 s9, s9, 0
	s_add_i32 s50, s80, s61
	global_load_lds_dwordx4 v[206:207], off
	s_mov_b32 m0, s50
	v_lshl_add_u64 v[206:207], s[8:9], 0, v[162:163]
	global_load_lds_dwordx4 v[206:207], off
	s_add_i32 m0, s50, 0x2000
	v_lshl_add_u64 v[206:207], s[8:9], 0, v[166:167]
	global_load_lds_dwordx4 v[206:207], off
	s_mov_b32 m0, s68
	v_lshl_add_u64 v[206:207], v[224:225], 0, s[36:37]
	global_load_lds_dwordx4 v[206:207], off
	s_mov_b32 m0, s69
	v_lshl_add_u64 v[206:207], v[226:227], 0, s[36:37]
	global_load_lds_dwordx4 v[206:207], off
	s_waitcnt vmcnt(8) lgkmcnt(0)
	s_barrier
	s_setprio 1
	v_mfma_f32_16x16x32_bf16 v[60:63], v[96:99], v[178:181], v[60:63]
	v_mfma_f32_16x16x32_bf16 v[60:63], v[100:103], v[182:185], v[60:63]
	v_mfma_f32_16x16x32_bf16 v[44:47], v[96:99], v[186:189], v[44:47]
	v_mfma_f32_16x16x32_bf16 v[44:47], v[100:103], v[190:193], v[44:47]
	v_mfma_f32_16x16x32_bf16 v[28:31], v[96:99], v[194:197], v[28:31]
	v_mfma_f32_16x16x32_bf16 v[28:31], v[100:103], v[198:201], v[28:31]
	v_mfma_f32_16x16x32_bf16 v[12:15], v[96:99], v[202:205], v[12:15]
	v_mfma_f32_16x16x32_bf16 v[12:15], v[100:103], v[218:221], v[12:15]
	v_mfma_f32_16x16x32_bf16 v[56:59], v[120:123], v[178:181], v[56:59]
	v_mfma_f32_16x16x32_bf16 v[56:59], v[124:127], v[182:185], v[56:59]
	v_mfma_f32_16x16x32_bf16 v[40:43], v[120:123], v[186:189], v[40:43]
	v_mfma_f32_16x16x32_bf16 v[40:43], v[124:127], v[190:193], v[40:43]
	v_mfma_f32_16x16x32_bf16 v[24:27], v[120:123], v[194:197], v[24:27]
	v_mfma_f32_16x16x32_bf16 v[24:27], v[124:127], v[198:201], v[24:27]
	v_mfma_f32_16x16x32_bf16 v[8:11], v[120:123], v[202:205], v[8:11]
	v_mfma_f32_16x16x32_bf16 v[8:11], v[124:127], v[218:221], v[8:11]
	v_mfma_f32_16x16x32_bf16 v[52:55], v[144:147], v[178:181], v[52:55]
	v_mfma_f32_16x16x32_bf16 v[52:55], v[148:151], v[182:185], v[52:55]
	v_mfma_f32_16x16x32_bf16 v[36:39], v[144:147], v[186:189], v[36:39]
	v_mfma_f32_16x16x32_bf16 v[36:39], v[148:151], v[190:193], v[36:39]
	v_mfma_f32_16x16x32_bf16 v[20:23], v[144:147], v[194:197], v[20:23]
	v_mfma_f32_16x16x32_bf16 v[20:23], v[148:151], v[198:201], v[20:23]
	v_mfma_f32_16x16x32_bf16 v[4:7], v[144:147], v[202:205], v[4:7]
	v_mfma_f32_16x16x32_bf16 v[4:7], v[148:151], v[218:221], v[4:7]
	v_mfma_f32_16x16x32_bf16 v[48:51], v[152:155], v[178:181], v[48:51]
	v_mfma_f32_16x16x32_bf16 v[48:51], v[156:159], v[182:185], v[48:51]
	v_mfma_f32_16x16x32_bf16 v[32:35], v[152:155], v[186:189], v[32:35]
	v_mfma_f32_16x16x32_bf16 v[32:35], v[156:159], v[190:193], v[32:35]
	s_setprio 2
	s_barrier
	v_mfma_f32_16x16x32_bf16 v[16:19], v[152:155], v[194:197], v[16:19]
	v_mfma_f32_16x16x32_bf16 v[16:19], v[156:159], v[198:201], v[16:19]
	v_mfma_f32_16x16x32_bf16 v[0:3], v[152:155], v[202:205], v[0:3]
	v_mfma_f32_16x16x32_bf16 v[0:3], v[156:159], v[218:221], v[0:3]
	s_setprio 0
	s_add_i32 s78, s78, 2
	s_add_u32 s6, s6, 0x100
	s_addc_u32 s7, s7, 0
	s_add_u32 s56, s56, 0x100
	s_addc_u32 s57, s57, 0
	s_cmp_gt_u32 s78, 13
.LBB0_323:
	ds_read_b128 v[96:99], v209
	ds_read_b128 v[100:103], v209 offset:1024
	ds_read_b128 v[120:123], v209 offset:2048
	ds_read_b128 v[124:127], v209 offset:3072
	ds_read_b128 v[144:147], v210
	ds_read_b128 v[148:151], v210 offset:1024
	ds_read_b128 v[152:155], v210 offset:2048
	ds_read_b128 v[156:159], v210 offset:3072
	s_add_u32 s8, s6, 0xfffc0080
	s_addc_u32 s9, s7, -1
	s_cmp_eq_u32 s78, 12
	s_cselect_b32 s51, s18, s9
	s_cselect_b32 s50, s43, s8
	s_cselect_b32 s9, s45, s57
	s_cselect_b32 s8, s55, s56
	v_lshl_add_u64 v[206:207], s[6:7], 0, v[170:171]
	s_add_i32 m0, s17, 0xc000
	ds_read_b128 v[178:181], v211
	ds_read_b128 v[182:185], v211 offset:1024
	ds_read_b128 v[186:189], v211 offset:2048
	ds_read_b128 v[190:193], v211 offset:3072
	ds_read_b128 v[194:197], v211 offset:4096
	ds_read_b128 v[198:201], v211 offset:5120
	ds_read_b128 v[202:205], v211 offset:6144
	ds_read_b128 v[218:221], v211 offset:7168
	global_load_lds_dwordx4 v[206:207], off
	s_add_i32 m0, s17, 0xe000
	v_lshl_add_u64 v[206:207], s[6:7], 0, v[172:173]
	global_load_lds_dwordx4 v[206:207], off
	s_waitcnt vmcnt(8) lgkmcnt(0)
	s_barrier
	s_setprio 1
	v_mfma_f32_16x16x32_bf16 v[140:143], v[96:99], v[178:181], v[140:143]
	v_mfma_f32_16x16x32_bf16 v[140:143], v[100:103], v[182:185], v[140:143]
	v_mfma_f32_16x16x32_bf16 v[116:119], v[96:99], v[186:189], v[116:119]
	v_mfma_f32_16x16x32_bf16 v[116:119], v[100:103], v[190:193], v[116:119]
	v_mfma_f32_16x16x32_bf16 v[92:95], v[96:99], v[194:197], v[92:95]
	v_mfma_f32_16x16x32_bf16 v[92:95], v[100:103], v[198:201], v[92:95]
	v_mfma_f32_16x16x32_bf16 v[76:79], v[96:99], v[202:205], v[76:79]
	v_mfma_f32_16x16x32_bf16 v[76:79], v[100:103], v[218:221], v[76:79]
	v_mfma_f32_16x16x32_bf16 v[136:139], v[120:123], v[178:181], v[136:139]
	v_mfma_f32_16x16x32_bf16 v[136:139], v[124:127], v[182:185], v[136:139]
	v_mfma_f32_16x16x32_bf16 v[112:115], v[120:123], v[186:189], v[112:115]
	v_mfma_f32_16x16x32_bf16 v[112:115], v[124:127], v[190:193], v[112:115]
	v_mfma_f32_16x16x32_bf16 v[88:91], v[120:123], v[194:197], v[88:91]
	v_mfma_f32_16x16x32_bf16 v[88:91], v[124:127], v[198:201], v[88:91]
	v_mfma_f32_16x16x32_bf16 v[72:75], v[120:123], v[202:205], v[72:75]
	v_mfma_f32_16x16x32_bf16 v[72:75], v[124:127], v[218:221], v[72:75]
	v_mfma_f32_16x16x32_bf16 v[132:135], v[144:147], v[178:181], v[132:135]
	v_mfma_f32_16x16x32_bf16 v[132:135], v[148:151], v[182:185], v[132:135]
	v_mfma_f32_16x16x32_bf16 v[108:111], v[144:147], v[186:189], v[108:111]
	v_mfma_f32_16x16x32_bf16 v[108:111], v[148:151], v[190:193], v[108:111]
	v_mfma_f32_16x16x32_bf16 v[84:87], v[144:147], v[194:197], v[84:87]
	v_mfma_f32_16x16x32_bf16 v[84:87], v[148:151], v[198:201], v[84:87]
	v_mfma_f32_16x16x32_bf16 v[68:71], v[144:147], v[202:205], v[68:71]
	v_mfma_f32_16x16x32_bf16 v[68:71], v[148:151], v[218:221], v[68:71]
	v_mfma_f32_16x16x32_bf16 v[128:131], v[152:155], v[178:181], v[128:131]
	v_mfma_f32_16x16x32_bf16 v[128:131], v[156:159], v[182:185], v[128:131]
	v_mfma_f32_16x16x32_bf16 v[104:107], v[152:155], v[186:189], v[104:107]
	v_mfma_f32_16x16x32_bf16 v[104:107], v[156:159], v[190:193], v[104:107]
	s_setprio 2
	s_barrier
	v_mfma_f32_16x16x32_bf16 v[80:83], v[152:155], v[194:197], v[80:83]
	v_mfma_f32_16x16x32_bf16 v[80:83], v[156:159], v[198:201], v[80:83]
	v_mfma_f32_16x16x32_bf16 v[64:67], v[152:155], v[202:205], v[64:67]
	v_mfma_f32_16x16x32_bf16 v[64:67], v[156:159], v[218:221], v[64:67]
	s_setprio 2
	s_add_i32 s79, s73, s61
	v_lshl_add_u64 v[206:207], s[8:9], 0, v[162:163]
	s_mov_b32 m0, s79
	ds_read_b128 v[178:181], v211 offset:16384
	ds_read_b128 v[182:185], v211 offset:17408
	ds_read_b128 v[186:189], v211 offset:18432
	ds_read_b128 v[190:193], v211 offset:19456
	ds_read_b128 v[194:197], v211 offset:20480
	ds_read_b128 v[198:201], v211 offset:21504
	ds_read_b128 v[202:205], v211 offset:22528
	ds_read_b128 v[218:221], v211 offset:23552
	global_load_lds_dwordx4 v[206:207], off
	s_add_i32 m0, s79, 0x2000
	s_add_u32 s80, s8, 0x40000
	v_lshl_add_u64 v[222:223], s[8:9], 0, v[166:167]
	s_addc_u32 s81, s9, 0
	s_add_i32 s79, s74, s61
	global_load_lds_dwordx4 v[222:223], off
	v_lshl_add_u64 v[224:225], s[80:81], 0, v[162:163]
	s_mov_b32 m0, s79
	v_lshl_add_u64 v[226:227], s[50:51], 0, v[164:165]
	global_load_lds_dwordx4 v[224:225], off
	s_add_i32 m0, s79, 0x2000
	v_lshl_add_u64 v[224:225], s[80:81], 0, v[166:167]
	global_load_lds_dwordx4 v[224:225], off
	s_mov_b32 m0, s17
	v_lshl_add_u64 v[224:225], s[50:51], 0, v[160:161]
	global_load_lds_dwordx4 v[224:225], off
	s_mov_b32 m0, s62
	s_nop 0
	global_load_lds_dwordx4 v[226:227], off
	s_waitcnt vmcnt(8) lgkmcnt(0)
	s_barrier
	s_setprio 1
	v_mfma_f32_16x16x32_bf16 v[60:63], v[96:99], v[178:181], v[60:63]
	v_mfma_f32_16x16x32_bf16 v[60:63], v[100:103], v[182:185], v[60:63]
	v_mfma_f32_16x16x32_bf16 v[44:47], v[96:99], v[186:189], v[44:47]
	v_mfma_f32_16x16x32_bf16 v[44:47], v[100:103], v[190:193], v[44:47]
	v_mfma_f32_16x16x32_bf16 v[28:31], v[96:99], v[194:197], v[28:31]
	v_mfma_f32_16x16x32_bf16 v[28:31], v[100:103], v[198:201], v[28:31]
	v_mfma_f32_16x16x32_bf16 v[12:15], v[96:99], v[202:205], v[12:15]
	v_mfma_f32_16x16x32_bf16 v[12:15], v[100:103], v[218:221], v[12:15]
	v_mfma_f32_16x16x32_bf16 v[56:59], v[120:123], v[178:181], v[56:59]
	v_mfma_f32_16x16x32_bf16 v[56:59], v[124:127], v[182:185], v[56:59]
	v_mfma_f32_16x16x32_bf16 v[40:43], v[120:123], v[186:189], v[40:43]
	v_mfma_f32_16x16x32_bf16 v[40:43], v[124:127], v[190:193], v[40:43]
	v_mfma_f32_16x16x32_bf16 v[24:27], v[120:123], v[194:197], v[24:27]
	v_mfma_f32_16x16x32_bf16 v[24:27], v[124:127], v[198:201], v[24:27]
	v_mfma_f32_16x16x32_bf16 v[8:11], v[120:123], v[202:205], v[8:11]
	v_mfma_f32_16x16x32_bf16 v[8:11], v[124:127], v[218:221], v[8:11]
	v_mfma_f32_16x16x32_bf16 v[52:55], v[144:147], v[178:181], v[52:55]
	v_mfma_f32_16x16x32_bf16 v[52:55], v[148:151], v[182:185], v[52:55]
	v_mfma_f32_16x16x32_bf16 v[36:39], v[144:147], v[186:189], v[36:39]
	v_mfma_f32_16x16x32_bf16 v[36:39], v[148:151], v[190:193], v[36:39]
	v_mfma_f32_16x16x32_bf16 v[20:23], v[144:147], v[194:197], v[20:23]
	v_mfma_f32_16x16x32_bf16 v[20:23], v[148:151], v[198:201], v[20:23]
	v_mfma_f32_16x16x32_bf16 v[4:7], v[144:147], v[202:205], v[4:7]
	v_mfma_f32_16x16x32_bf16 v[4:7], v[148:151], v[218:221], v[4:7]
	v_mfma_f32_16x16x32_bf16 v[48:51], v[152:155], v[178:181], v[48:51]
	v_mfma_f32_16x16x32_bf16 v[48:51], v[156:159], v[182:185], v[48:51]
	v_mfma_f32_16x16x32_bf16 v[32:35], v[152:155], v[186:189], v[32:35]
	v_mfma_f32_16x16x32_bf16 v[32:35], v[156:159], v[190:193], v[32:35]
	s_setprio 2
	s_barrier
	v_mfma_f32_16x16x32_bf16 v[16:19], v[152:155], v[194:197], v[16:19]
	v_mfma_f32_16x16x32_bf16 v[16:19], v[156:159], v[198:201], v[16:19]
	v_mfma_f32_16x16x32_bf16 v[0:3], v[152:155], v[202:205], v[0:3]
	v_mfma_f32_16x16x32_bf16 v[0:3], v[156:159], v[218:221], v[0:3]
	s_setprio 0
	s_add_i32 s79, 0, 0x18000
	s_add_i32 s80, 0, 0x1c000
	v_add_u32_e32 v124, s79, v208
	v_add_u32_e32 v156, s80, v208
	ds_read_b128 v[96:99], v124
	ds_read_b128 v[100:103], v124 offset:1024
	ds_read_b128 v[120:123], v124 offset:2048
	ds_read_b128 v[124:127], v124 offset:3072
	ds_read_b128 v[144:147], v156
	ds_read_b128 v[148:151], v156 offset:1024
	ds_read_b128 v[152:155], v156 offset:2048
	ds_read_b128 v[156:159], v156 offset:3072
	s_add_u32 s50, s50, 0x40000
	s_addc_u32 s51, s51, 0
	s_mov_b32 m0, s63
	v_lshl_add_u64 v[228:229], s[50:51], 0, v[160:161]
	ds_read_b128 v[178:181], v211 offset:32768
	ds_read_b128 v[182:185], v211 offset:33792
	ds_read_b128 v[186:189], v211 offset:34816
	ds_read_b128 v[190:193], v211 offset:35840
	ds_read_b128 v[194:197], v211 offset:36864
	ds_read_b128 v[198:201], v211 offset:37888
	ds_read_b128 v[202:205], v211 offset:38912
	ds_read_b128 v[218:221], v211 offset:39936
	global_load_lds_dwordx4 v[228:229], off
	s_mov_b32 m0, s64
	v_lshl_add_u64 v[228:229], s[50:51], 0, v[164:165]
	global_load_lds_dwordx4 v[228:229], off
	s_waitcnt vmcnt(8) lgkmcnt(0)
	s_barrier
	s_setprio 1
	v_mfma_f32_16x16x32_bf16 v[140:143], v[96:99], v[178:181], v[140:143]
	v_mfma_f32_16x16x32_bf16 v[140:143], v[100:103], v[182:185], v[140:143]
	v_mfma_f32_16x16x32_bf16 v[116:119], v[96:99], v[186:189], v[116:119]
	v_mfma_f32_16x16x32_bf16 v[116:119], v[100:103], v[190:193], v[116:119]
	v_mfma_f32_16x16x32_bf16 v[92:95], v[96:99], v[194:197], v[92:95]
	v_mfma_f32_16x16x32_bf16 v[92:95], v[100:103], v[198:201], v[92:95]
	v_mfma_f32_16x16x32_bf16 v[76:79], v[96:99], v[202:205], v[76:79]
	v_mfma_f32_16x16x32_bf16 v[76:79], v[100:103], v[218:221], v[76:79]
	v_mfma_f32_16x16x32_bf16 v[136:139], v[120:123], v[178:181], v[136:139]
	v_mfma_f32_16x16x32_bf16 v[136:139], v[124:127], v[182:185], v[136:139]
	v_mfma_f32_16x16x32_bf16 v[112:115], v[120:123], v[186:189], v[112:115]
	v_mfma_f32_16x16x32_bf16 v[112:115], v[124:127], v[190:193], v[112:115]
	v_mfma_f32_16x16x32_bf16 v[88:91], v[120:123], v[194:197], v[88:91]
	v_mfma_f32_16x16x32_bf16 v[88:91], v[124:127], v[198:201], v[88:91]
	v_mfma_f32_16x16x32_bf16 v[72:75], v[120:123], v[202:205], v[72:75]
	v_mfma_f32_16x16x32_bf16 v[72:75], v[124:127], v[218:221], v[72:75]
	v_mfma_f32_16x16x32_bf16 v[132:135], v[144:147], v[178:181], v[132:135]
	v_mfma_f32_16x16x32_bf16 v[132:135], v[148:151], v[182:185], v[132:135]
	v_mfma_f32_16x16x32_bf16 v[108:111], v[144:147], v[186:189], v[108:111]
	v_mfma_f32_16x16x32_bf16 v[108:111], v[148:151], v[190:193], v[108:111]
	v_mfma_f32_16x16x32_bf16 v[84:87], v[144:147], v[194:197], v[84:87]
	v_mfma_f32_16x16x32_bf16 v[84:87], v[148:151], v[198:201], v[84:87]
	v_mfma_f32_16x16x32_bf16 v[68:71], v[144:147], v[202:205], v[68:71]
	v_mfma_f32_16x16x32_bf16 v[68:71], v[148:151], v[218:221], v[68:71]
	v_mfma_f32_16x16x32_bf16 v[128:131], v[152:155], v[178:181], v[128:131]
	v_mfma_f32_16x16x32_bf16 v[128:131], v[156:159], v[182:185], v[128:131]
	v_mfma_f32_16x16x32_bf16 v[104:107], v[152:155], v[186:189], v[104:107]
	v_mfma_f32_16x16x32_bf16 v[104:107], v[156:159], v[190:193], v[104:107]
	s_setprio 2
	s_barrier
	v_mfma_f32_16x16x32_bf16 v[80:83], v[152:155], v[194:197], v[80:83]
	v_mfma_f32_16x16x32_bf16 v[80:83], v[156:159], v[198:201], v[80:83]
	v_mfma_f32_16x16x32_bf16 v[64:67], v[152:155], v[202:205], v[64:67]
	v_mfma_f32_16x16x32_bf16 v[64:67], v[156:159], v[218:221], v[64:67]
	s_setprio 2
	s_add_i32 s50, s79, s61
	v_lshl_add_u64 v[206:207], v[206:207], 0, s[36:37]
	s_mov_b32 m0, s50
	ds_read_b128 v[178:181], v211 offset:49152
	ds_read_b128 v[182:185], v211 offset:50176
	ds_read_b128 v[186:189], v211 offset:51200
	ds_read_b128 v[190:193], v211 offset:52224
	ds_read_b128 v[194:197], v211 offset:53248
	ds_read_b128 v[198:201], v211 offset:54272
	ds_read_b128 v[202:205], v211 offset:55296
	ds_read_b128 v[218:221], v211 offset:56320
	global_load_lds_dwordx4 v[206:207], off
	s_add_i32 m0, s50, 0x2000
	s_add_u32 s8, s8, 0x40080
	v_lshl_add_u64 v[206:207], v[222:223], 0, s[36:37]
	s_addc_u32 s9, s9, 0
	s_add_i32 s50, s80, s61
	global_load_lds_dwordx4 v[206:207], off
	s_mov_b32 m0, s50
	v_lshl_add_u64 v[206:207], s[8:9], 0, v[162:163]
	global_load_lds_dwordx4 v[206:207], off
	s_add_i32 m0, s50, 0x2000
	v_lshl_add_u64 v[206:207], s[8:9], 0, v[166:167]
	global_load_lds_dwordx4 v[206:207], off
	s_mov_b32 m0, s68
	v_lshl_add_u64 v[206:207], v[224:225], 0, s[36:37]
	global_load_lds_dwordx4 v[206:207], off
	s_mov_b32 m0, s69
	v_lshl_add_u64 v[206:207], v[226:227], 0, s[36:37]
	global_load_lds_dwordx4 v[206:207], off
	s_waitcnt vmcnt(8) lgkmcnt(0)
	s_barrier
	s_setprio 1
	v_mfma_f32_16x16x32_bf16 v[60:63], v[96:99], v[178:181], v[60:63]
	v_mfma_f32_16x16x32_bf16 v[60:63], v[100:103], v[182:185], v[60:63]
	v_mfma_f32_16x16x32_bf16 v[44:47], v[96:99], v[186:189], v[44:47]
	v_mfma_f32_16x16x32_bf16 v[44:47], v[100:103], v[190:193], v[44:47]
	v_mfma_f32_16x16x32_bf16 v[28:31], v[96:99], v[194:197], v[28:31]
	v_mfma_f32_16x16x32_bf16 v[28:31], v[100:103], v[198:201], v[28:31]
	v_mfma_f32_16x16x32_bf16 v[12:15], v[96:99], v[202:205], v[12:15]
	v_mfma_f32_16x16x32_bf16 v[12:15], v[100:103], v[218:221], v[12:15]
	v_mfma_f32_16x16x32_bf16 v[56:59], v[120:123], v[178:181], v[56:59]
	v_mfma_f32_16x16x32_bf16 v[56:59], v[124:127], v[182:185], v[56:59]
	v_mfma_f32_16x16x32_bf16 v[40:43], v[120:123], v[186:189], v[40:43]
	v_mfma_f32_16x16x32_bf16 v[40:43], v[124:127], v[190:193], v[40:43]
	v_mfma_f32_16x16x32_bf16 v[24:27], v[120:123], v[194:197], v[24:27]
	v_mfma_f32_16x16x32_bf16 v[24:27], v[124:127], v[198:201], v[24:27]
	v_mfma_f32_16x16x32_bf16 v[8:11], v[120:123], v[202:205], v[8:11]
	v_mfma_f32_16x16x32_bf16 v[8:11], v[124:127], v[218:221], v[8:11]
	v_mfma_f32_16x16x32_bf16 v[52:55], v[144:147], v[178:181], v[52:55]
	v_mfma_f32_16x16x32_bf16 v[52:55], v[148:151], v[182:185], v[52:55]
	v_mfma_f32_16x16x32_bf16 v[36:39], v[144:147], v[186:189], v[36:39]
	v_mfma_f32_16x16x32_bf16 v[36:39], v[148:151], v[190:193], v[36:39]
	v_mfma_f32_16x16x32_bf16 v[20:23], v[144:147], v[194:197], v[20:23]
	v_mfma_f32_16x16x32_bf16 v[20:23], v[148:151], v[198:201], v[20:23]
	v_mfma_f32_16x16x32_bf16 v[4:7], v[144:147], v[202:205], v[4:7]
	v_mfma_f32_16x16x32_bf16 v[4:7], v[148:151], v[218:221], v[4:7]
	v_mfma_f32_16x16x32_bf16 v[48:51], v[152:155], v[178:181], v[48:51]
	v_mfma_f32_16x16x32_bf16 v[48:51], v[156:159], v[182:185], v[48:51]
	v_mfma_f32_16x16x32_bf16 v[32:35], v[152:155], v[186:189], v[32:35]
	v_mfma_f32_16x16x32_bf16 v[32:35], v[156:159], v[190:193], v[32:35]
	s_setprio 2
	s_barrier
	v_mfma_f32_16x16x32_bf16 v[16:19], v[152:155], v[194:197], v[16:19]
	v_mfma_f32_16x16x32_bf16 v[16:19], v[156:159], v[198:201], v[16:19]
	v_mfma_f32_16x16x32_bf16 v[0:3], v[152:155], v[202:205], v[0:3]
	v_mfma_f32_16x16x32_bf16 v[0:3], v[156:159], v[218:221], v[0:3]
	s_setprio 0
	s_add_i32 s78, s78, 2
	s_add_u32 s6, s6, 0x100
	s_addc_u32 s7, s7, 0
	s_add_u32 s56, s56, 0x100
	s_addc_u32 s57, s57, 0
	s_cmp_gt_u32 s78, 13
	s_cbranch_scc0 .LBB0_323

.LBB0_700:
	ds_read_b128 v[130:133], v203
	ds_read_b128 v[134:137], v203 offset:1024
	ds_read_b128 v[138:141], v203 offset:2048
	ds_read_b128 v[142:145], v203 offset:3072
	ds_read_b128 v[146:149], v195
	ds_read_b128 v[150:153], v195 offset:1024
	ds_read_b128 v[154:157], v195 offset:2048
	ds_read_b128 v[158:161], v195 offset:3072
	s_add_u32 s47, s44, 0xfff80080
	s_addc_u32 s48, s45, -1
	s_cmp_eq_u32 s46, 28
	s_cselect_b32 s49, s29, s48
	s_cselect_b32 s48, s71, s47
	s_cselect_b32 s47, s31, s84
	s_cselect_b32 s46, s72, s83
	s_mov_b32 m0, s73
	v_lshl_add_u64 v[174:175], s[44:45], 0, v[180:181]
	ds_read_b128 v[162:165], v211
	ds_read_b128 v[166:169], v211 offset:1024
	ds_read_b128 v[170:173], v211 offset:2048
	ds_read_b128 v[184:187], v211 offset:3072
	ds_read_b128 v[190:193], v211 offset:4096
	ds_read_b128 v[196:199], v211 offset:5120
	ds_read_b128 v[204:207], v211 offset:6144
	ds_read_b128 v[212:215], v211 offset:7168
	global_load_lds_dwordx4 v[174:175], off
	s_mov_b32 m0, s74
	v_lshl_add_u64 v[174:175], s[44:45], 0, v[182:183]
	global_load_lds_dwordx4 v[174:175], off
	s_waitcnt vmcnt(8) lgkmcnt(0)
	s_barrier
	s_setprio 1
	v_mfma_f32_16x16x32_bf16 v[124:127], v[130:133], v[162:165], v[124:127]
	v_mfma_f32_16x16x32_bf16 v[124:127], v[134:137], v[166:169], v[124:127]
	v_mfma_f32_16x16x32_bf16 v[108:111], v[130:133], v[170:173], v[108:111]
	v_mfma_f32_16x16x32_bf16 v[108:111], v[134:137], v[184:187], v[108:111]
	v_mfma_f32_16x16x32_bf16 v[92:95], v[130:133], v[190:193], v[92:95]
	v_mfma_f32_16x16x32_bf16 v[92:95], v[134:137], v[196:199], v[92:95]
	v_mfma_f32_16x16x32_bf16 v[76:79], v[130:133], v[204:207], v[76:79]
	v_mfma_f32_16x16x32_bf16 v[76:79], v[134:137], v[212:215], v[76:79]
	v_mfma_f32_16x16x32_bf16 v[120:123], v[138:141], v[162:165], v[120:123]
	v_mfma_f32_16x16x32_bf16 v[120:123], v[142:145], v[166:169], v[120:123]
	v_mfma_f32_16x16x32_bf16 v[104:107], v[138:141], v[170:173], v[104:107]
	v_mfma_f32_16x16x32_bf16 v[104:107], v[142:145], v[184:187], v[104:107]
	v_mfma_f32_16x16x32_bf16 v[88:91], v[138:141], v[190:193], v[88:91]
	v_mfma_f32_16x16x32_bf16 v[88:91], v[142:145], v[196:199], v[88:91]
	v_mfma_f32_16x16x32_bf16 v[72:75], v[138:141], v[204:207], v[72:75]
	v_mfma_f32_16x16x32_bf16 v[72:75], v[142:145], v[212:215], v[72:75]
	v_mfma_f32_16x16x32_bf16 v[116:119], v[146:149], v[162:165], v[116:119]
	v_mfma_f32_16x16x32_bf16 v[116:119], v[150:153], v[166:169], v[116:119]
	v_mfma_f32_16x16x32_bf16 v[100:103], v[146:149], v[170:173], v[100:103]
	v_mfma_f32_16x16x32_bf16 v[100:103], v[150:153], v[184:187], v[100:103]
	v_mfma_f32_16x16x32_bf16 v[84:87], v[146:149], v[190:193], v[84:87]
	v_mfma_f32_16x16x32_bf16 v[84:87], v[150:153], v[196:199], v[84:87]
	v_mfma_f32_16x16x32_bf16 v[68:71], v[146:149], v[204:207], v[68:71]
	v_mfma_f32_16x16x32_bf16 v[68:71], v[150:153], v[212:215], v[68:71]
	v_mfma_f32_16x16x32_bf16 v[112:115], v[154:157], v[162:165], v[112:115]
	v_mfma_f32_16x16x32_bf16 v[112:115], v[158:161], v[166:169], v[112:115]
	v_mfma_f32_16x16x32_bf16 v[96:99], v[154:157], v[170:173], v[96:99]
	v_mfma_f32_16x16x32_bf16 v[96:99], v[158:161], v[184:187], v[96:99]
	s_setprio 2
	s_barrier
	v_mfma_f32_16x16x32_bf16 v[80:83], v[154:157], v[190:193], v[80:83]
	v_mfma_f32_16x16x32_bf16 v[80:83], v[158:161], v[196:199], v[80:83]
	v_mfma_f32_16x16x32_bf16 v[64:67], v[154:157], v[204:207], v[64:67]
	v_mfma_f32_16x16x32_bf16 v[64:67], v[158:161], v[212:215], v[64:67]
	s_setprio 2
	s_mov_b32 m0, s75
	v_lshl_add_u64 v[174:175], s[46:47], 0, v[176:177]
	s_add_u32 s86, s46, 0x80000
	ds_read_b128 v[162:165], v211 offset:16384
	ds_read_b128 v[166:169], v211 offset:17408
	ds_read_b128 v[170:173], v211 offset:18432
	ds_read_b128 v[184:187], v211 offset:19456
	ds_read_b128 v[190:193], v211 offset:20480
	ds_read_b128 v[196:199], v211 offset:21504
	ds_read_b128 v[204:207], v211 offset:22528
	ds_read_b128 v[212:215], v211 offset:23552
	global_load_lds_dwordx4 v[174:175], off
	v_lshl_add_u64 v[200:201], s[46:47], 0, v[178:179]
	s_mov_b32 m0, s76
	s_addc_u32 s87, s47, 0
	global_load_lds_dwordx4 v[200:201], off
	v_lshl_add_u64 v[208:209], s[86:87], 0, v[176:177]
	s_mov_b32 m0, s77
	v_lshl_add_u64 v[216:217], s[48:49], 0, v[178:179]
	global_load_lds_dwordx4 v[208:209], off
	s_mov_b32 m0, s78
	v_lshl_add_u64 v[208:209], s[86:87], 0, v[178:179]
	global_load_lds_dwordx4 v[208:209], off
	s_mov_b32 m0, s56
	v_lshl_add_u64 v[208:209], s[48:49], 0, v[176:177]
	global_load_lds_dwordx4 v[208:209], off
	s_mov_b32 m0, s57
	s_nop 0
	global_load_lds_dwordx4 v[216:217], off
	s_waitcnt vmcnt(8) lgkmcnt(0)
	s_barrier
	s_setprio 1
	v_mfma_f32_16x16x32_bf16 v[60:63], v[130:133], v[162:165], v[60:63]
	v_mfma_f32_16x16x32_bf16 v[60:63], v[134:137], v[166:169], v[60:63]
	v_mfma_f32_16x16x32_bf16 v[44:47], v[130:133], v[170:173], v[44:47]
	v_mfma_f32_16x16x32_bf16 v[44:47], v[134:137], v[184:187], v[44:47]
	v_mfma_f32_16x16x32_bf16 v[28:31], v[130:133], v[190:193], v[28:31]
	v_mfma_f32_16x16x32_bf16 v[28:31], v[134:137], v[196:199], v[28:31]
	v_mfma_f32_16x16x32_bf16 v[12:15], v[130:133], v[204:207], v[12:15]
	v_mfma_f32_16x16x32_bf16 v[12:15], v[134:137], v[212:215], v[12:15]
	v_mfma_f32_16x16x32_bf16 v[56:59], v[138:141], v[162:165], v[56:59]
	v_mfma_f32_16x16x32_bf16 v[56:59], v[142:145], v[166:169], v[56:59]
	v_mfma_f32_16x16x32_bf16 v[40:43], v[138:141], v[170:173], v[40:43]
	v_mfma_f32_16x16x32_bf16 v[40:43], v[142:145], v[184:187], v[40:43]
	v_mfma_f32_16x16x32_bf16 v[24:27], v[138:141], v[190:193], v[24:27]
	v_mfma_f32_16x16x32_bf16 v[24:27], v[142:145], v[196:199], v[24:27]
	v_mfma_f32_16x16x32_bf16 v[8:11], v[138:141], v[204:207], v[8:11]
	v_mfma_f32_16x16x32_bf16 v[8:11], v[142:145], v[212:215], v[8:11]
	v_mfma_f32_16x16x32_bf16 v[52:55], v[146:149], v[162:165], v[52:55]
	v_mfma_f32_16x16x32_bf16 v[52:55], v[150:153], v[166:169], v[52:55]
	v_mfma_f32_16x16x32_bf16 v[36:39], v[146:149], v[170:173], v[36:39]
	v_mfma_f32_16x16x32_bf16 v[36:39], v[150:153], v[184:187], v[36:39]
	v_mfma_f32_16x16x32_bf16 v[20:23], v[146:149], v[190:193], v[20:23]
	v_mfma_f32_16x16x32_bf16 v[20:23], v[150:153], v[196:199], v[20:23]
	v_mfma_f32_16x16x32_bf16 v[4:7], v[146:149], v[204:207], v[4:7]
	v_mfma_f32_16x16x32_bf16 v[4:7], v[150:153], v[212:215], v[4:7]
	v_mfma_f32_16x16x32_bf16 v[48:51], v[154:157], v[162:165], v[48:51]
	v_mfma_f32_16x16x32_bf16 v[48:51], v[158:161], v[166:169], v[48:51]
	v_mfma_f32_16x16x32_bf16 v[32:35], v[154:157], v[170:173], v[32:35]
	v_mfma_f32_16x16x32_bf16 v[32:35], v[158:161], v[184:187], v[32:35]
	s_setprio 2
	s_barrier
	v_mfma_f32_16x16x32_bf16 v[16:19], v[154:157], v[190:193], v[16:19]
	v_mfma_f32_16x16x32_bf16 v[16:19], v[158:161], v[196:199], v[16:19]
	v_mfma_f32_16x16x32_bf16 v[0:3], v[154:157], v[204:207], v[0:3]
	v_mfma_f32_16x16x32_bf16 v[0:3], v[158:161], v[212:215], v[0:3]
	s_setprio 0
	ds_read_b128 v[130:133], v128
	ds_read_b128 v[134:137], v128 offset:1024
	ds_read_b128 v[138:141], v128 offset:2048
	ds_read_b128 v[142:145], v128 offset:3072
	ds_read_b128 v[146:149], v129
	ds_read_b128 v[150:153], v129 offset:1024
	ds_read_b128 v[154:157], v129 offset:2048
	ds_read_b128 v[158:161], v129 offset:3072
	s_add_u32 s48, s48, 0x80000
	s_addc_u32 s49, s49, 0
	s_mov_b32 m0, s58
	v_lshl_add_u64 v[218:219], s[48:49], 0, v[176:177]
	ds_read_b128 v[162:165], v211 offset:32768
	ds_read_b128 v[166:169], v211 offset:33792
	ds_read_b128 v[170:173], v211 offset:34816
	ds_read_b128 v[184:187], v211 offset:35840
	ds_read_b128 v[190:193], v211 offset:36864
	ds_read_b128 v[196:199], v211 offset:37888
	ds_read_b128 v[204:207], v211 offset:38912
	ds_read_b128 v[212:215], v211 offset:39936
	global_load_lds_dwordx4 v[218:219], off
	s_mov_b32 m0, s59
	v_lshl_add_u64 v[218:219], s[48:49], 0, v[178:179]
	global_load_lds_dwordx4 v[218:219], off
	s_waitcnt vmcnt(8) lgkmcnt(0)
	s_barrier
	s_setprio 1
	v_mfma_f32_16x16x32_bf16 v[124:127], v[130:133], v[162:165], v[124:127]
	v_mfma_f32_16x16x32_bf16 v[124:127], v[134:137], v[166:169], v[124:127]
	v_mfma_f32_16x16x32_bf16 v[108:111], v[130:133], v[170:173], v[108:111]
	v_mfma_f32_16x16x32_bf16 v[108:111], v[134:137], v[184:187], v[108:111]
	v_mfma_f32_16x16x32_bf16 v[92:95], v[130:133], v[190:193], v[92:95]
	v_mfma_f32_16x16x32_bf16 v[92:95], v[134:137], v[196:199], v[92:95]
	v_mfma_f32_16x16x32_bf16 v[76:79], v[130:133], v[204:207], v[76:79]
	v_mfma_f32_16x16x32_bf16 v[76:79], v[134:137], v[212:215], v[76:79]
	v_mfma_f32_16x16x32_bf16 v[120:123], v[138:141], v[162:165], v[120:123]
	v_mfma_f32_16x16x32_bf16 v[120:123], v[142:145], v[166:169], v[120:123]
	v_mfma_f32_16x16x32_bf16 v[104:107], v[138:141], v[170:173], v[104:107]
	v_mfma_f32_16x16x32_bf16 v[104:107], v[142:145], v[184:187], v[104:107]
	v_mfma_f32_16x16x32_bf16 v[88:91], v[138:141], v[190:193], v[88:91]
	v_mfma_f32_16x16x32_bf16 v[88:91], v[142:145], v[196:199], v[88:91]
	v_mfma_f32_16x16x32_bf16 v[72:75], v[138:141], v[204:207], v[72:75]
	v_mfma_f32_16x16x32_bf16 v[72:75], v[142:145], v[212:215], v[72:75]
	v_mfma_f32_16x16x32_bf16 v[116:119], v[146:149], v[162:165], v[116:119]
	v_mfma_f32_16x16x32_bf16 v[116:119], v[150:153], v[166:169], v[116:119]
	v_mfma_f32_16x16x32_bf16 v[100:103], v[146:149], v[170:173], v[100:103]
	v_mfma_f32_16x16x32_bf16 v[100:103], v[150:153], v[184:187], v[100:103]
	v_mfma_f32_16x16x32_bf16 v[84:87], v[146:149], v[190:193], v[84:87]
	v_mfma_f32_16x16x32_bf16 v[84:87], v[150:153], v[196:199], v[84:87]
	v_mfma_f32_16x16x32_bf16 v[68:71], v[146:149], v[204:207], v[68:71]
	v_mfma_f32_16x16x32_bf16 v[68:71], v[150:153], v[212:215], v[68:71]
	v_mfma_f32_16x16x32_bf16 v[112:115], v[154:157], v[162:165], v[112:115]
	v_mfma_f32_16x16x32_bf16 v[112:115], v[158:161], v[166:169], v[112:115]
	v_mfma_f32_16x16x32_bf16 v[96:99], v[154:157], v[170:173], v[96:99]
	v_mfma_f32_16x16x32_bf16 v[96:99], v[158:161], v[184:187], v[96:99]
	s_setprio 2
	s_barrier
	v_mfma_f32_16x16x32_bf16 v[80:83], v[154:157], v[190:193], v[80:83]
	v_mfma_f32_16x16x32_bf16 v[80:83], v[158:161], v[196:199], v[80:83]
	v_mfma_f32_16x16x32_bf16 v[64:67], v[154:157], v[204:207], v[64:67]
	v_mfma_f32_16x16x32_bf16 v[64:67], v[158:161], v[212:215], v[64:67]
	s_setprio 2
	s_mov_b32 m0, s79
	v_lshl_add_u64 v[174:175], v[174:175], 0, s[20:21]
	s_add_u32 s46, s46, 0x80080
	ds_read_b128 v[162:165], v211 offset:49152
	ds_read_b128 v[166:169], v211 offset:50176
	ds_read_b128 v[170:173], v211 offset:51200
	ds_read_b128 v[184:187], v211 offset:52224
	ds_read_b128 v[190:193], v211 offset:53248
	ds_read_b128 v[196:199], v211 offset:54272
	ds_read_b128 v[204:207], v211 offset:55296
	ds_read_b128 v[212:215], v211 offset:56320
	global_load_lds_dwordx4 v[174:175], off
	v_lshl_add_u64 v[174:175], v[200:201], 0, s[20:21]
	s_mov_b32 m0, s80
	s_addc_u32 s47, s47, 0
	global_load_lds_dwordx4 v[174:175], off
	s_mov_b32 m0, s81
	v_lshl_add_u64 v[174:175], s[46:47], 0, v[176:177]
	global_load_lds_dwordx4 v[174:175], off
	s_mov_b32 m0, s82
	v_lshl_add_u64 v[174:175], s[46:47], 0, v[178:179]
	global_load_lds_dwordx4 v[174:175], off
	s_mov_b32 m0, s61
	v_lshl_add_u64 v[174:175], v[208:209], 0, s[20:21]
	global_load_lds_dwordx4 v[174:175], off
	s_mov_b32 m0, s62
	v_lshl_add_u64 v[174:175], v[216:217], 0, s[20:21]
	global_load_lds_dwordx4 v[174:175], off
	s_waitcnt vmcnt(8) lgkmcnt(0)
	s_barrier
	s_setprio 1
	v_mfma_f32_16x16x32_bf16 v[60:63], v[130:133], v[162:165], v[60:63]
	v_mfma_f32_16x16x32_bf16 v[60:63], v[134:137], v[166:169], v[60:63]
	v_mfma_f32_16x16x32_bf16 v[44:47], v[130:133], v[170:173], v[44:47]
	v_mfma_f32_16x16x32_bf16 v[44:47], v[134:137], v[184:187], v[44:47]
	v_mfma_f32_16x16x32_bf16 v[28:31], v[130:133], v[190:193], v[28:31]
	v_mfma_f32_16x16x32_bf16 v[28:31], v[134:137], v[196:199], v[28:31]
	v_mfma_f32_16x16x32_bf16 v[12:15], v[130:133], v[204:207], v[12:15]
	v_mfma_f32_16x16x32_bf16 v[12:15], v[134:137], v[212:215], v[12:15]
	v_mfma_f32_16x16x32_bf16 v[56:59], v[138:141], v[162:165], v[56:59]
	v_mfma_f32_16x16x32_bf16 v[56:59], v[142:145], v[166:169], v[56:59]
	v_mfma_f32_16x16x32_bf16 v[40:43], v[138:141], v[170:173], v[40:43]
	v_mfma_f32_16x16x32_bf16 v[40:43], v[142:145], v[184:187], v[40:43]
	v_mfma_f32_16x16x32_bf16 v[24:27], v[138:141], v[190:193], v[24:27]
	v_mfma_f32_16x16x32_bf16 v[24:27], v[142:145], v[196:199], v[24:27]
	v_mfma_f32_16x16x32_bf16 v[8:11], v[138:141], v[204:207], v[8:11]
	v_mfma_f32_16x16x32_bf16 v[8:11], v[142:145], v[212:215], v[8:11]
	v_mfma_f32_16x16x32_bf16 v[52:55], v[146:149], v[162:165], v[52:55]
	v_mfma_f32_16x16x32_bf16 v[52:55], v[150:153], v[166:169], v[52:55]
	v_mfma_f32_16x16x32_bf16 v[36:39], v[146:149], v[170:173], v[36:39]
	v_mfma_f32_16x16x32_bf16 v[36:39], v[150:153], v[184:187], v[36:39]
	v_mfma_f32_16x16x32_bf16 v[20:23], v[146:149], v[190:193], v[20:23]
	v_mfma_f32_16x16x32_bf16 v[20:23], v[150:153], v[196:199], v[20:23]
	v_mfma_f32_16x16x32_bf16 v[4:7], v[146:149], v[204:207], v[4:7]
	v_mfma_f32_16x16x32_bf16 v[4:7], v[150:153], v[212:215], v[4:7]
	v_mfma_f32_16x16x32_bf16 v[48:51], v[154:157], v[162:165], v[48:51]
	v_mfma_f32_16x16x32_bf16 v[48:51], v[158:161], v[166:169], v[48:51]
	v_mfma_f32_16x16x32_bf16 v[32:35], v[154:157], v[170:173], v[32:35]
	v_mfma_f32_16x16x32_bf16 v[32:35], v[158:161], v[184:187], v[32:35]
	s_setprio 2
	s_barrier
	v_mfma_f32_16x16x32_bf16 v[16:19], v[154:157], v[190:193], v[16:19]
	v_mfma_f32_16x16x32_bf16 v[16:19], v[158:161], v[196:199], v[16:19]
	v_mfma_f32_16x16x32_bf16 v[0:3], v[154:157], v[204:207], v[0:3]
	v_mfma_f32_16x16x32_bf16 v[0:3], v[158:161], v[212:215], v[0:3]
	s_setprio 0
	s_add_i32 s70, s70, 1
	s_add_u32 s44, s44, 0x100
	s_addc_u32 s45, s45, 0
	s_add_u32 s83, s83, 0x100
	s_addc_u32 s84, s84, 0
	s_cmp_gt_u32 s85, 29
	s_cbranch_scc0 .LBB0_698
	s_lshl_b32 s29, s41, 12
	s_and_b32 s29, s29, 0x1000
	s_add_i32 s29, s29, 0
	v_mbcnt_lo_u32_b32 v128, -1, 0
	v_mbcnt_hi_u32_b32 v128, -1, v128
	s_add_i32 s29, s29, s63
	v_lshlrev_b32_e32 v128, 4, v128
	s_add_i32 s29, s29, 0x20400
	v_and_b32_e32 v128, 0xf0, v128
	v_add_u32_e32 v128, s29, v128
	ds_read2_b32 v[214:215], v128 offset0:3 offset1:67
	ds_read2_b32 v[206:207], v128 offset0:131 offset1:195
	v_add_u32_e32 v128, 12, v128
	ds_read2st64_b32 v[196:197], v128 offset0:8 offset1:9
	ds_read2st64_b32 v[190:191], v128 offset0:10 offset1:11
	s_and_b64 vcc, exec, s[22:23]
	s_waitcnt lgkmcnt(0)
	v_mov_b32_e32 v210, v215
	v_mov_b32_e32 v202, v207
	v_mov_b32_e32 v194, v197
	v_mov_b32_e32 v188, v191
	s_cbranch_vccz .LBB0_703
	s_barrier

.LBB0_783:
	s_ashr_i32 s23, s22, 31
	s_lshl_b64 s[26:27], s[22:23], 19
	s_add_u32 s26, s43, s26
	s_addc_u32 s27, s44, s27
	s_and_b64 s[28:29], s[4:5], exec
	s_cselect_b32 s23, s27, s37
	s_cselect_b32 s31, s26, s36
	s_ashr_i32 s25, s24, 31
	s_lshl_b64 s[28:29], s[24:25], 19
	s_add_u32 s28, s45, s28
	s_addc_u32 s29, s46, s29
	s_and_b64 s[40:41], s[4:5], exec
	s_cselect_b32 s25, s29, s39
	s_cselect_b32 s62, s28, s38
	s_add_u32 s36, s36, 0x40080
	s_addc_u32 s37, s37, 0
	s_add_u32 s63, s38, 0x100
	s_addc_u32 s64, s39, 0
	s_mov_b32 s65, -2
	ds_read_b128 v[144:147], v163
	ds_read_b128 v[148:151], v163 offset:1024
	ds_read_b128 v[152:155], v163 offset:2048
	ds_read_b128 v[156:159], v163 offset:3072
	ds_read_b128 v[168:171], v164
	ds_read_b128 v[172:175], v164 offset:1024
	ds_read_b128 v[176:179], v164 offset:2048
	ds_read_b128 v[180:183], v164 offset:3072
	s_add_u32 s38, s36, 0xfffc0080
	s_addc_u32 s39, s37, -1
	s_cmp_eq_u32 s65, 12
	s_cselect_b32 s41, s23, s39
	s_cselect_b32 s40, s31, s38
	s_cselect_b32 s39, s25, s64
	s_cselect_b32 s38, s62, s63
	v_lshl_add_u64 v[160:161], s[36:37], 0, v[136:137]
	s_add_i32 m0, s50, 0xc000
	ds_read_b128 v[184:187], v165
	ds_read_b128 v[188:191], v165 offset:1024
	ds_read_b128 v[192:195], v165 offset:2048
	ds_read_b128 v[196:199], v165 offset:3072
	ds_read_b128 v[200:203], v165 offset:4096
	ds_read_b128 v[204:207], v165 offset:5120
	ds_read_b128 v[208:211], v165 offset:6144
	ds_read_b128 v[212:215], v165 offset:7168
	global_load_lds_dwordx4 v[160:161], off
	s_add_i32 m0, s50, 0xe000
	v_lshl_add_u64 v[160:161], s[36:37], 0, v[138:139]
	global_load_lds_dwordx4 v[160:161], off
	s_waitcnt vmcnt(8) lgkmcnt(0)
	s_barrier
	s_setprio 1
	v_mfma_f32_16x16x32_bf16 v[124:127], v[144:147], v[184:187], 0
	v_mfma_f32_16x16x32_bf16 v[124:127], v[148:151], v[188:191], v[124:127]
	v_mfma_f32_16x16x32_bf16 v[108:111], v[144:147], v[192:195], 0
	v_mfma_f32_16x16x32_bf16 v[108:111], v[148:151], v[196:199], v[108:111]
	v_mfma_f32_16x16x32_bf16 v[92:95], v[144:147], v[200:203], 0
	v_mfma_f32_16x16x32_bf16 v[92:95], v[148:151], v[204:207], v[92:95]
	v_mfma_f32_16x16x32_bf16 v[76:79], v[144:147], v[208:211], 0
	v_mfma_f32_16x16x32_bf16 v[76:79], v[148:151], v[212:215], v[76:79]
	v_mfma_f32_16x16x32_bf16 v[120:123], v[152:155], v[184:187], 0
	v_mfma_f32_16x16x32_bf16 v[120:123], v[156:159], v[188:191], v[120:123]
	v_mfma_f32_16x16x32_bf16 v[104:107], v[152:155], v[192:195], 0
	v_mfma_f32_16x16x32_bf16 v[104:107], v[156:159], v[196:199], v[104:107]
	v_mfma_f32_16x16x32_bf16 v[88:91], v[152:155], v[200:203], 0
	v_mfma_f32_16x16x32_bf16 v[88:91], v[156:159], v[204:207], v[88:91]
	v_mfma_f32_16x16x32_bf16 v[72:75], v[152:155], v[208:211], 0
	v_mfma_f32_16x16x32_bf16 v[72:75], v[156:159], v[212:215], v[72:75]
	v_mfma_f32_16x16x32_bf16 v[116:119], v[168:171], v[184:187], 0
	v_mfma_f32_16x16x32_bf16 v[116:119], v[172:175], v[188:191], v[116:119]
	v_mfma_f32_16x16x32_bf16 v[100:103], v[168:171], v[192:195], 0
	v_mfma_f32_16x16x32_bf16 v[100:103], v[172:175], v[196:199], v[100:103]
	v_mfma_f32_16x16x32_bf16 v[84:87], v[168:171], v[200:203], 0
	v_mfma_f32_16x16x32_bf16 v[84:87], v[172:175], v[204:207], v[84:87]
	v_mfma_f32_16x16x32_bf16 v[68:71], v[168:171], v[208:211], 0
	v_mfma_f32_16x16x32_bf16 v[68:71], v[172:175], v[212:215], v[68:71]
	v_mfma_f32_16x16x32_bf16 v[112:115], v[176:179], v[184:187], 0
	v_mfma_f32_16x16x32_bf16 v[112:115], v[180:183], v[188:191], v[112:115]
	v_mfma_f32_16x16x32_bf16 v[96:99], v[176:179], v[192:195], 0
	v_mfma_f32_16x16x32_bf16 v[96:99], v[180:183], v[196:199], v[96:99]
	s_setprio 2
	s_barrier
	v_mfma_f32_16x16x32_bf16 v[80:83], v[176:179], v[200:203], 0
	v_mfma_f32_16x16x32_bf16 v[80:83], v[180:183], v[204:207], v[80:83]
	v_mfma_f32_16x16x32_bf16 v[64:67], v[176:179], v[208:211], 0
	v_mfma_f32_16x16x32_bf16 v[64:67], v[180:183], v[212:215], v[64:67]
	s_setprio 2
	s_add_i32 s66, s59, s47
	v_lshl_add_u64 v[160:161], s[38:39], 0, v[132:133]
	s_mov_b32 m0, s66
	ds_read_b128 v[184:187], v165 offset:16384
	ds_read_b128 v[188:191], v165 offset:17408
	ds_read_b128 v[192:195], v165 offset:18432
	ds_read_b128 v[196:199], v165 offset:19456
	ds_read_b128 v[200:203], v165 offset:20480
	ds_read_b128 v[204:207], v165 offset:21504
	ds_read_b128 v[208:211], v165 offset:22528
	ds_read_b128 v[212:215], v165 offset:23552
	global_load_lds_dwordx4 v[160:161], off
	s_add_i32 m0, s66, 0x2000
	s_add_u32 s66, s38, 0x40000
	v_lshl_add_u64 v[216:217], s[38:39], 0, v[128:129]
	s_addc_u32 s67, s39, 0
	s_add_i32 s68, s60, s47
	global_load_lds_dwordx4 v[216:217], off
	v_lshl_add_u64 v[218:219], s[66:67], 0, v[132:133]
	s_mov_b32 m0, s68
	v_lshl_add_u64 v[220:221], s[40:41], 0, v[130:131]
	global_load_lds_dwordx4 v[218:219], off
	s_add_i32 m0, s68, 0x2000
	v_lshl_add_u64 v[218:219], s[66:67], 0, v[128:129]
	global_load_lds_dwordx4 v[218:219], off
	s_mov_b32 m0, s50
	v_lshl_add_u64 v[218:219], s[40:41], 0, v[134:135]
	global_load_lds_dwordx4 v[218:219], off
	s_mov_b32 m0, s51
	s_nop 0
	global_load_lds_dwordx4 v[220:221], off
	s_waitcnt vmcnt(8) lgkmcnt(0)
	s_barrier
	s_setprio 1
	v_mfma_f32_16x16x32_bf16 v[60:63], v[144:147], v[184:187], 0
	v_mfma_f32_16x16x32_bf16 v[60:63], v[148:151], v[188:191], v[60:63]
	v_mfma_f32_16x16x32_bf16 v[44:47], v[144:147], v[192:195], 0
	v_mfma_f32_16x16x32_bf16 v[44:47], v[148:151], v[196:199], v[44:47]
	v_mfma_f32_16x16x32_bf16 v[28:31], v[144:147], v[200:203], 0
	v_mfma_f32_16x16x32_bf16 v[28:31], v[148:151], v[204:207], v[28:31]
	v_mfma_f32_16x16x32_bf16 v[12:15], v[144:147], v[208:211], 0
	v_mfma_f32_16x16x32_bf16 v[12:15], v[148:151], v[212:215], v[12:15]
	v_mfma_f32_16x16x32_bf16 v[56:59], v[152:155], v[184:187], 0
	v_mfma_f32_16x16x32_bf16 v[56:59], v[156:159], v[188:191], v[56:59]
	v_mfma_f32_16x16x32_bf16 v[40:43], v[152:155], v[192:195], 0
	v_mfma_f32_16x16x32_bf16 v[40:43], v[156:159], v[196:199], v[40:43]
	v_mfma_f32_16x16x32_bf16 v[24:27], v[152:155], v[200:203], 0
	v_mfma_f32_16x16x32_bf16 v[24:27], v[156:159], v[204:207], v[24:27]
	v_mfma_f32_16x16x32_bf16 v[8:11], v[152:155], v[208:211], 0
	v_mfma_f32_16x16x32_bf16 v[8:11], v[156:159], v[212:215], v[8:11]
	v_mfma_f32_16x16x32_bf16 v[52:55], v[168:171], v[184:187], 0
	v_mfma_f32_16x16x32_bf16 v[52:55], v[172:175], v[188:191], v[52:55]
	v_mfma_f32_16x16x32_bf16 v[36:39], v[168:171], v[192:195], 0
	v_mfma_f32_16x16x32_bf16 v[36:39], v[172:175], v[196:199], v[36:39]
	v_mfma_f32_16x16x32_bf16 v[20:23], v[168:171], v[200:203], 0
	v_mfma_f32_16x16x32_bf16 v[20:23], v[172:175], v[204:207], v[20:23]
	v_mfma_f32_16x16x32_bf16 v[4:7], v[168:171], v[208:211], 0
	v_mfma_f32_16x16x32_bf16 v[4:7], v[172:175], v[212:215], v[4:7]
	v_mfma_f32_16x16x32_bf16 v[48:51], v[176:179], v[184:187], 0
	v_mfma_f32_16x16x32_bf16 v[48:51], v[180:183], v[188:191], v[48:51]
	v_mfma_f32_16x16x32_bf16 v[32:35], v[176:179], v[192:195], 0
	v_mfma_f32_16x16x32_bf16 v[32:35], v[180:183], v[196:199], v[32:35]
	s_setprio 2
	s_barrier
	v_mfma_f32_16x16x32_bf16 v[16:19], v[176:179], v[200:203], 0
	v_mfma_f32_16x16x32_bf16 v[16:19], v[180:183], v[204:207], v[16:19]
	v_mfma_f32_16x16x32_bf16 v[0:3], v[176:179], v[208:211], 0
	v_mfma_f32_16x16x32_bf16 v[0:3], v[180:183], v[212:215], v[0:3]
	s_setprio 0
	s_add_i32 s66, 0, 0x18000
	s_add_i32 s67, 0, 0x1c000
	v_add_u32_e32 v156, s66, v162
	v_add_u32_e32 v167, s67, v162
	ds_read_b128 v[144:147], v156
	ds_read_b128 v[148:151], v156 offset:1024
	ds_read_b128 v[152:155], v156 offset:2048
	ds_read_b128 v[156:159], v156 offset:3072
	ds_read_b128 v[168:171], v167
	ds_read_b128 v[172:175], v167 offset:1024
	ds_read_b128 v[176:179], v167 offset:2048
	ds_read_b128 v[180:183], v167 offset:3072
	s_add_u32 s40, s40, 0x40000
	s_addc_u32 s41, s41, 0
	s_mov_b32 m0, s54
	v_lshl_add_u64 v[222:223], s[40:41], 0, v[134:135]
	ds_read_b128 v[184:187], v165 offset:32768
	ds_read_b128 v[188:191], v165 offset:33792
	ds_read_b128 v[192:195], v165 offset:34816
	ds_read_b128 v[196:199], v165 offset:35840
	ds_read_b128 v[200:203], v165 offset:36864
	ds_read_b128 v[204:207], v165 offset:37888
	ds_read_b128 v[208:211], v165 offset:38912
	ds_read_b128 v[212:215], v165 offset:39936
	global_load_lds_dwordx4 v[222:223], off
	s_mov_b32 m0, s55
	v_lshl_add_u64 v[222:223], s[40:41], 0, v[130:131]
	global_load_lds_dwordx4 v[222:223], off
	s_waitcnt vmcnt(8) lgkmcnt(0)
	s_barrier
	s_setprio 1
	v_mfma_f32_16x16x32_bf16 v[124:127], v[144:147], v[184:187], v[124:127]
	v_mfma_f32_16x16x32_bf16 v[124:127], v[148:151], v[188:191], v[124:127]
	v_mfma_f32_16x16x32_bf16 v[108:111], v[144:147], v[192:195], v[108:111]
	v_mfma_f32_16x16x32_bf16 v[108:111], v[148:151], v[196:199], v[108:111]
	v_mfma_f32_16x16x32_bf16 v[92:95], v[144:147], v[200:203], v[92:95]
	v_mfma_f32_16x16x32_bf16 v[92:95], v[148:151], v[204:207], v[92:95]
	v_mfma_f32_16x16x32_bf16 v[76:79], v[144:147], v[208:211], v[76:79]
	v_mfma_f32_16x16x32_bf16 v[76:79], v[148:151], v[212:215], v[76:79]
	v_mfma_f32_16x16x32_bf16 v[120:123], v[152:155], v[184:187], v[120:123]
	v_mfma_f32_16x16x32_bf16 v[120:123], v[156:159], v[188:191], v[120:123]
	v_mfma_f32_16x16x32_bf16 v[104:107], v[152:155], v[192:195], v[104:107]
	v_mfma_f32_16x16x32_bf16 v[104:107], v[156:159], v[196:199], v[104:107]
	v_mfma_f32_16x16x32_bf16 v[88:91], v[152:155], v[200:203], v[88:91]
	v_mfma_f32_16x16x32_bf16 v[88:91], v[156:159], v[204:207], v[88:91]
	v_mfma_f32_16x16x32_bf16 v[72:75], v[152:155], v[208:211], v[72:75]
	v_mfma_f32_16x16x32_bf16 v[72:75], v[156:159], v[212:215], v[72:75]
	v_mfma_f32_16x16x32_bf16 v[116:119], v[168:171], v[184:187], v[116:119]
	v_mfma_f32_16x16x32_bf16 v[116:119], v[172:175], v[188:191], v[116:119]
	v_mfma_f32_16x16x32_bf16 v[100:103], v[168:171], v[192:195], v[100:103]
	v_mfma_f32_16x16x32_bf16 v[100:103], v[172:175], v[196:199], v[100:103]
	v_mfma_f32_16x16x32_bf16 v[84:87], v[168:171], v[200:203], v[84:87]
	v_mfma_f32_16x16x32_bf16 v[84:87], v[172:175], v[204:207], v[84:87]
	v_mfma_f32_16x16x32_bf16 v[68:71], v[168:171], v[208:211], v[68:71]
	v_mfma_f32_16x16x32_bf16 v[68:71], v[172:175], v[212:215], v[68:71]
	v_mfma_f32_16x16x32_bf16 v[112:115], v[176:179], v[184:187], v[112:115]
	v_mfma_f32_16x16x32_bf16 v[112:115], v[180:183], v[188:191], v[112:115]
	v_mfma_f32_16x16x32_bf16 v[96:99], v[176:179], v[192:195], v[96:99]
	v_mfma_f32_16x16x32_bf16 v[96:99], v[180:183], v[196:199], v[96:99]
	s_setprio 2
	s_barrier
	v_mfma_f32_16x16x32_bf16 v[80:83], v[176:179], v[200:203], v[80:83]
	v_mfma_f32_16x16x32_bf16 v[80:83], v[180:183], v[204:207], v[80:83]
	v_mfma_f32_16x16x32_bf16 v[64:67], v[176:179], v[208:211], v[64:67]
	v_mfma_f32_16x16x32_bf16 v[64:67], v[180:183], v[212:215], v[64:67]
	s_setprio 2
	s_add_i32 s40, s66, s47
	v_lshl_add_u64 v[160:161], v[160:161], 0, s[16:17]
	s_mov_b32 m0, s40
	ds_read_b128 v[184:187], v165 offset:49152
	ds_read_b128 v[188:191], v165 offset:50176
	ds_read_b128 v[192:195], v165 offset:51200
	ds_read_b128 v[196:199], v165 offset:52224
	ds_read_b128 v[200:203], v165 offset:53248
	ds_read_b128 v[204:207], v165 offset:54272
	ds_read_b128 v[208:211], v165 offset:55296
	ds_read_b128 v[212:215], v165 offset:56320
	global_load_lds_dwordx4 v[160:161], off
	s_add_i32 m0, s40, 0x2000
	s_add_u32 s38, s38, 0x40080
	v_lshl_add_u64 v[160:161], v[216:217], 0, s[16:17]
	s_addc_u32 s39, s39, 0
	s_add_i32 s40, s67, s47
	global_load_lds_dwordx4 v[160:161], off
	s_mov_b32 m0, s40
	v_lshl_add_u64 v[160:161], s[38:39], 0, v[132:133]
	global_load_lds_dwordx4 v[160:161], off
	s_add_i32 m0, s40, 0x2000
	v_lshl_add_u64 v[160:161], s[38:39], 0, v[128:129]
	global_load_lds_dwordx4 v[160:161], off
	s_mov_b32 m0, s57
	v_lshl_add_u64 v[160:161], v[218:219], 0, s[16:17]
	global_load_lds_dwordx4 v[160:161], off
	s_mov_b32 m0, s58
	v_lshl_add_u64 v[160:161], v[220:221], 0, s[16:17]
	global_load_lds_dwordx4 v[160:161], off
	s_waitcnt vmcnt(8) lgkmcnt(0)
	s_barrier
	s_setprio 1
	v_mfma_f32_16x16x32_bf16 v[60:63], v[144:147], v[184:187], v[60:63]
	v_mfma_f32_16x16x32_bf16 v[60:63], v[148:151], v[188:191], v[60:63]
	v_mfma_f32_16x16x32_bf16 v[44:47], v[144:147], v[192:195], v[44:47]
	v_mfma_f32_16x16x32_bf16 v[44:47], v[148:151], v[196:199], v[44:47]
	v_mfma_f32_16x16x32_bf16 v[28:31], v[144:147], v[200:203], v[28:31]
	v_mfma_f32_16x16x32_bf16 v[28:31], v[148:151], v[204:207], v[28:31]
	v_mfma_f32_16x16x32_bf16 v[12:15], v[144:147], v[208:211], v[12:15]
	v_mfma_f32_16x16x32_bf16 v[12:15], v[148:151], v[212:215], v[12:15]
	v_mfma_f32_16x16x32_bf16 v[56:59], v[152:155], v[184:187], v[56:59]
	v_mfma_f32_16x16x32_bf16 v[56:59], v[156:159], v[188:191], v[56:59]
	v_mfma_f32_16x16x32_bf16 v[40:43], v[152:155], v[192:195], v[40:43]
	v_mfma_f32_16x16x32_bf16 v[40:43], v[156:159], v[196:199], v[40:43]
	v_mfma_f32_16x16x32_bf16 v[24:27], v[152:155], v[200:203], v[24:27]
	v_mfma_f32_16x16x32_bf16 v[24:27], v[156:159], v[204:207], v[24:27]
	v_mfma_f32_16x16x32_bf16 v[8:11], v[152:155], v[208:211], v[8:11]
	v_mfma_f32_16x16x32_bf16 v[8:11], v[156:159], v[212:215], v[8:11]
	v_mfma_f32_16x16x32_bf16 v[52:55], v[168:171], v[184:187], v[52:55]
	v_mfma_f32_16x16x32_bf16 v[52:55], v[172:175], v[188:191], v[52:55]
	v_mfma_f32_16x16x32_bf16 v[36:39], v[168:171], v[192:195], v[36:39]
	v_mfma_f32_16x16x32_bf16 v[36:39], v[172:175], v[196:199], v[36:39]
	v_mfma_f32_16x16x32_bf16 v[20:23], v[168:171], v[200:203], v[20:23]
	v_mfma_f32_16x16x32_bf16 v[20:23], v[172:175], v[204:207], v[20:23]
	v_mfma_f32_16x16x32_bf16 v[4:7], v[168:171], v[208:211], v[4:7]
	v_mfma_f32_16x16x32_bf16 v[4:7], v[172:175], v[212:215], v[4:7]
	v_mfma_f32_16x16x32_bf16 v[48:51], v[176:179], v[184:187], v[48:51]
	v_mfma_f32_16x16x32_bf16 v[48:51], v[180:183], v[188:191], v[48:51]
	v_mfma_f32_16x16x32_bf16 v[32:35], v[176:179], v[192:195], v[32:35]
	v_mfma_f32_16x16x32_bf16 v[32:35], v[180:183], v[196:199], v[32:35]
	s_setprio 2
	s_barrier
	v_mfma_f32_16x16x32_bf16 v[16:19], v[176:179], v[200:203], v[16:19]
	v_mfma_f32_16x16x32_bf16 v[16:19], v[180:183], v[204:207], v[16:19]
	v_mfma_f32_16x16x32_bf16 v[0:3], v[176:179], v[208:211], v[0:3]
	v_mfma_f32_16x16x32_bf16 v[0:3], v[180:183], v[212:215], v[0:3]
	s_setprio 0
	s_add_i32 s65, s65, 2
	s_add_u32 s36, s36, 0x100
	s_addc_u32 s37, s37, 0
	s_add_u32 s63, s63, 0x100
	s_addc_u32 s64, s64, 0
	s_cmp_gt_u32 s65, 13
.LBB0_784:
	ds_read_b128 v[144:147], v163
	ds_read_b128 v[148:151], v163 offset:1024
	ds_read_b128 v[152:155], v163 offset:2048
	ds_read_b128 v[156:159], v163 offset:3072
	ds_read_b128 v[168:171], v164
	ds_read_b128 v[172:175], v164 offset:1024
	ds_read_b128 v[176:179], v164 offset:2048
	ds_read_b128 v[180:183], v164 offset:3072
	s_add_u32 s38, s36, 0xfffc0080
	s_addc_u32 s39, s37, -1
	s_cmp_eq_u32 s65, 12
	s_cselect_b32 s41, s23, s39
	s_cselect_b32 s40, s31, s38
	s_cselect_b32 s39, s25, s64
	s_cselect_b32 s38, s62, s63
	v_lshl_add_u64 v[160:161], s[36:37], 0, v[136:137]
	s_add_i32 m0, s50, 0xc000
	ds_read_b128 v[184:187], v165
	ds_read_b128 v[188:191], v165 offset:1024
	ds_read_b128 v[192:195], v165 offset:2048
	ds_read_b128 v[196:199], v165 offset:3072
	ds_read_b128 v[200:203], v165 offset:4096
	ds_read_b128 v[204:207], v165 offset:5120
	ds_read_b128 v[208:211], v165 offset:6144
	ds_read_b128 v[212:215], v165 offset:7168
	global_load_lds_dwordx4 v[160:161], off
	s_add_i32 m0, s50, 0xe000
	v_lshl_add_u64 v[160:161], s[36:37], 0, v[138:139]
	global_load_lds_dwordx4 v[160:161], off
	s_waitcnt vmcnt(8) lgkmcnt(0)
	s_barrier
	s_setprio 1
	v_mfma_f32_16x16x32_bf16 v[124:127], v[144:147], v[184:187], v[124:127]
	v_mfma_f32_16x16x32_bf16 v[124:127], v[148:151], v[188:191], v[124:127]
	v_mfma_f32_16x16x32_bf16 v[108:111], v[144:147], v[192:195], v[108:111]
	v_mfma_f32_16x16x32_bf16 v[108:111], v[148:151], v[196:199], v[108:111]
	v_mfma_f32_16x16x32_bf16 v[92:95], v[144:147], v[200:203], v[92:95]
	v_mfma_f32_16x16x32_bf16 v[92:95], v[148:151], v[204:207], v[92:95]
	v_mfma_f32_16x16x32_bf16 v[76:79], v[144:147], v[208:211], v[76:79]
	v_mfma_f32_16x16x32_bf16 v[76:79], v[148:151], v[212:215], v[76:79]
	v_mfma_f32_16x16x32_bf16 v[120:123], v[152:155], v[184:187], v[120:123]
	v_mfma_f32_16x16x32_bf16 v[120:123], v[156:159], v[188:191], v[120:123]
	v_mfma_f32_16x16x32_bf16 v[104:107], v[152:155], v[192:195], v[104:107]
	v_mfma_f32_16x16x32_bf16 v[104:107], v[156:159], v[196:199], v[104:107]
	v_mfma_f32_16x16x32_bf16 v[88:91], v[152:155], v[200:203], v[88:91]
	v_mfma_f32_16x16x32_bf16 v[88:91], v[156:159], v[204:207], v[88:91]
	v_mfma_f32_16x16x32_bf16 v[72:75], v[152:155], v[208:211], v[72:75]
	v_mfma_f32_16x16x32_bf16 v[72:75], v[156:159], v[212:215], v[72:75]
	v_mfma_f32_16x16x32_bf16 v[116:119], v[168:171], v[184:187], v[116:119]
	v_mfma_f32_16x16x32_bf16 v[116:119], v[172:175], v[188:191], v[116:119]
	v_mfma_f32_16x16x32_bf16 v[100:103], v[168:171], v[192:195], v[100:103]
	v_mfma_f32_16x16x32_bf16 v[100:103], v[172:175], v[196:199], v[100:103]
	v_mfma_f32_16x16x32_bf16 v[84:87], v[168:171], v[200:203], v[84:87]
	v_mfma_f32_16x16x32_bf16 v[84:87], v[172:175], v[204:207], v[84:87]
	v_mfma_f32_16x16x32_bf16 v[68:71], v[168:171], v[208:211], v[68:71]
	v_mfma_f32_16x16x32_bf16 v[68:71], v[172:175], v[212:215], v[68:71]
	v_mfma_f32_16x16x32_bf16 v[112:115], v[176:179], v[184:187], v[112:115]
	v_mfma_f32_16x16x32_bf16 v[112:115], v[180:183], v[188:191], v[112:115]
	v_mfma_f32_16x16x32_bf16 v[96:99], v[176:179], v[192:195], v[96:99]
	v_mfma_f32_16x16x32_bf16 v[96:99], v[180:183], v[196:199], v[96:99]
	s_setprio 2
	s_barrier
	v_mfma_f32_16x16x32_bf16 v[80:83], v[176:179], v[200:203], v[80:83]
	v_mfma_f32_16x16x32_bf16 v[80:83], v[180:183], v[204:207], v[80:83]
	v_mfma_f32_16x16x32_bf16 v[64:67], v[176:179], v[208:211], v[64:67]
	v_mfma_f32_16x16x32_bf16 v[64:67], v[180:183], v[212:215], v[64:67]
	s_setprio 2
	s_add_i32 s66, s59, s47
	v_lshl_add_u64 v[160:161], s[38:39], 0, v[132:133]
	s_mov_b32 m0, s66
	ds_read_b128 v[184:187], v165 offset:16384
	ds_read_b128 v[188:191], v165 offset:17408
	ds_read_b128 v[192:195], v165 offset:18432
	ds_read_b128 v[196:199], v165 offset:19456
	ds_read_b128 v[200:203], v165 offset:20480
	ds_read_b128 v[204:207], v165 offset:21504
	ds_read_b128 v[208:211], v165 offset:22528
	ds_read_b128 v[212:215], v165 offset:23552
	global_load_lds_dwordx4 v[160:161], off
	s_add_i32 m0, s66, 0x2000
	s_add_u32 s66, s38, 0x40000
	v_lshl_add_u64 v[216:217], s[38:39], 0, v[128:129]
	s_addc_u32 s67, s39, 0
	s_add_i32 s68, s60, s47
	global_load_lds_dwordx4 v[216:217], off
	v_lshl_add_u64 v[218:219], s[66:67], 0, v[132:133]
	s_mov_b32 m0, s68
	v_lshl_add_u64 v[220:221], s[40:41], 0, v[130:131]
	global_load_lds_dwordx4 v[218:219], off
	s_add_i32 m0, s68, 0x2000
	v_lshl_add_u64 v[218:219], s[66:67], 0, v[128:129]
	global_load_lds_dwordx4 v[218:219], off
	s_mov_b32 m0, s50
	v_lshl_add_u64 v[218:219], s[40:41], 0, v[134:135]
	global_load_lds_dwordx4 v[218:219], off
	s_mov_b32 m0, s51
	s_nop 0
	global_load_lds_dwordx4 v[220:221], off
	s_waitcnt vmcnt(8) lgkmcnt(0)
	s_barrier
	s_setprio 1
	v_mfma_f32_16x16x32_bf16 v[60:63], v[144:147], v[184:187], v[60:63]
	v_mfma_f32_16x16x32_bf16 v[60:63], v[148:151], v[188:191], v[60:63]
	v_mfma_f32_16x16x32_bf16 v[44:47], v[144:147], v[192:195], v[44:47]
	v_mfma_f32_16x16x32_bf16 v[44:47], v[148:151], v[196:199], v[44:47]
	v_mfma_f32_16x16x32_bf16 v[28:31], v[144:147], v[200:203], v[28:31]
	v_mfma_f32_16x16x32_bf16 v[28:31], v[148:151], v[204:207], v[28:31]
	v_mfma_f32_16x16x32_bf16 v[12:15], v[144:147], v[208:211], v[12:15]
	v_mfma_f32_16x16x32_bf16 v[12:15], v[148:151], v[212:215], v[12:15]
	v_mfma_f32_16x16x32_bf16 v[56:59], v[152:155], v[184:187], v[56:59]
	v_mfma_f32_16x16x32_bf16 v[56:59], v[156:159], v[188:191], v[56:59]
	v_mfma_f32_16x16x32_bf16 v[40:43], v[152:155], v[192:195], v[40:43]
	v_mfma_f32_16x16x32_bf16 v[40:43], v[156:159], v[196:199], v[40:43]
	v_mfma_f32_16x16x32_bf16 v[24:27], v[152:155], v[200:203], v[24:27]
	v_mfma_f32_16x16x32_bf16 v[24:27], v[156:159], v[204:207], v[24:27]
	v_mfma_f32_16x16x32_bf16 v[8:11], v[152:155], v[208:211], v[8:11]
	v_mfma_f32_16x16x32_bf16 v[8:11], v[156:159], v[212:215], v[8:11]
	v_mfma_f32_16x16x32_bf16 v[52:55], v[168:171], v[184:187], v[52:55]
	v_mfma_f32_16x16x32_bf16 v[52:55], v[172:175], v[188:191], v[52:55]
	v_mfma_f32_16x16x32_bf16 v[36:39], v[168:171], v[192:195], v[36:39]
	v_mfma_f32_16x16x32_bf16 v[36:39], v[172:175], v[196:199], v[36:39]
	v_mfma_f32_16x16x32_bf16 v[20:23], v[168:171], v[200:203], v[20:23]
	v_mfma_f32_16x16x32_bf16 v[20:23], v[172:175], v[204:207], v[20:23]
	v_mfma_f32_16x16x32_bf16 v[4:7], v[168:171], v[208:211], v[4:7]
	v_mfma_f32_16x16x32_bf16 v[4:7], v[172:175], v[212:215], v[4:7]
	v_mfma_f32_16x16x32_bf16 v[48:51], v[176:179], v[184:187], v[48:51]
	v_mfma_f32_16x16x32_bf16 v[48:51], v[180:183], v[188:191], v[48:51]
	v_mfma_f32_16x16x32_bf16 v[32:35], v[176:179], v[192:195], v[32:35]
	v_mfma_f32_16x16x32_bf16 v[32:35], v[180:183], v[196:199], v[32:35]
	s_setprio 2
	s_barrier
	v_mfma_f32_16x16x32_bf16 v[16:19], v[176:179], v[200:203], v[16:19]
	v_mfma_f32_16x16x32_bf16 v[16:19], v[180:183], v[204:207], v[16:19]
	v_mfma_f32_16x16x32_bf16 v[0:3], v[176:179], v[208:211], v[0:3]
	v_mfma_f32_16x16x32_bf16 v[0:3], v[180:183], v[212:215], v[0:3]
	s_setprio 0
	s_add_i32 s66, 0, 0x18000
	s_add_i32 s67, 0, 0x1c000
	v_add_u32_e32 v156, s66, v162
	v_add_u32_e32 v167, s67, v162
	ds_read_b128 v[144:147], v156
	ds_read_b128 v[148:151], v156 offset:1024
	ds_read_b128 v[152:155], v156 offset:2048
	ds_read_b128 v[156:159], v156 offset:3072
	ds_read_b128 v[168:171], v167
	ds_read_b128 v[172:175], v167 offset:1024
	ds_read_b128 v[176:179], v167 offset:2048
	ds_read_b128 v[180:183], v167 offset:3072
	s_add_u32 s40, s40, 0x40000
	s_addc_u32 s41, s41, 0
	s_mov_b32 m0, s54
	v_lshl_add_u64 v[222:223], s[40:41], 0, v[134:135]
	ds_read_b128 v[184:187], v165 offset:32768
	ds_read_b128 v[188:191], v165 offset:33792
	ds_read_b128 v[192:195], v165 offset:34816
	ds_read_b128 v[196:199], v165 offset:35840
	ds_read_b128 v[200:203], v165 offset:36864
	ds_read_b128 v[204:207], v165 offset:37888
	ds_read_b128 v[208:211], v165 offset:38912
	ds_read_b128 v[212:215], v165 offset:39936
	global_load_lds_dwordx4 v[222:223], off
	s_mov_b32 m0, s55
	v_lshl_add_u64 v[222:223], s[40:41], 0, v[130:131]
	global_load_lds_dwordx4 v[222:223], off
	s_waitcnt vmcnt(8) lgkmcnt(0)
	s_barrier
	s_setprio 1
	v_mfma_f32_16x16x32_bf16 v[124:127], v[144:147], v[184:187], v[124:127]
	v_mfma_f32_16x16x32_bf16 v[124:127], v[148:151], v[188:191], v[124:127]
	v_mfma_f32_16x16x32_bf16 v[108:111], v[144:147], v[192:195], v[108:111]
	v_mfma_f32_16x16x32_bf16 v[108:111], v[148:151], v[196:199], v[108:111]
	v_mfma_f32_16x16x32_bf16 v[92:95], v[144:147], v[200:203], v[92:95]
	v_mfma_f32_16x16x32_bf16 v[92:95], v[148:151], v[204:207], v[92:95]
	v_mfma_f32_16x16x32_bf16 v[76:79], v[144:147], v[208:211], v[76:79]
	v_mfma_f32_16x16x32_bf16 v[76:79], v[148:151], v[212:215], v[76:79]
	v_mfma_f32_16x16x32_bf16 v[120:123], v[152:155], v[184:187], v[120:123]
	v_mfma_f32_16x16x32_bf16 v[120:123], v[156:159], v[188:191], v[120:123]
	v_mfma_f32_16x16x32_bf16 v[104:107], v[152:155], v[192:195], v[104:107]
	v_mfma_f32_16x16x32_bf16 v[104:107], v[156:159], v[196:199], v[104:107]
	v_mfma_f32_16x16x32_bf16 v[88:91], v[152:155], v[200:203], v[88:91]
	v_mfma_f32_16x16x32_bf16 v[88:91], v[156:159], v[204:207], v[88:91]
	v_mfma_f32_16x16x32_bf16 v[72:75], v[152:155], v[208:211], v[72:75]
	v_mfma_f32_16x16x32_bf16 v[72:75], v[156:159], v[212:215], v[72:75]
	v_mfma_f32_16x16x32_bf16 v[116:119], v[168:171], v[184:187], v[116:119]
	v_mfma_f32_16x16x32_bf16 v[116:119], v[172:175], v[188:191], v[116:119]
	v_mfma_f32_16x16x32_bf16 v[100:103], v[168:171], v[192:195], v[100:103]
	v_mfma_f32_16x16x32_bf16 v[100:103], v[172:175], v[196:199], v[100:103]
	v_mfma_f32_16x16x32_bf16 v[84:87], v[168:171], v[200:203], v[84:87]
	v_mfma_f32_16x16x32_bf16 v[84:87], v[172:175], v[204:207], v[84:87]
	v_mfma_f32_16x16x32_bf16 v[68:71], v[168:171], v[208:211], v[68:71]
	v_mfma_f32_16x16x32_bf16 v[68:71], v[172:175], v[212:215], v[68:71]
	v_mfma_f32_16x16x32_bf16 v[112:115], v[176:179], v[184:187], v[112:115]
	v_mfma_f32_16x16x32_bf16 v[112:115], v[180:183], v[188:191], v[112:115]
	v_mfma_f32_16x16x32_bf16 v[96:99], v[176:179], v[192:195], v[96:99]
	v_mfma_f32_16x16x32_bf16 v[96:99], v[180:183], v[196:199], v[96:99]
	s_setprio 2
	s_barrier
	v_mfma_f32_16x16x32_bf16 v[80:83], v[176:179], v[200:203], v[80:83]
	v_mfma_f32_16x16x32_bf16 v[80:83], v[180:183], v[204:207], v[80:83]
	v_mfma_f32_16x16x32_bf16 v[64:67], v[176:179], v[208:211], v[64:67]
	v_mfma_f32_16x16x32_bf16 v[64:67], v[180:183], v[212:215], v[64:67]
	s_setprio 2
	s_add_i32 s40, s66, s47
	v_lshl_add_u64 v[160:161], v[160:161], 0, s[16:17]
	s_mov_b32 m0, s40
	ds_read_b128 v[184:187], v165 offset:49152
	ds_read_b128 v[188:191], v165 offset:50176
	ds_read_b128 v[192:195], v165 offset:51200
	ds_read_b128 v[196:199], v165 offset:52224
	ds_read_b128 v[200:203], v165 offset:53248
	ds_read_b128 v[204:207], v165 offset:54272
	ds_read_b128 v[208:211], v165 offset:55296
	ds_read_b128 v[212:215], v165 offset:56320
	global_load_lds_dwordx4 v[160:161], off
	s_add_i32 m0, s40, 0x2000
	s_add_u32 s38, s38, 0x40080
	v_lshl_add_u64 v[160:161], v[216:217], 0, s[16:17]
	s_addc_u32 s39, s39, 0
	s_add_i32 s40, s67, s47
	global_load_lds_dwordx4 v[160:161], off
	s_mov_b32 m0, s40
	v_lshl_add_u64 v[160:161], s[38:39], 0, v[132:133]
	global_load_lds_dwordx4 v[160:161], off
	s_add_i32 m0, s40, 0x2000
	v_lshl_add_u64 v[160:161], s[38:39], 0, v[128:129]
	global_load_lds_dwordx4 v[160:161], off
	s_mov_b32 m0, s57
	v_lshl_add_u64 v[160:161], v[218:219], 0, s[16:17]
	global_load_lds_dwordx4 v[160:161], off
	s_mov_b32 m0, s58
	v_lshl_add_u64 v[160:161], v[220:221], 0, s[16:17]
	global_load_lds_dwordx4 v[160:161], off
	s_waitcnt vmcnt(8) lgkmcnt(0)
	s_barrier
	s_setprio 1
	v_mfma_f32_16x16x32_bf16 v[60:63], v[144:147], v[184:187], v[60:63]
	v_mfma_f32_16x16x32_bf16 v[60:63], v[148:151], v[188:191], v[60:63]
	v_mfma_f32_16x16x32_bf16 v[44:47], v[144:147], v[192:195], v[44:47]
	v_mfma_f32_16x16x32_bf16 v[44:47], v[148:151], v[196:199], v[44:47]
	v_mfma_f32_16x16x32_bf16 v[28:31], v[144:147], v[200:203], v[28:31]
	v_mfma_f32_16x16x32_bf16 v[28:31], v[148:151], v[204:207], v[28:31]
	v_mfma_f32_16x16x32_bf16 v[12:15], v[144:147], v[208:211], v[12:15]
	v_mfma_f32_16x16x32_bf16 v[12:15], v[148:151], v[212:215], v[12:15]
	v_mfma_f32_16x16x32_bf16 v[56:59], v[152:155], v[184:187], v[56:59]
	v_mfma_f32_16x16x32_bf16 v[56:59], v[156:159], v[188:191], v[56:59]
	v_mfma_f32_16x16x32_bf16 v[40:43], v[152:155], v[192:195], v[40:43]
	v_mfma_f32_16x16x32_bf16 v[40:43], v[156:159], v[196:199], v[40:43]
	v_mfma_f32_16x16x32_bf16 v[24:27], v[152:155], v[200:203], v[24:27]
	v_mfma_f32_16x16x32_bf16 v[24:27], v[156:159], v[204:207], v[24:27]
	v_mfma_f32_16x16x32_bf16 v[8:11], v[152:155], v[208:211], v[8:11]
	v_mfma_f32_16x16x32_bf16 v[8:11], v[156:159], v[212:215], v[8:11]
	v_mfma_f32_16x16x32_bf16 v[52:55], v[168:171], v[184:187], v[52:55]
	v_mfma_f32_16x16x32_bf16 v[52:55], v[172:175], v[188:191], v[52:55]
	v_mfma_f32_16x16x32_bf16 v[36:39], v[168:171], v[192:195], v[36:39]
	v_mfma_f32_16x16x32_bf16 v[36:39], v[172:175], v[196:199], v[36:39]
	v_mfma_f32_16x16x32_bf16 v[20:23], v[168:171], v[200:203], v[20:23]
	v_mfma_f32_16x16x32_bf16 v[20:23], v[172:175], v[204:207], v[20:23]
	v_mfma_f32_16x16x32_bf16 v[4:7], v[168:171], v[208:211], v[4:7]
	v_mfma_f32_16x16x32_bf16 v[4:7], v[172:175], v[212:215], v[4:7]
	v_mfma_f32_16x16x32_bf16 v[48:51], v[176:179], v[184:187], v[48:51]
	v_mfma_f32_16x16x32_bf16 v[48:51], v[180:183], v[188:191], v[48:51]
	v_mfma_f32_16x16x32_bf16 v[32:35], v[176:179], v[192:195], v[32:35]
	v_mfma_f32_16x16x32_bf16 v[32:35], v[180:183], v[196:199], v[32:35]
	s_setprio 2
	s_barrier
	v_mfma_f32_16x16x32_bf16 v[16:19], v[176:179], v[200:203], v[16:19]
	v_mfma_f32_16x16x32_bf16 v[16:19], v[180:183], v[204:207], v[16:19]
	v_mfma_f32_16x16x32_bf16 v[0:3], v[176:179], v[208:211], v[0:3]
	v_mfma_f32_16x16x32_bf16 v[0:3], v[180:183], v[212:215], v[0:3]
	s_setprio 0
	s_add_i32 s65, s65, 2
	s_add_u32 s36, s36, 0x100
	s_addc_u32 s37, s37, 0
	s_add_u32 s63, s63, 0x100
	s_addc_u32 s64, s64, 0
	s_cmp_gt_u32 s65, 13
	s_cbranch_scc0 .LBB0_784

.LBB0_865:
	s_add_u32 s62, s28, 0x100
	s_addc_u32 s63, s29, 0
	s_mov_b32 s64, -2
	ds_read_b128 v[120:123], v233
	ds_read_b128 v[124:127], v233 offset:1024
	ds_read_b128 v[136:139], v233 offset:2048
	ds_read_b128 v[140:143], v233 offset:3072
	ds_read_b128 v[144:147], v234
	ds_read_b128 v[148:151], v234 offset:1024
	ds_read_b128 v[152:155], v234 offset:2048
	ds_read_b128 v[156:159], v234 offset:3072
	s_add_u32 s28, s26, 0x100
	s_addc_u32 s29, s27, 0
	s_cmp_eq_u32 s64, 40
	s_cselect_b32 s37, s7, s29
	s_cselect_b32 s36, s6, s28
	s_cselect_b32 s31, s25, s63
	s_cselect_b32 s30, s24, s62
	v_lshl_add_u64 v[208:209], s[26:27], 0, v[192:193]
	s_add_i32 m0, s44, 0xc000
	ds_read_b128 v[160:163], v235
	ds_read_b128 v[164:167], v235 offset:1024
	ds_read_b128 v[168:171], v235 offset:2048
	ds_read_b128 v[172:175], v235 offset:3072
	ds_read_b128 v[176:179], v235 offset:4096
	ds_read_b128 v[180:183], v235 offset:5120
	ds_read_b128 v[200:203], v235 offset:6144
	ds_read_b128 v[204:207], v235 offset:7168
	global_load_lds_dwordx4 v[208:209], off
	s_add_i32 m0, s44, 0xe000
	v_lshl_add_u64 v[208:209], s[26:27], 0, v[194:195]
	global_load_lds_dwordx4 v[208:209], off
	s_waitcnt vmcnt(8) lgkmcnt(0)
	s_barrier
	s_setprio 1
	v_mfma_f32_16x16x32_bf16 v[132:135], v[120:123], v[160:163], 0
	v_mfma_f32_16x16x32_bf16 v[132:135], v[124:127], v[164:167], v[132:135]
	v_mfma_f32_16x16x32_bf16 v[108:111], v[120:123], v[168:171], 0
	v_mfma_f32_16x16x32_bf16 v[108:111], v[124:127], v[172:175], v[108:111]
	v_mfma_f32_16x16x32_bf16 v[92:95], v[120:123], v[176:179], 0
	v_mfma_f32_16x16x32_bf16 v[92:95], v[124:127], v[180:183], v[92:95]
	v_mfma_f32_16x16x32_bf16 v[76:79], v[120:123], v[200:203], 0
	v_mfma_f32_16x16x32_bf16 v[76:79], v[124:127], v[204:207], v[76:79]
	v_mfma_f32_16x16x32_bf16 v[128:131], v[136:139], v[160:163], 0
	v_mfma_f32_16x16x32_bf16 v[128:131], v[140:143], v[164:167], v[128:131]
	v_mfma_f32_16x16x32_bf16 v[104:107], v[136:139], v[168:171], 0
	v_mfma_f32_16x16x32_bf16 v[104:107], v[140:143], v[172:175], v[104:107]
	v_mfma_f32_16x16x32_bf16 v[88:91], v[136:139], v[176:179], 0
	v_mfma_f32_16x16x32_bf16 v[88:91], v[140:143], v[180:183], v[88:91]
	v_mfma_f32_16x16x32_bf16 v[72:75], v[136:139], v[200:203], 0
	v_mfma_f32_16x16x32_bf16 v[72:75], v[140:143], v[204:207], v[72:75]
	v_mfma_f32_16x16x32_bf16 v[116:119], v[144:147], v[160:163], 0
	v_mfma_f32_16x16x32_bf16 v[116:119], v[148:151], v[164:167], v[116:119]
	v_mfma_f32_16x16x32_bf16 v[100:103], v[144:147], v[168:171], 0
	v_mfma_f32_16x16x32_bf16 v[100:103], v[148:151], v[172:175], v[100:103]
	v_mfma_f32_16x16x32_bf16 v[84:87], v[144:147], v[176:179], 0
	v_mfma_f32_16x16x32_bf16 v[84:87], v[148:151], v[180:183], v[84:87]
	v_mfma_f32_16x16x32_bf16 v[68:71], v[144:147], v[200:203], 0
	v_mfma_f32_16x16x32_bf16 v[68:71], v[148:151], v[204:207], v[68:71]
	v_mfma_f32_16x16x32_bf16 v[112:115], v[152:155], v[160:163], 0
	v_mfma_f32_16x16x32_bf16 v[112:115], v[156:159], v[164:167], v[112:115]
	v_mfma_f32_16x16x32_bf16 v[96:99], v[152:155], v[168:171], 0
	v_mfma_f32_16x16x32_bf16 v[96:99], v[156:159], v[172:175], v[96:99]
	s_setprio 2
	s_barrier
	v_mfma_f32_16x16x32_bf16 v[80:83], v[152:155], v[176:179], 0
	v_mfma_f32_16x16x32_bf16 v[80:83], v[156:159], v[180:183], v[80:83]
	v_mfma_f32_16x16x32_bf16 v[64:67], v[152:155], v[200:203], 0
	v_mfma_f32_16x16x32_bf16 v[64:67], v[156:159], v[204:207], v[64:67]
	s_setprio 2
	s_add_i32 s26, s56, s43
	v_lshl_add_u64 v[208:209], s[30:31], 0, v[186:187]
	s_mov_b32 m0, s26
	ds_read_b128 v[160:163], v235 offset:16384
	ds_read_b128 v[164:167], v235 offset:17408
	ds_read_b128 v[168:171], v235 offset:18432
	ds_read_b128 v[172:175], v235 offset:19456
	ds_read_b128 v[176:179], v235 offset:20480
	ds_read_b128 v[180:183], v235 offset:21504
	ds_read_b128 v[200:203], v235 offset:22528
	ds_read_b128 v[204:207], v235 offset:23552
	global_load_lds_dwordx4 v[208:209], off
	s_add_i32 m0, s26, 0x2000
	s_add_u32 s26, s30, 0xb0000
	v_lshl_add_u64 v[210:211], s[30:31], 0, v[190:191]
	s_addc_u32 s27, s31, 0
	s_add_i32 s65, s57, s43
	global_load_lds_dwordx4 v[210:211], off
	v_lshl_add_u64 v[212:213], s[26:27], 0, v[186:187]
	s_mov_b32 m0, s65
	v_lshl_add_u64 v[214:215], s[36:37], 0, v[188:189]
	global_load_lds_dwordx4 v[212:213], off
	s_add_i32 m0, s65, 0x2000
	v_lshl_add_u64 v[212:213], s[26:27], 0, v[190:191]
	global_load_lds_dwordx4 v[212:213], off
	s_mov_b32 m0, s44
	v_lshl_add_u64 v[212:213], s[36:37], 0, v[184:185]
	global_load_lds_dwordx4 v[212:213], off
	s_mov_b32 m0, s45
	s_nop 0
	global_load_lds_dwordx4 v[214:215], off
	s_waitcnt vmcnt(8) lgkmcnt(0)
	s_barrier
	s_setprio 1
	v_mfma_f32_16x16x32_bf16 v[60:63], v[120:123], v[160:163], 0
	v_mfma_f32_16x16x32_bf16 v[60:63], v[124:127], v[164:167], v[60:63]
	v_mfma_f32_16x16x32_bf16 v[44:47], v[120:123], v[168:171], 0
	v_mfma_f32_16x16x32_bf16 v[44:47], v[124:127], v[172:175], v[44:47]
	v_mfma_f32_16x16x32_bf16 v[28:31], v[120:123], v[176:179], 0
	v_mfma_f32_16x16x32_bf16 v[28:31], v[124:127], v[180:183], v[28:31]
	v_mfma_f32_16x16x32_bf16 v[12:15], v[120:123], v[200:203], 0
	v_mfma_f32_16x16x32_bf16 v[12:15], v[124:127], v[204:207], v[12:15]
	v_mfma_f32_16x16x32_bf16 v[56:59], v[136:139], v[160:163], 0
	v_mfma_f32_16x16x32_bf16 v[56:59], v[140:143], v[164:167], v[56:59]
	v_mfma_f32_16x16x32_bf16 v[40:43], v[136:139], v[168:171], 0
	v_mfma_f32_16x16x32_bf16 v[40:43], v[140:143], v[172:175], v[40:43]
	v_mfma_f32_16x16x32_bf16 v[24:27], v[136:139], v[176:179], 0
	v_mfma_f32_16x16x32_bf16 v[24:27], v[140:143], v[180:183], v[24:27]
	v_mfma_f32_16x16x32_bf16 v[8:11], v[136:139], v[200:203], 0
	v_mfma_f32_16x16x32_bf16 v[8:11], v[140:143], v[204:207], v[8:11]
	v_mfma_f32_16x16x32_bf16 v[52:55], v[144:147], v[160:163], 0
	v_mfma_f32_16x16x32_bf16 v[52:55], v[148:151], v[164:167], v[52:55]
	v_mfma_f32_16x16x32_bf16 v[36:39], v[144:147], v[168:171], 0
	v_mfma_f32_16x16x32_bf16 v[36:39], v[148:151], v[172:175], v[36:39]
	v_mfma_f32_16x16x32_bf16 v[20:23], v[144:147], v[176:179], 0
	v_mfma_f32_16x16x32_bf16 v[20:23], v[148:151], v[180:183], v[20:23]
	v_mfma_f32_16x16x32_bf16 v[4:7], v[144:147], v[200:203], 0
	v_mfma_f32_16x16x32_bf16 v[4:7], v[148:151], v[204:207], v[4:7]
	v_mfma_f32_16x16x32_bf16 v[48:51], v[152:155], v[160:163], 0
	v_mfma_f32_16x16x32_bf16 v[48:51], v[156:159], v[164:167], v[48:51]
	v_mfma_f32_16x16x32_bf16 v[32:35], v[152:155], v[168:171], 0
	v_mfma_f32_16x16x32_bf16 v[32:35], v[156:159], v[172:175], v[32:35]
	s_setprio 2
	s_barrier
	v_mfma_f32_16x16x32_bf16 v[16:19], v[152:155], v[176:179], 0
	v_mfma_f32_16x16x32_bf16 v[16:19], v[156:159], v[180:183], v[16:19]
	v_mfma_f32_16x16x32_bf16 v[0:3], v[152:155], v[200:203], 0
	v_mfma_f32_16x16x32_bf16 v[0:3], v[156:159], v[204:207], v[0:3]
	s_setprio 0
	s_add_i32 s65, 0, 0x18000
	s_add_i32 s66, 0, 0x1c000
	v_add_u32_e32 v140, s65, v232
	v_add_u32_e32 v156, s66, v232
	ds_read_b128 v[120:123], v140
	ds_read_b128 v[124:127], v140 offset:1024
	ds_read_b128 v[136:139], v140 offset:2048
	ds_read_b128 v[140:143], v140 offset:3072
	ds_read_b128 v[144:147], v156
	ds_read_b128 v[148:151], v156 offset:1024
	ds_read_b128 v[152:155], v156 offset:2048
	ds_read_b128 v[156:159], v156 offset:3072
	s_add_u32 s26, s36, 0xb0000
	s_addc_u32 s27, s37, 0
	s_mov_b32 m0, s46
	v_lshl_add_u64 v[216:217], s[26:27], 0, v[184:185]
	ds_read_b128 v[160:163], v235 offset:32768
	ds_read_b128 v[164:167], v235 offset:33792
	ds_read_b128 v[168:171], v235 offset:34816
	ds_read_b128 v[172:175], v235 offset:35840
	ds_read_b128 v[176:179], v235 offset:36864
	ds_read_b128 v[180:183], v235 offset:37888
	ds_read_b128 v[200:203], v235 offset:38912
	ds_read_b128 v[204:207], v235 offset:39936
	global_load_lds_dwordx4 v[216:217], off
	s_mov_b32 m0, s47
	v_lshl_add_u64 v[216:217], s[26:27], 0, v[188:189]
	global_load_lds_dwordx4 v[216:217], off
	s_waitcnt vmcnt(8) lgkmcnt(0)
	s_barrier
	s_setprio 1
	v_mfma_f32_16x16x32_bf16 v[132:135], v[120:123], v[160:163], v[132:135]
	v_mfma_f32_16x16x32_bf16 v[132:135], v[124:127], v[164:167], v[132:135]
	v_mfma_f32_16x16x32_bf16 v[108:111], v[120:123], v[168:171], v[108:111]
	v_mfma_f32_16x16x32_bf16 v[108:111], v[124:127], v[172:175], v[108:111]
	v_mfma_f32_16x16x32_bf16 v[92:95], v[120:123], v[176:179], v[92:95]
	v_mfma_f32_16x16x32_bf16 v[92:95], v[124:127], v[180:183], v[92:95]
	v_mfma_f32_16x16x32_bf16 v[76:79], v[120:123], v[200:203], v[76:79]
	v_mfma_f32_16x16x32_bf16 v[76:79], v[124:127], v[204:207], v[76:79]
	v_mfma_f32_16x16x32_bf16 v[128:131], v[136:139], v[160:163], v[128:131]
	v_mfma_f32_16x16x32_bf16 v[128:131], v[140:143], v[164:167], v[128:131]
	v_mfma_f32_16x16x32_bf16 v[104:107], v[136:139], v[168:171], v[104:107]
	v_mfma_f32_16x16x32_bf16 v[104:107], v[140:143], v[172:175], v[104:107]
	v_mfma_f32_16x16x32_bf16 v[88:91], v[136:139], v[176:179], v[88:91]
	v_mfma_f32_16x16x32_bf16 v[88:91], v[140:143], v[180:183], v[88:91]
	v_mfma_f32_16x16x32_bf16 v[72:75], v[136:139], v[200:203], v[72:75]
	v_mfma_f32_16x16x32_bf16 v[72:75], v[140:143], v[204:207], v[72:75]
	v_mfma_f32_16x16x32_bf16 v[116:119], v[144:147], v[160:163], v[116:119]
	v_mfma_f32_16x16x32_bf16 v[116:119], v[148:151], v[164:167], v[116:119]
	v_mfma_f32_16x16x32_bf16 v[100:103], v[144:147], v[168:171], v[100:103]
	v_mfma_f32_16x16x32_bf16 v[100:103], v[148:151], v[172:175], v[100:103]
	v_mfma_f32_16x16x32_bf16 v[84:87], v[144:147], v[176:179], v[84:87]
	v_mfma_f32_16x16x32_bf16 v[84:87], v[148:151], v[180:183], v[84:87]
	v_mfma_f32_16x16x32_bf16 v[68:71], v[144:147], v[200:203], v[68:71]
	v_mfma_f32_16x16x32_bf16 v[68:71], v[148:151], v[204:207], v[68:71]
	v_mfma_f32_16x16x32_bf16 v[112:115], v[152:155], v[160:163], v[112:115]
	v_mfma_f32_16x16x32_bf16 v[112:115], v[156:159], v[164:167], v[112:115]
	v_mfma_f32_16x16x32_bf16 v[96:99], v[152:155], v[168:171], v[96:99]
	v_mfma_f32_16x16x32_bf16 v[96:99], v[156:159], v[172:175], v[96:99]
	s_setprio 2
	s_barrier
	v_mfma_f32_16x16x32_bf16 v[80:83], v[152:155], v[176:179], v[80:83]
	v_mfma_f32_16x16x32_bf16 v[80:83], v[156:159], v[180:183], v[80:83]
	v_mfma_f32_16x16x32_bf16 v[64:67], v[152:155], v[200:203], v[64:67]
	v_mfma_f32_16x16x32_bf16 v[64:67], v[156:159], v[204:207], v[64:67]
	s_setprio 2
	s_add_i32 s26, s65, s43
	v_lshl_add_u64 v[208:209], v[208:209], 0, s[20:21]
	s_mov_b32 m0, s26
	ds_read_b128 v[160:163], v235 offset:49152
	ds_read_b128 v[164:167], v235 offset:50176
	ds_read_b128 v[168:171], v235 offset:51200
	ds_read_b128 v[172:175], v235 offset:52224
	ds_read_b128 v[176:179], v235 offset:53248
	ds_read_b128 v[180:183], v235 offset:54272
	ds_read_b128 v[200:203], v235 offset:55296
	ds_read_b128 v[204:207], v235 offset:56320
	global_load_lds_dwordx4 v[208:209], off
	s_add_i32 m0, s26, 0x2000
	s_add_u32 s26, s30, 0xb0080
	v_lshl_add_u64 v[208:209], v[210:211], 0, s[20:21]
	s_addc_u32 s27, s31, 0
	s_add_i32 s30, s66, s43
	global_load_lds_dwordx4 v[208:209], off
	s_mov_b32 m0, s30
	v_lshl_add_u64 v[208:209], s[26:27], 0, v[186:187]
	global_load_lds_dwordx4 v[208:209], off
	s_add_i32 m0, s30, 0x2000
	v_lshl_add_u64 v[208:209], s[26:27], 0, v[190:191]
	global_load_lds_dwordx4 v[208:209], off
	s_mov_b32 m0, s49
	v_lshl_add_u64 v[208:209], v[212:213], 0, s[20:21]
	global_load_lds_dwordx4 v[208:209], off
	s_mov_b32 m0, s50
	v_lshl_add_u64 v[208:209], v[214:215], 0, s[20:21]
	global_load_lds_dwordx4 v[208:209], off
	s_waitcnt vmcnt(8) lgkmcnt(0)
	s_barrier
	s_setprio 1
	v_mfma_f32_16x16x32_bf16 v[60:63], v[120:123], v[160:163], v[60:63]
	v_mfma_f32_16x16x32_bf16 v[60:63], v[124:127], v[164:167], v[60:63]
	v_mfma_f32_16x16x32_bf16 v[44:47], v[120:123], v[168:171], v[44:47]
	v_mfma_f32_16x16x32_bf16 v[44:47], v[124:127], v[172:175], v[44:47]
	v_mfma_f32_16x16x32_bf16 v[28:31], v[120:123], v[176:179], v[28:31]
	v_mfma_f32_16x16x32_bf16 v[28:31], v[124:127], v[180:183], v[28:31]
	v_mfma_f32_16x16x32_bf16 v[12:15], v[120:123], v[200:203], v[12:15]
	v_mfma_f32_16x16x32_bf16 v[12:15], v[124:127], v[204:207], v[12:15]
	v_mfma_f32_16x16x32_bf16 v[56:59], v[136:139], v[160:163], v[56:59]
	v_mfma_f32_16x16x32_bf16 v[56:59], v[140:143], v[164:167], v[56:59]
	v_mfma_f32_16x16x32_bf16 v[40:43], v[136:139], v[168:171], v[40:43]
	v_mfma_f32_16x16x32_bf16 v[40:43], v[140:143], v[172:175], v[40:43]
	v_mfma_f32_16x16x32_bf16 v[24:27], v[136:139], v[176:179], v[24:27]
	v_mfma_f32_16x16x32_bf16 v[24:27], v[140:143], v[180:183], v[24:27]
	v_mfma_f32_16x16x32_bf16 v[8:11], v[136:139], v[200:203], v[8:11]
	v_mfma_f32_16x16x32_bf16 v[8:11], v[140:143], v[204:207], v[8:11]
	v_mfma_f32_16x16x32_bf16 v[52:55], v[144:147], v[160:163], v[52:55]
	v_mfma_f32_16x16x32_bf16 v[52:55], v[148:151], v[164:167], v[52:55]
	v_mfma_f32_16x16x32_bf16 v[36:39], v[144:147], v[168:171], v[36:39]
	v_mfma_f32_16x16x32_bf16 v[36:39], v[148:151], v[172:175], v[36:39]
	v_mfma_f32_16x16x32_bf16 v[20:23], v[144:147], v[176:179], v[20:23]
	v_mfma_f32_16x16x32_bf16 v[20:23], v[148:151], v[180:183], v[20:23]
	v_mfma_f32_16x16x32_bf16 v[4:7], v[144:147], v[200:203], v[4:7]
	v_mfma_f32_16x16x32_bf16 v[4:7], v[148:151], v[204:207], v[4:7]
	v_mfma_f32_16x16x32_bf16 v[48:51], v[152:155], v[160:163], v[48:51]
	v_mfma_f32_16x16x32_bf16 v[48:51], v[156:159], v[164:167], v[48:51]
	v_mfma_f32_16x16x32_bf16 v[32:35], v[152:155], v[168:171], v[32:35]
	v_mfma_f32_16x16x32_bf16 v[32:35], v[156:159], v[172:175], v[32:35]
	s_setprio 2
	s_barrier
	v_mfma_f32_16x16x32_bf16 v[16:19], v[152:155], v[176:179], v[16:19]
	v_mfma_f32_16x16x32_bf16 v[16:19], v[156:159], v[180:183], v[16:19]
	v_mfma_f32_16x16x32_bf16 v[0:3], v[152:155], v[200:203], v[0:3]
	v_mfma_f32_16x16x32_bf16 v[0:3], v[156:159], v[204:207], v[0:3]
	s_setprio 0
	s_add_i32 s64, s64, 2
	s_add_u32 s62, s62, 0x100
	s_addc_u32 s63, s63, 0
	s_cmp_gt_u32 s64, 41
	s_mov_b64 s[26:27], s[28:29]
.LBB0_866:
	ds_read_b128 v[120:123], v233
	ds_read_b128 v[124:127], v233 offset:1024
	ds_read_b128 v[136:139], v233 offset:2048
	ds_read_b128 v[140:143], v233 offset:3072
	ds_read_b128 v[144:147], v234
	ds_read_b128 v[148:151], v234 offset:1024
	ds_read_b128 v[152:155], v234 offset:2048
	ds_read_b128 v[156:159], v234 offset:3072
	s_add_u32 s28, s26, 0x100
	s_addc_u32 s29, s27, 0
	s_cmp_eq_u32 s64, 40
	s_cselect_b32 s37, s7, s29
	s_cselect_b32 s36, s6, s28
	s_cselect_b32 s31, s25, s63
	s_cselect_b32 s30, s24, s62
	v_lshl_add_u64 v[208:209], s[26:27], 0, v[192:193]
	s_add_i32 m0, s44, 0xc000
	ds_read_b128 v[160:163], v235
	ds_read_b128 v[164:167], v235 offset:1024
	ds_read_b128 v[168:171], v235 offset:2048
	ds_read_b128 v[172:175], v235 offset:3072
	ds_read_b128 v[176:179], v235 offset:4096
	ds_read_b128 v[180:183], v235 offset:5120
	ds_read_b128 v[200:203], v235 offset:6144
	ds_read_b128 v[204:207], v235 offset:7168
	global_load_lds_dwordx4 v[208:209], off
	s_add_i32 m0, s44, 0xe000
	v_lshl_add_u64 v[208:209], s[26:27], 0, v[194:195]
	global_load_lds_dwordx4 v[208:209], off
	s_waitcnt vmcnt(8) lgkmcnt(0)
	s_barrier
	s_setprio 1
	v_mfma_f32_16x16x32_bf16 v[132:135], v[120:123], v[160:163], v[132:135]
	v_mfma_f32_16x16x32_bf16 v[132:135], v[124:127], v[164:167], v[132:135]
	v_mfma_f32_16x16x32_bf16 v[108:111], v[120:123], v[168:171], v[108:111]
	v_mfma_f32_16x16x32_bf16 v[108:111], v[124:127], v[172:175], v[108:111]
	v_mfma_f32_16x16x32_bf16 v[92:95], v[120:123], v[176:179], v[92:95]
	v_mfma_f32_16x16x32_bf16 v[92:95], v[124:127], v[180:183], v[92:95]
	v_mfma_f32_16x16x32_bf16 v[76:79], v[120:123], v[200:203], v[76:79]
	v_mfma_f32_16x16x32_bf16 v[76:79], v[124:127], v[204:207], v[76:79]
	v_mfma_f32_16x16x32_bf16 v[128:131], v[136:139], v[160:163], v[128:131]
	v_mfma_f32_16x16x32_bf16 v[128:131], v[140:143], v[164:167], v[128:131]
	v_mfma_f32_16x16x32_bf16 v[104:107], v[136:139], v[168:171], v[104:107]
	v_mfma_f32_16x16x32_bf16 v[104:107], v[140:143], v[172:175], v[104:107]
	v_mfma_f32_16x16x32_bf16 v[88:91], v[136:139], v[176:179], v[88:91]
	v_mfma_f32_16x16x32_bf16 v[88:91], v[140:143], v[180:183], v[88:91]
	v_mfma_f32_16x16x32_bf16 v[72:75], v[136:139], v[200:203], v[72:75]
	v_mfma_f32_16x16x32_bf16 v[72:75], v[140:143], v[204:207], v[72:75]
	v_mfma_f32_16x16x32_bf16 v[116:119], v[144:147], v[160:163], v[116:119]
	v_mfma_f32_16x16x32_bf16 v[116:119], v[148:151], v[164:167], v[116:119]
	v_mfma_f32_16x16x32_bf16 v[100:103], v[144:147], v[168:171], v[100:103]
	v_mfma_f32_16x16x32_bf16 v[100:103], v[148:151], v[172:175], v[100:103]
	v_mfma_f32_16x16x32_bf16 v[84:87], v[144:147], v[176:179], v[84:87]
	v_mfma_f32_16x16x32_bf16 v[84:87], v[148:151], v[180:183], v[84:87]
	v_mfma_f32_16x16x32_bf16 v[68:71], v[144:147], v[200:203], v[68:71]
	v_mfma_f32_16x16x32_bf16 v[68:71], v[148:151], v[204:207], v[68:71]
	v_mfma_f32_16x16x32_bf16 v[112:115], v[152:155], v[160:163], v[112:115]
	v_mfma_f32_16x16x32_bf16 v[112:115], v[156:159], v[164:167], v[112:115]
	v_mfma_f32_16x16x32_bf16 v[96:99], v[152:155], v[168:171], v[96:99]
	v_mfma_f32_16x16x32_bf16 v[96:99], v[156:159], v[172:175], v[96:99]
	s_setprio 2
	s_barrier
	v_mfma_f32_16x16x32_bf16 v[80:83], v[152:155], v[176:179], v[80:83]
	v_mfma_f32_16x16x32_bf16 v[80:83], v[156:159], v[180:183], v[80:83]
	v_mfma_f32_16x16x32_bf16 v[64:67], v[152:155], v[200:203], v[64:67]
	v_mfma_f32_16x16x32_bf16 v[64:67], v[156:159], v[204:207], v[64:67]
	s_setprio 2
	s_add_i32 s26, s56, s43
	v_lshl_add_u64 v[208:209], s[30:31], 0, v[186:187]
	s_mov_b32 m0, s26
	ds_read_b128 v[160:163], v235 offset:16384
	ds_read_b128 v[164:167], v235 offset:17408
	ds_read_b128 v[168:171], v235 offset:18432
	ds_read_b128 v[172:175], v235 offset:19456
	ds_read_b128 v[176:179], v235 offset:20480
	ds_read_b128 v[180:183], v235 offset:21504
	ds_read_b128 v[200:203], v235 offset:22528
	ds_read_b128 v[204:207], v235 offset:23552
	global_load_lds_dwordx4 v[208:209], off
	s_add_i32 m0, s26, 0x2000
	s_add_u32 s26, s30, 0xb0000
	v_lshl_add_u64 v[210:211], s[30:31], 0, v[190:191]
	s_addc_u32 s27, s31, 0
	s_add_i32 s65, s57, s43
	global_load_lds_dwordx4 v[210:211], off
	v_lshl_add_u64 v[212:213], s[26:27], 0, v[186:187]
	s_mov_b32 m0, s65
	v_lshl_add_u64 v[214:215], s[36:37], 0, v[188:189]
	global_load_lds_dwordx4 v[212:213], off
	s_add_i32 m0, s65, 0x2000
	v_lshl_add_u64 v[212:213], s[26:27], 0, v[190:191]
	global_load_lds_dwordx4 v[212:213], off
	s_mov_b32 m0, s44
	v_lshl_add_u64 v[212:213], s[36:37], 0, v[184:185]
	global_load_lds_dwordx4 v[212:213], off
	s_mov_b32 m0, s45
	s_nop 0
	global_load_lds_dwordx4 v[214:215], off
	s_waitcnt vmcnt(8) lgkmcnt(0)
	s_barrier
	s_setprio 1
	v_mfma_f32_16x16x32_bf16 v[60:63], v[120:123], v[160:163], v[60:63]
	v_mfma_f32_16x16x32_bf16 v[60:63], v[124:127], v[164:167], v[60:63]
	v_mfma_f32_16x16x32_bf16 v[44:47], v[120:123], v[168:171], v[44:47]
	v_mfma_f32_16x16x32_bf16 v[44:47], v[124:127], v[172:175], v[44:47]
	v_mfma_f32_16x16x32_bf16 v[28:31], v[120:123], v[176:179], v[28:31]
	v_mfma_f32_16x16x32_bf16 v[28:31], v[124:127], v[180:183], v[28:31]
	v_mfma_f32_16x16x32_bf16 v[12:15], v[120:123], v[200:203], v[12:15]
	v_mfma_f32_16x16x32_bf16 v[12:15], v[124:127], v[204:207], v[12:15]
	v_mfma_f32_16x16x32_bf16 v[56:59], v[136:139], v[160:163], v[56:59]
	v_mfma_f32_16x16x32_bf16 v[56:59], v[140:143], v[164:167], v[56:59]
	v_mfma_f32_16x16x32_bf16 v[40:43], v[136:139], v[168:171], v[40:43]
	v_mfma_f32_16x16x32_bf16 v[40:43], v[140:143], v[172:175], v[40:43]
	v_mfma_f32_16x16x32_bf16 v[24:27], v[136:139], v[176:179], v[24:27]
	v_mfma_f32_16x16x32_bf16 v[24:27], v[140:143], v[180:183], v[24:27]
	v_mfma_f32_16x16x32_bf16 v[8:11], v[136:139], v[200:203], v[8:11]
	v_mfma_f32_16x16x32_bf16 v[8:11], v[140:143], v[204:207], v[8:11]
	v_mfma_f32_16x16x32_bf16 v[52:55], v[144:147], v[160:163], v[52:55]
	v_mfma_f32_16x16x32_bf16 v[52:55], v[148:151], v[164:167], v[52:55]
	v_mfma_f32_16x16x32_bf16 v[36:39], v[144:147], v[168:171], v[36:39]
	v_mfma_f32_16x16x32_bf16 v[36:39], v[148:151], v[172:175], v[36:39]
	v_mfma_f32_16x16x32_bf16 v[20:23], v[144:147], v[176:179], v[20:23]
	v_mfma_f32_16x16x32_bf16 v[20:23], v[148:151], v[180:183], v[20:23]
	v_mfma_f32_16x16x32_bf16 v[4:7], v[144:147], v[200:203], v[4:7]
	v_mfma_f32_16x16x32_bf16 v[4:7], v[148:151], v[204:207], v[4:7]
	v_mfma_f32_16x16x32_bf16 v[48:51], v[152:155], v[160:163], v[48:51]
	v_mfma_f32_16x16x32_bf16 v[48:51], v[156:159], v[164:167], v[48:51]
	v_mfma_f32_16x16x32_bf16 v[32:35], v[152:155], v[168:171], v[32:35]
	v_mfma_f32_16x16x32_bf16 v[32:35], v[156:159], v[172:175], v[32:35]
	s_setprio 2
	s_barrier
	v_mfma_f32_16x16x32_bf16 v[16:19], v[152:155], v[176:179], v[16:19]
	v_mfma_f32_16x16x32_bf16 v[16:19], v[156:159], v[180:183], v[16:19]
	v_mfma_f32_16x16x32_bf16 v[0:3], v[152:155], v[200:203], v[0:3]
	v_mfma_f32_16x16x32_bf16 v[0:3], v[156:159], v[204:207], v[0:3]
	s_setprio 0
	s_add_i32 s65, 0, 0x18000
	s_add_i32 s66, 0, 0x1c000
	v_add_u32_e32 v140, s65, v232
	v_add_u32_e32 v156, s66, v232
	ds_read_b128 v[120:123], v140
	ds_read_b128 v[124:127], v140 offset:1024
	ds_read_b128 v[136:139], v140 offset:2048
	ds_read_b128 v[140:143], v140 offset:3072
	ds_read_b128 v[144:147], v156
	ds_read_b128 v[148:151], v156 offset:1024
	ds_read_b128 v[152:155], v156 offset:2048
	ds_read_b128 v[156:159], v156 offset:3072
	s_add_u32 s26, s36, 0xb0000
	s_addc_u32 s27, s37, 0
	s_mov_b32 m0, s46
	v_lshl_add_u64 v[216:217], s[26:27], 0, v[184:185]
	ds_read_b128 v[160:163], v235 offset:32768
	ds_read_b128 v[164:167], v235 offset:33792
	ds_read_b128 v[168:171], v235 offset:34816
	ds_read_b128 v[172:175], v235 offset:35840
	ds_read_b128 v[176:179], v235 offset:36864
	ds_read_b128 v[180:183], v235 offset:37888
	ds_read_b128 v[200:203], v235 offset:38912
	ds_read_b128 v[204:207], v235 offset:39936
	global_load_lds_dwordx4 v[216:217], off
	s_mov_b32 m0, s47
	v_lshl_add_u64 v[216:217], s[26:27], 0, v[188:189]
	global_load_lds_dwordx4 v[216:217], off
	s_waitcnt vmcnt(8) lgkmcnt(0)
	s_barrier
	s_setprio 1
	v_mfma_f32_16x16x32_bf16 v[132:135], v[120:123], v[160:163], v[132:135]
	v_mfma_f32_16x16x32_bf16 v[132:135], v[124:127], v[164:167], v[132:135]
	v_mfma_f32_16x16x32_bf16 v[108:111], v[120:123], v[168:171], v[108:111]
	v_mfma_f32_16x16x32_bf16 v[108:111], v[124:127], v[172:175], v[108:111]
	v_mfma_f32_16x16x32_bf16 v[92:95], v[120:123], v[176:179], v[92:95]
	v_mfma_f32_16x16x32_bf16 v[92:95], v[124:127], v[180:183], v[92:95]
	v_mfma_f32_16x16x32_bf16 v[76:79], v[120:123], v[200:203], v[76:79]
	v_mfma_f32_16x16x32_bf16 v[76:79], v[124:127], v[204:207], v[76:79]
	v_mfma_f32_16x16x32_bf16 v[128:131], v[136:139], v[160:163], v[128:131]
	v_mfma_f32_16x16x32_bf16 v[128:131], v[140:143], v[164:167], v[128:131]
	v_mfma_f32_16x16x32_bf16 v[104:107], v[136:139], v[168:171], v[104:107]
	v_mfma_f32_16x16x32_bf16 v[104:107], v[140:143], v[172:175], v[104:107]
	v_mfma_f32_16x16x32_bf16 v[88:91], v[136:139], v[176:179], v[88:91]
	v_mfma_f32_16x16x32_bf16 v[88:91], v[140:143], v[180:183], v[88:91]
	v_mfma_f32_16x16x32_bf16 v[72:75], v[136:139], v[200:203], v[72:75]
	v_mfma_f32_16x16x32_bf16 v[72:75], v[140:143], v[204:207], v[72:75]
	v_mfma_f32_16x16x32_bf16 v[116:119], v[144:147], v[160:163], v[116:119]
	v_mfma_f32_16x16x32_bf16 v[116:119], v[148:151], v[164:167], v[116:119]
	v_mfma_f32_16x16x32_bf16 v[100:103], v[144:147], v[168:171], v[100:103]
	v_mfma_f32_16x16x32_bf16 v[100:103], v[148:151], v[172:175], v[100:103]
	v_mfma_f32_16x16x32_bf16 v[84:87], v[144:147], v[176:179], v[84:87]
	v_mfma_f32_16x16x32_bf16 v[84:87], v[148:151], v[180:183], v[84:87]
	v_mfma_f32_16x16x32_bf16 v[68:71], v[144:147], v[200:203], v[68:71]
	v_mfma_f32_16x16x32_bf16 v[68:71], v[148:151], v[204:207], v[68:71]
	v_mfma_f32_16x16x32_bf16 v[112:115], v[152:155], v[160:163], v[112:115]
	v_mfma_f32_16x16x32_bf16 v[112:115], v[156:159], v[164:167], v[112:115]
	v_mfma_f32_16x16x32_bf16 v[96:99], v[152:155], v[168:171], v[96:99]
	v_mfma_f32_16x16x32_bf16 v[96:99], v[156:159], v[172:175], v[96:99]
	s_setprio 2
	s_barrier
	v_mfma_f32_16x16x32_bf16 v[80:83], v[152:155], v[176:179], v[80:83]
	v_mfma_f32_16x16x32_bf16 v[80:83], v[156:159], v[180:183], v[80:83]
	v_mfma_f32_16x16x32_bf16 v[64:67], v[152:155], v[200:203], v[64:67]
	v_mfma_f32_16x16x32_bf16 v[64:67], v[156:159], v[204:207], v[64:67]
	s_setprio 2
	s_add_i32 s26, s65, s43
	v_lshl_add_u64 v[208:209], v[208:209], 0, s[20:21]
	s_mov_b32 m0, s26
	ds_read_b128 v[160:163], v235 offset:49152
	ds_read_b128 v[164:167], v235 offset:50176
	ds_read_b128 v[168:171], v235 offset:51200
	ds_read_b128 v[172:175], v235 offset:52224
	ds_read_b128 v[176:179], v235 offset:53248
	ds_read_b128 v[180:183], v235 offset:54272
	ds_read_b128 v[200:203], v235 offset:55296
	ds_read_b128 v[204:207], v235 offset:56320
	global_load_lds_dwordx4 v[208:209], off
	s_add_i32 m0, s26, 0x2000
	s_add_u32 s26, s30, 0xb0080
	v_lshl_add_u64 v[208:209], v[210:211], 0, s[20:21]
	s_addc_u32 s27, s31, 0
	s_add_i32 s30, s66, s43
	global_load_lds_dwordx4 v[208:209], off
	s_mov_b32 m0, s30
	v_lshl_add_u64 v[208:209], s[26:27], 0, v[186:187]
	global_load_lds_dwordx4 v[208:209], off
	s_add_i32 m0, s30, 0x2000
	v_lshl_add_u64 v[208:209], s[26:27], 0, v[190:191]
	global_load_lds_dwordx4 v[208:209], off
	s_mov_b32 m0, s49
	v_lshl_add_u64 v[208:209], v[212:213], 0, s[20:21]
	global_load_lds_dwordx4 v[208:209], off
	s_mov_b32 m0, s50
	v_lshl_add_u64 v[208:209], v[214:215], 0, s[20:21]
	global_load_lds_dwordx4 v[208:209], off
	s_waitcnt vmcnt(8) lgkmcnt(0)
	s_barrier
	s_setprio 1
	v_mfma_f32_16x16x32_bf16 v[60:63], v[120:123], v[160:163], v[60:63]
	v_mfma_f32_16x16x32_bf16 v[60:63], v[124:127], v[164:167], v[60:63]
	v_mfma_f32_16x16x32_bf16 v[44:47], v[120:123], v[168:171], v[44:47]
	v_mfma_f32_16x16x32_bf16 v[44:47], v[124:127], v[172:175], v[44:47]
	v_mfma_f32_16x16x32_bf16 v[28:31], v[120:123], v[176:179], v[28:31]
	v_mfma_f32_16x16x32_bf16 v[28:31], v[124:127], v[180:183], v[28:31]
	v_mfma_f32_16x16x32_bf16 v[12:15], v[120:123], v[200:203], v[12:15]
	v_mfma_f32_16x16x32_bf16 v[12:15], v[124:127], v[204:207], v[12:15]
	v_mfma_f32_16x16x32_bf16 v[56:59], v[136:139], v[160:163], v[56:59]
	v_mfma_f32_16x16x32_bf16 v[56:59], v[140:143], v[164:167], v[56:59]
	v_mfma_f32_16x16x32_bf16 v[40:43], v[136:139], v[168:171], v[40:43]
	v_mfma_f32_16x16x32_bf16 v[40:43], v[140:143], v[172:175], v[40:43]
	v_mfma_f32_16x16x32_bf16 v[24:27], v[136:139], v[176:179], v[24:27]
	v_mfma_f32_16x16x32_bf16 v[24:27], v[140:143], v[180:183], v[24:27]
	v_mfma_f32_16x16x32_bf16 v[8:11], v[136:139], v[200:203], v[8:11]
	v_mfma_f32_16x16x32_bf16 v[8:11], v[140:143], v[204:207], v[8:11]
	v_mfma_f32_16x16x32_bf16 v[52:55], v[144:147], v[160:163], v[52:55]
	v_mfma_f32_16x16x32_bf16 v[52:55], v[148:151], v[164:167], v[52:55]
	v_mfma_f32_16x16x32_bf16 v[36:39], v[144:147], v[168:171], v[36:39]
	v_mfma_f32_16x16x32_bf16 v[36:39], v[148:151], v[172:175], v[36:39]
	v_mfma_f32_16x16x32_bf16 v[20:23], v[144:147], v[176:179], v[20:23]
	v_mfma_f32_16x16x32_bf16 v[20:23], v[148:151], v[180:183], v[20:23]
	v_mfma_f32_16x16x32_bf16 v[4:7], v[144:147], v[200:203], v[4:7]
	v_mfma_f32_16x16x32_bf16 v[4:7], v[148:151], v[204:207], v[4:7]
	v_mfma_f32_16x16x32_bf16 v[48:51], v[152:155], v[160:163], v[48:51]
	v_mfma_f32_16x16x32_bf16 v[48:51], v[156:159], v[164:167], v[48:51]
	v_mfma_f32_16x16x32_bf16 v[32:35], v[152:155], v[168:171], v[32:35]
	v_mfma_f32_16x16x32_bf16 v[32:35], v[156:159], v[172:175], v[32:35]
	s_setprio 2
	s_barrier
	v_mfma_f32_16x16x32_bf16 v[16:19], v[152:155], v[176:179], v[16:19]
	v_mfma_f32_16x16x32_bf16 v[16:19], v[156:159], v[180:183], v[16:19]
	v_mfma_f32_16x16x32_bf16 v[0:3], v[152:155], v[200:203], v[0:3]
	v_mfma_f32_16x16x32_bf16 v[0:3], v[156:159], v[204:207], v[0:3]
	s_setprio 0
	s_add_i32 s64, s64, 2
	s_add_u32 s62, s62, 0x100
	s_addc_u32 s63, s63, 0
	s_cmp_gt_u32 s64, 41
	s_mov_b64 s[26:27], s[28:29]
	s_cbranch_scc0 .LBB0_866

.LBB0_951:
	s_ashr_i32 s27, s26, 31
	s_lshl_b64 s[30:31], s[26:27], 19
	s_add_u32 s30, s47, s30
	s_addc_u32 s31, s48, s31
	s_and_b64 s[36:37], s[4:5], exec
	s_cselect_b32 s27, s31, s7
	s_cselect_b32 s39, s30, s6
	s_ashr_i32 s29, s28, 31
	s_lshl_b64 s[36:37], s[28:29], 19
	s_add_u32 s36, s49, s36
	s_addc_u32 s37, s50, s37
	s_and_b64 s[44:45], s[4:5], exec
	s_cselect_b32 s29, s37, s41
	s_cselect_b32 s43, s36, s40
	s_add_u32 s6, s6, 0x40080
	s_addc_u32 s7, s7, 0
	s_add_u32 s71, s40, 0x100
	s_addc_u32 s72, s41, 0
	s_mov_b32 s73, -2
	ds_read_b128 v[144:147], v179
	ds_read_b128 v[148:151], v179 offset:1024
	ds_read_b128 v[152:155], v179 offset:2048
	ds_read_b128 v[156:159], v179 offset:3072
	ds_read_b128 v[160:163], v180
	ds_read_b128 v[164:167], v180 offset:1024
	ds_read_b128 v[168:171], v180 offset:2048
	ds_read_b128 v[172:175], v180 offset:3072
	s_add_u32 s40, s6, 0xfffc0080
	s_addc_u32 s41, s7, -1
	s_cmp_eq_u32 s73, 12
	s_cselect_b32 s45, s27, s41
	s_cselect_b32 s44, s39, s40
	s_cselect_b32 s41, s29, s72
	s_cselect_b32 s40, s43, s71
	v_lshl_add_u64 v[176:177], s[6:7], 0, v[136:137]
	s_add_i32 m0, s54, 0xc000
	ds_read_b128 v[184:187], v181
	ds_read_b128 v[188:191], v181 offset:1024
	ds_read_b128 v[192:195], v181 offset:2048
	ds_read_b128 v[196:199], v181 offset:3072
	ds_read_b128 v[200:203], v181 offset:4096
	ds_read_b128 v[204:207], v181 offset:5120
	ds_read_b128 v[208:211], v181 offset:6144
	ds_read_b128 v[212:215], v181 offset:7168
	global_load_lds_dwordx4 v[176:177], off
	s_add_i32 m0, s54, 0xe000
	v_lshl_add_u64 v[176:177], s[6:7], 0, v[138:139]
	global_load_lds_dwordx4 v[176:177], off
	s_waitcnt vmcnt(8) lgkmcnt(0)
	s_barrier
	s_setprio 1
	v_mfma_f32_16x16x32_bf16 v[124:127], v[144:147], v[184:187], 0
	v_mfma_f32_16x16x32_bf16 v[124:127], v[148:151], v[188:191], v[124:127]
	v_mfma_f32_16x16x32_bf16 v[108:111], v[144:147], v[192:195], 0
	v_mfma_f32_16x16x32_bf16 v[108:111], v[148:151], v[196:199], v[108:111]
	v_mfma_f32_16x16x32_bf16 v[92:95], v[144:147], v[200:203], 0
	v_mfma_f32_16x16x32_bf16 v[92:95], v[148:151], v[204:207], v[92:95]
	v_mfma_f32_16x16x32_bf16 v[76:79], v[144:147], v[208:211], 0
	v_mfma_f32_16x16x32_bf16 v[76:79], v[148:151], v[212:215], v[76:79]
	v_mfma_f32_16x16x32_bf16 v[120:123], v[152:155], v[184:187], 0
	v_mfma_f32_16x16x32_bf16 v[120:123], v[156:159], v[188:191], v[120:123]
	v_mfma_f32_16x16x32_bf16 v[104:107], v[152:155], v[192:195], 0
	v_mfma_f32_16x16x32_bf16 v[104:107], v[156:159], v[196:199], v[104:107]
	v_mfma_f32_16x16x32_bf16 v[88:91], v[152:155], v[200:203], 0
	v_mfma_f32_16x16x32_bf16 v[88:91], v[156:159], v[204:207], v[88:91]
	v_mfma_f32_16x16x32_bf16 v[72:75], v[152:155], v[208:211], 0
	v_mfma_f32_16x16x32_bf16 v[72:75], v[156:159], v[212:215], v[72:75]
	v_mfma_f32_16x16x32_bf16 v[116:119], v[160:163], v[184:187], 0
	v_mfma_f32_16x16x32_bf16 v[116:119], v[164:167], v[188:191], v[116:119]
	v_mfma_f32_16x16x32_bf16 v[100:103], v[160:163], v[192:195], 0
	v_mfma_f32_16x16x32_bf16 v[100:103], v[164:167], v[196:199], v[100:103]
	v_mfma_f32_16x16x32_bf16 v[84:87], v[160:163], v[200:203], 0
	v_mfma_f32_16x16x32_bf16 v[84:87], v[164:167], v[204:207], v[84:87]
	v_mfma_f32_16x16x32_bf16 v[68:71], v[160:163], v[208:211], 0
	v_mfma_f32_16x16x32_bf16 v[68:71], v[164:167], v[212:215], v[68:71]
	v_mfma_f32_16x16x32_bf16 v[112:115], v[168:171], v[184:187], 0
	v_mfma_f32_16x16x32_bf16 v[112:115], v[172:175], v[188:191], v[112:115]
	v_mfma_f32_16x16x32_bf16 v[96:99], v[168:171], v[192:195], 0
	v_mfma_f32_16x16x32_bf16 v[96:99], v[172:175], v[196:199], v[96:99]
	s_setprio 2
	s_barrier
	v_mfma_f32_16x16x32_bf16 v[80:83], v[168:171], v[200:203], 0
	v_mfma_f32_16x16x32_bf16 v[80:83], v[172:175], v[204:207], v[80:83]
	v_mfma_f32_16x16x32_bf16 v[64:67], v[168:171], v[208:211], 0
	v_mfma_f32_16x16x32_bf16 v[64:67], v[172:175], v[212:215], v[64:67]
	s_setprio 2
	s_add_i32 s74, s69, s51
	v_lshl_add_u64 v[176:177], s[40:41], 0, v[130:131]
	s_mov_b32 m0, s74
	ds_read_b128 v[184:187], v181 offset:16384
	ds_read_b128 v[188:191], v181 offset:17408
	ds_read_b128 v[192:195], v181 offset:18432
	ds_read_b128 v[196:199], v181 offset:19456
	ds_read_b128 v[200:203], v181 offset:20480
	ds_read_b128 v[204:207], v181 offset:21504
	ds_read_b128 v[208:211], v181 offset:22528
	ds_read_b128 v[212:215], v181 offset:23552
	global_load_lds_dwordx4 v[176:177], off
	s_add_i32 m0, s74, 0x2000
	s_add_u32 s74, s40, 0x40000
	v_lshl_add_u64 v[216:217], s[40:41], 0, v[134:135]
	s_addc_u32 s75, s41, 0
	s_add_i32 s76, s70, s51
	global_load_lds_dwordx4 v[216:217], off
	v_lshl_add_u64 v[218:219], s[74:75], 0, v[130:131]
	s_mov_b32 m0, s76
	v_lshl_add_u64 v[220:221], s[44:45], 0, v[132:133]
	global_load_lds_dwordx4 v[218:219], off
	s_add_i32 m0, s76, 0x2000
	v_lshl_add_u64 v[218:219], s[74:75], 0, v[134:135]
	global_load_lds_dwordx4 v[218:219], off
	s_mov_b32 m0, s54
	v_lshl_add_u64 v[218:219], s[44:45], 0, v[128:129]
	global_load_lds_dwordx4 v[218:219], off
	s_mov_b32 m0, s55
	s_nop 0
	global_load_lds_dwordx4 v[220:221], off
	s_waitcnt vmcnt(8) lgkmcnt(0)
	s_barrier
	s_setprio 1
	v_mfma_f32_16x16x32_bf16 v[60:63], v[144:147], v[184:187], 0
	v_mfma_f32_16x16x32_bf16 v[60:63], v[148:151], v[188:191], v[60:63]
	v_mfma_f32_16x16x32_bf16 v[44:47], v[144:147], v[192:195], 0
	v_mfma_f32_16x16x32_bf16 v[44:47], v[148:151], v[196:199], v[44:47]
	v_mfma_f32_16x16x32_bf16 v[28:31], v[144:147], v[200:203], 0
	v_mfma_f32_16x16x32_bf16 v[28:31], v[148:151], v[204:207], v[28:31]
	v_mfma_f32_16x16x32_bf16 v[12:15], v[144:147], v[208:211], 0
	v_mfma_f32_16x16x32_bf16 v[12:15], v[148:151], v[212:215], v[12:15]
	v_mfma_f32_16x16x32_bf16 v[56:59], v[152:155], v[184:187], 0
	v_mfma_f32_16x16x32_bf16 v[56:59], v[156:159], v[188:191], v[56:59]
	v_mfma_f32_16x16x32_bf16 v[40:43], v[152:155], v[192:195], 0
	v_mfma_f32_16x16x32_bf16 v[40:43], v[156:159], v[196:199], v[40:43]
	v_mfma_f32_16x16x32_bf16 v[24:27], v[152:155], v[200:203], 0
	v_mfma_f32_16x16x32_bf16 v[24:27], v[156:159], v[204:207], v[24:27]
	v_mfma_f32_16x16x32_bf16 v[8:11], v[152:155], v[208:211], 0
	v_mfma_f32_16x16x32_bf16 v[8:11], v[156:159], v[212:215], v[8:11]
	v_mfma_f32_16x16x32_bf16 v[52:55], v[160:163], v[184:187], 0
	v_mfma_f32_16x16x32_bf16 v[52:55], v[164:167], v[188:191], v[52:55]
	v_mfma_f32_16x16x32_bf16 v[36:39], v[160:163], v[192:195], 0
	v_mfma_f32_16x16x32_bf16 v[36:39], v[164:167], v[196:199], v[36:39]
	v_mfma_f32_16x16x32_bf16 v[20:23], v[160:163], v[200:203], 0
	v_mfma_f32_16x16x32_bf16 v[20:23], v[164:167], v[204:207], v[20:23]
	v_mfma_f32_16x16x32_bf16 v[4:7], v[160:163], v[208:211], 0
	v_mfma_f32_16x16x32_bf16 v[4:7], v[164:167], v[212:215], v[4:7]
	v_mfma_f32_16x16x32_bf16 v[48:51], v[168:171], v[184:187], 0
	v_mfma_f32_16x16x32_bf16 v[48:51], v[172:175], v[188:191], v[48:51]
	v_mfma_f32_16x16x32_bf16 v[32:35], v[168:171], v[192:195], 0
	v_mfma_f32_16x16x32_bf16 v[32:35], v[172:175], v[196:199], v[32:35]
	s_setprio 2
	s_barrier
	v_mfma_f32_16x16x32_bf16 v[16:19], v[168:171], v[200:203], 0
	v_mfma_f32_16x16x32_bf16 v[16:19], v[172:175], v[204:207], v[16:19]
	v_mfma_f32_16x16x32_bf16 v[0:3], v[168:171], v[208:211], 0
	v_mfma_f32_16x16x32_bf16 v[0:3], v[172:175], v[212:215], v[0:3]
	s_setprio 0
	s_add_i32 s74, 0, 0x18000
	s_add_i32 s75, 0, 0x1c000
	v_add_u32_e32 v156, s74, v178
	v_add_u32_e32 v172, s75, v178
	ds_read_b128 v[144:147], v156
	ds_read_b128 v[148:151], v156 offset:1024
	ds_read_b128 v[152:155], v156 offset:2048
	ds_read_b128 v[156:159], v156 offset:3072
	ds_read_b128 v[160:163], v172
	ds_read_b128 v[164:167], v172 offset:1024
	ds_read_b128 v[168:171], v172 offset:2048
	ds_read_b128 v[172:175], v172 offset:3072
	s_add_u32 s44, s44, 0x40000
	s_addc_u32 s45, s45, 0
	s_mov_b32 m0, s56
	v_lshl_add_u64 v[222:223], s[44:45], 0, v[128:129]
	ds_read_b128 v[184:187], v181 offset:32768
	ds_read_b128 v[188:191], v181 offset:33792
	ds_read_b128 v[192:195], v181 offset:34816
	ds_read_b128 v[196:199], v181 offset:35840
	ds_read_b128 v[200:203], v181 offset:36864
	ds_read_b128 v[204:207], v181 offset:37888
	ds_read_b128 v[208:211], v181 offset:38912
	ds_read_b128 v[212:215], v181 offset:39936
	global_load_lds_dwordx4 v[222:223], off
	s_mov_b32 m0, s57
	v_lshl_add_u64 v[222:223], s[44:45], 0, v[132:133]
	global_load_lds_dwordx4 v[222:223], off
	s_waitcnt vmcnt(8) lgkmcnt(0)
	s_barrier
	s_setprio 1
	v_mfma_f32_16x16x32_bf16 v[124:127], v[144:147], v[184:187], v[124:127]
	v_mfma_f32_16x16x32_bf16 v[124:127], v[148:151], v[188:191], v[124:127]
	v_mfma_f32_16x16x32_bf16 v[108:111], v[144:147], v[192:195], v[108:111]
	v_mfma_f32_16x16x32_bf16 v[108:111], v[148:151], v[196:199], v[108:111]
	v_mfma_f32_16x16x32_bf16 v[92:95], v[144:147], v[200:203], v[92:95]
	v_mfma_f32_16x16x32_bf16 v[92:95], v[148:151], v[204:207], v[92:95]
	v_mfma_f32_16x16x32_bf16 v[76:79], v[144:147], v[208:211], v[76:79]
	v_mfma_f32_16x16x32_bf16 v[76:79], v[148:151], v[212:215], v[76:79]
	v_mfma_f32_16x16x32_bf16 v[120:123], v[152:155], v[184:187], v[120:123]
	v_mfma_f32_16x16x32_bf16 v[120:123], v[156:159], v[188:191], v[120:123]
	v_mfma_f32_16x16x32_bf16 v[104:107], v[152:155], v[192:195], v[104:107]
	v_mfma_f32_16x16x32_bf16 v[104:107], v[156:159], v[196:199], v[104:107]
	v_mfma_f32_16x16x32_bf16 v[88:91], v[152:155], v[200:203], v[88:91]
	v_mfma_f32_16x16x32_bf16 v[88:91], v[156:159], v[204:207], v[88:91]
	v_mfma_f32_16x16x32_bf16 v[72:75], v[152:155], v[208:211], v[72:75]
	v_mfma_f32_16x16x32_bf16 v[72:75], v[156:159], v[212:215], v[72:75]
	v_mfma_f32_16x16x32_bf16 v[116:119], v[160:163], v[184:187], v[116:119]
	v_mfma_f32_16x16x32_bf16 v[116:119], v[164:167], v[188:191], v[116:119]
	v_mfma_f32_16x16x32_bf16 v[100:103], v[160:163], v[192:195], v[100:103]
	v_mfma_f32_16x16x32_bf16 v[100:103], v[164:167], v[196:199], v[100:103]
	v_mfma_f32_16x16x32_bf16 v[84:87], v[160:163], v[200:203], v[84:87]
	v_mfma_f32_16x16x32_bf16 v[84:87], v[164:167], v[204:207], v[84:87]
	v_mfma_f32_16x16x32_bf16 v[68:71], v[160:163], v[208:211], v[68:71]
	v_mfma_f32_16x16x32_bf16 v[68:71], v[164:167], v[212:215], v[68:71]
	v_mfma_f32_16x16x32_bf16 v[112:115], v[168:171], v[184:187], v[112:115]
	v_mfma_f32_16x16x32_bf16 v[112:115], v[172:175], v[188:191], v[112:115]
	v_mfma_f32_16x16x32_bf16 v[96:99], v[168:171], v[192:195], v[96:99]
	v_mfma_f32_16x16x32_bf16 v[96:99], v[172:175], v[196:199], v[96:99]
	s_setprio 2
	s_barrier
	v_mfma_f32_16x16x32_bf16 v[80:83], v[168:171], v[200:203], v[80:83]
	v_mfma_f32_16x16x32_bf16 v[80:83], v[172:175], v[204:207], v[80:83]
	v_mfma_f32_16x16x32_bf16 v[64:67], v[168:171], v[208:211], v[64:67]
	v_mfma_f32_16x16x32_bf16 v[64:67], v[172:175], v[212:215], v[64:67]
	s_setprio 2
	s_add_i32 s44, s74, s51
	v_lshl_add_u64 v[176:177], v[176:177], 0, s[22:23]
	s_mov_b32 m0, s44
	ds_read_b128 v[184:187], v181 offset:49152
	ds_read_b128 v[188:191], v181 offset:50176
	ds_read_b128 v[192:195], v181 offset:51200
	ds_read_b128 v[196:199], v181 offset:52224
	ds_read_b128 v[200:203], v181 offset:53248
	ds_read_b128 v[204:207], v181 offset:54272
	ds_read_b128 v[208:211], v181 offset:55296
	ds_read_b128 v[212:215], v181 offset:56320
	global_load_lds_dwordx4 v[176:177], off
	s_add_i32 m0, s44, 0x2000
	s_add_u32 s40, s40, 0x40080
	v_lshl_add_u64 v[176:177], v[216:217], 0, s[22:23]
	s_addc_u32 s41, s41, 0
	s_add_i32 s44, s75, s51
	global_load_lds_dwordx4 v[176:177], off
	s_mov_b32 m0, s44
	v_lshl_add_u64 v[176:177], s[40:41], 0, v[130:131]
	global_load_lds_dwordx4 v[176:177], off
	s_add_i32 m0, s44, 0x2000
	v_lshl_add_u64 v[176:177], s[40:41], 0, v[134:135]
	global_load_lds_dwordx4 v[176:177], off
	s_mov_b32 m0, s64
	v_lshl_add_u64 v[176:177], v[218:219], 0, s[22:23]
	global_load_lds_dwordx4 v[176:177], off
	s_mov_b32 m0, s65
	v_lshl_add_u64 v[176:177], v[220:221], 0, s[22:23]
	global_load_lds_dwordx4 v[176:177], off
	s_waitcnt vmcnt(8) lgkmcnt(0)
	s_barrier
	s_setprio 1
	v_mfma_f32_16x16x32_bf16 v[60:63], v[144:147], v[184:187], v[60:63]
	v_mfma_f32_16x16x32_bf16 v[60:63], v[148:151], v[188:191], v[60:63]
	v_mfma_f32_16x16x32_bf16 v[44:47], v[144:147], v[192:195], v[44:47]
	v_mfma_f32_16x16x32_bf16 v[44:47], v[148:151], v[196:199], v[44:47]
	v_mfma_f32_16x16x32_bf16 v[28:31], v[144:147], v[200:203], v[28:31]
	v_mfma_f32_16x16x32_bf16 v[28:31], v[148:151], v[204:207], v[28:31]
	v_mfma_f32_16x16x32_bf16 v[12:15], v[144:147], v[208:211], v[12:15]
	v_mfma_f32_16x16x32_bf16 v[12:15], v[148:151], v[212:215], v[12:15]
	v_mfma_f32_16x16x32_bf16 v[56:59], v[152:155], v[184:187], v[56:59]
	v_mfma_f32_16x16x32_bf16 v[56:59], v[156:159], v[188:191], v[56:59]
	v_mfma_f32_16x16x32_bf16 v[40:43], v[152:155], v[192:195], v[40:43]
	v_mfma_f32_16x16x32_bf16 v[40:43], v[156:159], v[196:199], v[40:43]
	v_mfma_f32_16x16x32_bf16 v[24:27], v[152:155], v[200:203], v[24:27]
	v_mfma_f32_16x16x32_bf16 v[24:27], v[156:159], v[204:207], v[24:27]
	v_mfma_f32_16x16x32_bf16 v[8:11], v[152:155], v[208:211], v[8:11]
	v_mfma_f32_16x16x32_bf16 v[8:11], v[156:159], v[212:215], v[8:11]
	v_mfma_f32_16x16x32_bf16 v[52:55], v[160:163], v[184:187], v[52:55]
	v_mfma_f32_16x16x32_bf16 v[52:55], v[164:167], v[188:191], v[52:55]
	v_mfma_f32_16x16x32_bf16 v[36:39], v[160:163], v[192:195], v[36:39]
	v_mfma_f32_16x16x32_bf16 v[36:39], v[164:167], v[196:199], v[36:39]
	v_mfma_f32_16x16x32_bf16 v[20:23], v[160:163], v[200:203], v[20:23]
	v_mfma_f32_16x16x32_bf16 v[20:23], v[164:167], v[204:207], v[20:23]
	v_mfma_f32_16x16x32_bf16 v[4:7], v[160:163], v[208:211], v[4:7]
	v_mfma_f32_16x16x32_bf16 v[4:7], v[164:167], v[212:215], v[4:7]
	v_mfma_f32_16x16x32_bf16 v[48:51], v[168:171], v[184:187], v[48:51]
	v_mfma_f32_16x16x32_bf16 v[48:51], v[172:175], v[188:191], v[48:51]
	v_mfma_f32_16x16x32_bf16 v[32:35], v[168:171], v[192:195], v[32:35]
	v_mfma_f32_16x16x32_bf16 v[32:35], v[172:175], v[196:199], v[32:35]
	s_setprio 2
	s_barrier
	v_mfma_f32_16x16x32_bf16 v[16:19], v[168:171], v[200:203], v[16:19]
	v_mfma_f32_16x16x32_bf16 v[16:19], v[172:175], v[204:207], v[16:19]
	v_mfma_f32_16x16x32_bf16 v[0:3], v[168:171], v[208:211], v[0:3]
	v_mfma_f32_16x16x32_bf16 v[0:3], v[172:175], v[212:215], v[0:3]
	s_setprio 0
	s_add_i32 s73, s73, 2
	s_add_u32 s6, s6, 0x100
	s_addc_u32 s7, s7, 0
	s_add_u32 s71, s71, 0x100
	s_addc_u32 s72, s72, 0
	s_cmp_gt_u32 s73, 13
.LBB0_952:
	ds_read_b128 v[144:147], v179
	ds_read_b128 v[148:151], v179 offset:1024
	ds_read_b128 v[152:155], v179 offset:2048
	ds_read_b128 v[156:159], v179 offset:3072
	ds_read_b128 v[160:163], v180
	ds_read_b128 v[164:167], v180 offset:1024
	ds_read_b128 v[168:171], v180 offset:2048
	ds_read_b128 v[172:175], v180 offset:3072
	s_add_u32 s40, s6, 0xfffc0080
	s_addc_u32 s41, s7, -1
	s_cmp_eq_u32 s73, 12
	s_cselect_b32 s45, s27, s41
	s_cselect_b32 s44, s39, s40
	s_cselect_b32 s41, s29, s72
	s_cselect_b32 s40, s43, s71
	v_lshl_add_u64 v[176:177], s[6:7], 0, v[136:137]
	s_add_i32 m0, s54, 0xc000
	ds_read_b128 v[184:187], v181
	ds_read_b128 v[188:191], v181 offset:1024
	ds_read_b128 v[192:195], v181 offset:2048
	ds_read_b128 v[196:199], v181 offset:3072
	ds_read_b128 v[200:203], v181 offset:4096
	ds_read_b128 v[204:207], v181 offset:5120
	ds_read_b128 v[208:211], v181 offset:6144
	ds_read_b128 v[212:215], v181 offset:7168
	global_load_lds_dwordx4 v[176:177], off
	s_add_i32 m0, s54, 0xe000
	v_lshl_add_u64 v[176:177], s[6:7], 0, v[138:139]
	global_load_lds_dwordx4 v[176:177], off
	s_waitcnt vmcnt(8) lgkmcnt(0)
	s_barrier
	s_setprio 1
	v_mfma_f32_16x16x32_bf16 v[124:127], v[144:147], v[184:187], v[124:127]
	v_mfma_f32_16x16x32_bf16 v[124:127], v[148:151], v[188:191], v[124:127]
	v_mfma_f32_16x16x32_bf16 v[108:111], v[144:147], v[192:195], v[108:111]
	v_mfma_f32_16x16x32_bf16 v[108:111], v[148:151], v[196:199], v[108:111]
	v_mfma_f32_16x16x32_bf16 v[92:95], v[144:147], v[200:203], v[92:95]
	v_mfma_f32_16x16x32_bf16 v[92:95], v[148:151], v[204:207], v[92:95]
	v_mfma_f32_16x16x32_bf16 v[76:79], v[144:147], v[208:211], v[76:79]
	v_mfma_f32_16x16x32_bf16 v[76:79], v[148:151], v[212:215], v[76:79]
	v_mfma_f32_16x16x32_bf16 v[120:123], v[152:155], v[184:187], v[120:123]
	v_mfma_f32_16x16x32_bf16 v[120:123], v[156:159], v[188:191], v[120:123]
	v_mfma_f32_16x16x32_bf16 v[104:107], v[152:155], v[192:195], v[104:107]
	v_mfma_f32_16x16x32_bf16 v[104:107], v[156:159], v[196:199], v[104:107]
	v_mfma_f32_16x16x32_bf16 v[88:91], v[152:155], v[200:203], v[88:91]
	v_mfma_f32_16x16x32_bf16 v[88:91], v[156:159], v[204:207], v[88:91]
	v_mfma_f32_16x16x32_bf16 v[72:75], v[152:155], v[208:211], v[72:75]
	v_mfma_f32_16x16x32_bf16 v[72:75], v[156:159], v[212:215], v[72:75]
	v_mfma_f32_16x16x32_bf16 v[116:119], v[160:163], v[184:187], v[116:119]
	v_mfma_f32_16x16x32_bf16 v[116:119], v[164:167], v[188:191], v[116:119]
	v_mfma_f32_16x16x32_bf16 v[100:103], v[160:163], v[192:195], v[100:103]
	v_mfma_f32_16x16x32_bf16 v[100:103], v[164:167], v[196:199], v[100:103]
	v_mfma_f32_16x16x32_bf16 v[84:87], v[160:163], v[200:203], v[84:87]
	v_mfma_f32_16x16x32_bf16 v[84:87], v[164:167], v[204:207], v[84:87]
	v_mfma_f32_16x16x32_bf16 v[68:71], v[160:163], v[208:211], v[68:71]
	v_mfma_f32_16x16x32_bf16 v[68:71], v[164:167], v[212:215], v[68:71]
	v_mfma_f32_16x16x32_bf16 v[112:115], v[168:171], v[184:187], v[112:115]
	v_mfma_f32_16x16x32_bf16 v[112:115], v[172:175], v[188:191], v[112:115]
	v_mfma_f32_16x16x32_bf16 v[96:99], v[168:171], v[192:195], v[96:99]
	v_mfma_f32_16x16x32_bf16 v[96:99], v[172:175], v[196:199], v[96:99]
	s_setprio 2
	s_barrier
	v_mfma_f32_16x16x32_bf16 v[80:83], v[168:171], v[200:203], v[80:83]
	v_mfma_f32_16x16x32_bf16 v[80:83], v[172:175], v[204:207], v[80:83]
	v_mfma_f32_16x16x32_bf16 v[64:67], v[168:171], v[208:211], v[64:67]
	v_mfma_f32_16x16x32_bf16 v[64:67], v[172:175], v[212:215], v[64:67]
	s_setprio 2
	s_add_i32 s74, s69, s51
	v_lshl_add_u64 v[176:177], s[40:41], 0, v[130:131]
	s_mov_b32 m0, s74
	ds_read_b128 v[184:187], v181 offset:16384
	ds_read_b128 v[188:191], v181 offset:17408
	ds_read_b128 v[192:195], v181 offset:18432
	ds_read_b128 v[196:199], v181 offset:19456
	ds_read_b128 v[200:203], v181 offset:20480
	ds_read_b128 v[204:207], v181 offset:21504
	ds_read_b128 v[208:211], v181 offset:22528
	ds_read_b128 v[212:215], v181 offset:23552
	global_load_lds_dwordx4 v[176:177], off
	s_add_i32 m0, s74, 0x2000
	s_add_u32 s74, s40, 0x40000
	v_lshl_add_u64 v[216:217], s[40:41], 0, v[134:135]
	s_addc_u32 s75, s41, 0
	s_add_i32 s76, s70, s51
	global_load_lds_dwordx4 v[216:217], off
	v_lshl_add_u64 v[218:219], s[74:75], 0, v[130:131]
	s_mov_b32 m0, s76
	v_lshl_add_u64 v[220:221], s[44:45], 0, v[132:133]
	global_load_lds_dwordx4 v[218:219], off
	s_add_i32 m0, s76, 0x2000
	v_lshl_add_u64 v[218:219], s[74:75], 0, v[134:135]
	global_load_lds_dwordx4 v[218:219], off
	s_mov_b32 m0, s54
	v_lshl_add_u64 v[218:219], s[44:45], 0, v[128:129]
	global_load_lds_dwordx4 v[218:219], off
	s_mov_b32 m0, s55
	s_nop 0
	global_load_lds_dwordx4 v[220:221], off
	s_waitcnt vmcnt(8) lgkmcnt(0)
	s_barrier
	s_setprio 1
	v_mfma_f32_16x16x32_bf16 v[60:63], v[144:147], v[184:187], v[60:63]
	v_mfma_f32_16x16x32_bf16 v[60:63], v[148:151], v[188:191], v[60:63]
	v_mfma_f32_16x16x32_bf16 v[44:47], v[144:147], v[192:195], v[44:47]
	v_mfma_f32_16x16x32_bf16 v[44:47], v[148:151], v[196:199], v[44:47]
	v_mfma_f32_16x16x32_bf16 v[28:31], v[144:147], v[200:203], v[28:31]
	v_mfma_f32_16x16x32_bf16 v[28:31], v[148:151], v[204:207], v[28:31]
	v_mfma_f32_16x16x32_bf16 v[12:15], v[144:147], v[208:211], v[12:15]
	v_mfma_f32_16x16x32_bf16 v[12:15], v[148:151], v[212:215], v[12:15]
	v_mfma_f32_16x16x32_bf16 v[56:59], v[152:155], v[184:187], v[56:59]
	v_mfma_f32_16x16x32_bf16 v[56:59], v[156:159], v[188:191], v[56:59]
	v_mfma_f32_16x16x32_bf16 v[40:43], v[152:155], v[192:195], v[40:43]
	v_mfma_f32_16x16x32_bf16 v[40:43], v[156:159], v[196:199], v[40:43]
	v_mfma_f32_16x16x32_bf16 v[24:27], v[152:155], v[200:203], v[24:27]
	v_mfma_f32_16x16x32_bf16 v[24:27], v[156:159], v[204:207], v[24:27]
	v_mfma_f32_16x16x32_bf16 v[8:11], v[152:155], v[208:211], v[8:11]
	v_mfma_f32_16x16x32_bf16 v[8:11], v[156:159], v[212:215], v[8:11]
	v_mfma_f32_16x16x32_bf16 v[52:55], v[160:163], v[184:187], v[52:55]
	v_mfma_f32_16x16x32_bf16 v[52:55], v[164:167], v[188:191], v[52:55]
	v_mfma_f32_16x16x32_bf16 v[36:39], v[160:163], v[192:195], v[36:39]
	v_mfma_f32_16x16x32_bf16 v[36:39], v[164:167], v[196:199], v[36:39]
	v_mfma_f32_16x16x32_bf16 v[20:23], v[160:163], v[200:203], v[20:23]
	v_mfma_f32_16x16x32_bf16 v[20:23], v[164:167], v[204:207], v[20:23]
	v_mfma_f32_16x16x32_bf16 v[4:7], v[160:163], v[208:211], v[4:7]
	v_mfma_f32_16x16x32_bf16 v[4:7], v[164:167], v[212:215], v[4:7]
	v_mfma_f32_16x16x32_bf16 v[48:51], v[168:171], v[184:187], v[48:51]
	v_mfma_f32_16x16x32_bf16 v[48:51], v[172:175], v[188:191], v[48:51]
	v_mfma_f32_16x16x32_bf16 v[32:35], v[168:171], v[192:195], v[32:35]
	v_mfma_f32_16x16x32_bf16 v[32:35], v[172:175], v[196:199], v[32:35]
	s_setprio 2
	s_barrier
	v_mfma_f32_16x16x32_bf16 v[16:19], v[168:171], v[200:203], v[16:19]
	v_mfma_f32_16x16x32_bf16 v[16:19], v[172:175], v[204:207], v[16:19]
	v_mfma_f32_16x16x32_bf16 v[0:3], v[168:171], v[208:211], v[0:3]
	v_mfma_f32_16x16x32_bf16 v[0:3], v[172:175], v[212:215], v[0:3]
	s_setprio 0
	s_add_i32 s74, 0, 0x18000
	s_add_i32 s75, 0, 0x1c000
	v_add_u32_e32 v156, s74, v178
	v_add_u32_e32 v172, s75, v178
	ds_read_b128 v[144:147], v156
	ds_read_b128 v[148:151], v156 offset:1024
	ds_read_b128 v[152:155], v156 offset:2048
	ds_read_b128 v[156:159], v156 offset:3072
	ds_read_b128 v[160:163], v172
	ds_read_b128 v[164:167], v172 offset:1024
	ds_read_b128 v[168:171], v172 offset:2048
	ds_read_b128 v[172:175], v172 offset:3072
	s_add_u32 s44, s44, 0x40000
	s_addc_u32 s45, s45, 0
	s_mov_b32 m0, s56
	v_lshl_add_u64 v[222:223], s[44:45], 0, v[128:129]
	ds_read_b128 v[184:187], v181 offset:32768
	ds_read_b128 v[188:191], v181 offset:33792
	ds_read_b128 v[192:195], v181 offset:34816
	ds_read_b128 v[196:199], v181 offset:35840
	ds_read_b128 v[200:203], v181 offset:36864
	ds_read_b128 v[204:207], v181 offset:37888
	ds_read_b128 v[208:211], v181 offset:38912
	ds_read_b128 v[212:215], v181 offset:39936
	global_load_lds_dwordx4 v[222:223], off
	s_mov_b32 m0, s57
	v_lshl_add_u64 v[222:223], s[44:45], 0, v[132:133]
	global_load_lds_dwordx4 v[222:223], off
	s_waitcnt vmcnt(8) lgkmcnt(0)
	s_barrier
	s_setprio 1
	v_mfma_f32_16x16x32_bf16 v[124:127], v[144:147], v[184:187], v[124:127]
	v_mfma_f32_16x16x32_bf16 v[124:127], v[148:151], v[188:191], v[124:127]
	v_mfma_f32_16x16x32_bf16 v[108:111], v[144:147], v[192:195], v[108:111]
	v_mfma_f32_16x16x32_bf16 v[108:111], v[148:151], v[196:199], v[108:111]
	v_mfma_f32_16x16x32_bf16 v[92:95], v[144:147], v[200:203], v[92:95]
	v_mfma_f32_16x16x32_bf16 v[92:95], v[148:151], v[204:207], v[92:95]
	v_mfma_f32_16x16x32_bf16 v[76:79], v[144:147], v[208:211], v[76:79]
	v_mfma_f32_16x16x32_bf16 v[76:79], v[148:151], v[212:215], v[76:79]
	v_mfma_f32_16x16x32_bf16 v[120:123], v[152:155], v[184:187], v[120:123]
	v_mfma_f32_16x16x32_bf16 v[120:123], v[156:159], v[188:191], v[120:123]
	v_mfma_f32_16x16x32_bf16 v[104:107], v[152:155], v[192:195], v[104:107]
	v_mfma_f32_16x16x32_bf16 v[104:107], v[156:159], v[196:199], v[104:107]
	v_mfma_f32_16x16x32_bf16 v[88:91], v[152:155], v[200:203], v[88:91]
	v_mfma_f32_16x16x32_bf16 v[88:91], v[156:159], v[204:207], v[88:91]
	v_mfma_f32_16x16x32_bf16 v[72:75], v[152:155], v[208:211], v[72:75]
	v_mfma_f32_16x16x32_bf16 v[72:75], v[156:159], v[212:215], v[72:75]
	v_mfma_f32_16x16x32_bf16 v[116:119], v[160:163], v[184:187], v[116:119]
	v_mfma_f32_16x16x32_bf16 v[116:119], v[164:167], v[188:191], v[116:119]
	v_mfma_f32_16x16x32_bf16 v[100:103], v[160:163], v[192:195], v[100:103]
	v_mfma_f32_16x16x32_bf16 v[100:103], v[164:167], v[196:199], v[100:103]
	v_mfma_f32_16x16x32_bf16 v[84:87], v[160:163], v[200:203], v[84:87]
	v_mfma_f32_16x16x32_bf16 v[84:87], v[164:167], v[204:207], v[84:87]
	v_mfma_f32_16x16x32_bf16 v[68:71], v[160:163], v[208:211], v[68:71]
	v_mfma_f32_16x16x32_bf16 v[68:71], v[164:167], v[212:215], v[68:71]
	v_mfma_f32_16x16x32_bf16 v[112:115], v[168:171], v[184:187], v[112:115]
	v_mfma_f32_16x16x32_bf16 v[112:115], v[172:175], v[188:191], v[112:115]
	v_mfma_f32_16x16x32_bf16 v[96:99], v[168:171], v[192:195], v[96:99]
	v_mfma_f32_16x16x32_bf16 v[96:99], v[172:175], v[196:199], v[96:99]
	s_setprio 2
	s_barrier
	v_mfma_f32_16x16x32_bf16 v[80:83], v[168:171], v[200:203], v[80:83]
	v_mfma_f32_16x16x32_bf16 v[80:83], v[172:175], v[204:207], v[80:83]
	v_mfma_f32_16x16x32_bf16 v[64:67], v[168:171], v[208:211], v[64:67]
	v_mfma_f32_16x16x32_bf16 v[64:67], v[172:175], v[212:215], v[64:67]
	s_setprio 2
	s_add_i32 s44, s74, s51
	v_lshl_add_u64 v[176:177], v[176:177], 0, s[22:23]
	s_mov_b32 m0, s44
	ds_read_b128 v[184:187], v181 offset:49152
	ds_read_b128 v[188:191], v181 offset:50176
	ds_read_b128 v[192:195], v181 offset:51200
	ds_read_b128 v[196:199], v181 offset:52224
	ds_read_b128 v[200:203], v181 offset:53248
	ds_read_b128 v[204:207], v181 offset:54272
	ds_read_b128 v[208:211], v181 offset:55296
	ds_read_b128 v[212:215], v181 offset:56320
	global_load_lds_dwordx4 v[176:177], off
	s_add_i32 m0, s44, 0x2000
	s_add_u32 s40, s40, 0x40080
	v_lshl_add_u64 v[176:177], v[216:217], 0, s[22:23]
	s_addc_u32 s41, s41, 0
	s_add_i32 s44, s75, s51
	global_load_lds_dwordx4 v[176:177], off
	s_mov_b32 m0, s44
	v_lshl_add_u64 v[176:177], s[40:41], 0, v[130:131]
	global_load_lds_dwordx4 v[176:177], off
	s_add_i32 m0, s44, 0x2000
	v_lshl_add_u64 v[176:177], s[40:41], 0, v[134:135]
	global_load_lds_dwordx4 v[176:177], off
	s_mov_b32 m0, s64
	v_lshl_add_u64 v[176:177], v[218:219], 0, s[22:23]
	global_load_lds_dwordx4 v[176:177], off
	s_mov_b32 m0, s65
	v_lshl_add_u64 v[176:177], v[220:221], 0, s[22:23]
	global_load_lds_dwordx4 v[176:177], off
	s_waitcnt vmcnt(8) lgkmcnt(0)
	s_barrier
	s_setprio 1
	v_mfma_f32_16x16x32_bf16 v[60:63], v[144:147], v[184:187], v[60:63]
	v_mfma_f32_16x16x32_bf16 v[60:63], v[148:151], v[188:191], v[60:63]
	v_mfma_f32_16x16x32_bf16 v[44:47], v[144:147], v[192:195], v[44:47]
	v_mfma_f32_16x16x32_bf16 v[44:47], v[148:151], v[196:199], v[44:47]
	v_mfma_f32_16x16x32_bf16 v[28:31], v[144:147], v[200:203], v[28:31]
	v_mfma_f32_16x16x32_bf16 v[28:31], v[148:151], v[204:207], v[28:31]
	v_mfma_f32_16x16x32_bf16 v[12:15], v[144:147], v[208:211], v[12:15]
	v_mfma_f32_16x16x32_bf16 v[12:15], v[148:151], v[212:215], v[12:15]
	v_mfma_f32_16x16x32_bf16 v[56:59], v[152:155], v[184:187], v[56:59]
	v_mfma_f32_16x16x32_bf16 v[56:59], v[156:159], v[188:191], v[56:59]
	v_mfma_f32_16x16x32_bf16 v[40:43], v[152:155], v[192:195], v[40:43]
	v_mfma_f32_16x16x32_bf16 v[40:43], v[156:159], v[196:199], v[40:43]
	v_mfma_f32_16x16x32_bf16 v[24:27], v[152:155], v[200:203], v[24:27]
	v_mfma_f32_16x16x32_bf16 v[24:27], v[156:159], v[204:207], v[24:27]
	v_mfma_f32_16x16x32_bf16 v[8:11], v[152:155], v[208:211], v[8:11]
	v_mfma_f32_16x16x32_bf16 v[8:11], v[156:159], v[212:215], v[8:11]
	v_mfma_f32_16x16x32_bf16 v[52:55], v[160:163], v[184:187], v[52:55]
	v_mfma_f32_16x16x32_bf16 v[52:55], v[164:167], v[188:191], v[52:55]
	v_mfma_f32_16x16x32_bf16 v[36:39], v[160:163], v[192:195], v[36:39]
	v_mfma_f32_16x16x32_bf16 v[36:39], v[164:167], v[196:199], v[36:39]
	v_mfma_f32_16x16x32_bf16 v[20:23], v[160:163], v[200:203], v[20:23]
	v_mfma_f32_16x16x32_bf16 v[20:23], v[164:167], v[204:207], v[20:23]
	v_mfma_f32_16x16x32_bf16 v[4:7], v[160:163], v[208:211], v[4:7]
	v_mfma_f32_16x16x32_bf16 v[4:7], v[164:167], v[212:215], v[4:7]
	v_mfma_f32_16x16x32_bf16 v[48:51], v[168:171], v[184:187], v[48:51]
	v_mfma_f32_16x16x32_bf16 v[48:51], v[172:175], v[188:191], v[48:51]
	v_mfma_f32_16x16x32_bf16 v[32:35], v[168:171], v[192:195], v[32:35]
	v_mfma_f32_16x16x32_bf16 v[32:35], v[172:175], v[196:199], v[32:35]
	s_setprio 2
	s_barrier
	v_mfma_f32_16x16x32_bf16 v[16:19], v[168:171], v[200:203], v[16:19]
	v_mfma_f32_16x16x32_bf16 v[16:19], v[172:175], v[204:207], v[16:19]
	v_mfma_f32_16x16x32_bf16 v[0:3], v[168:171], v[208:211], v[0:3]
	v_mfma_f32_16x16x32_bf16 v[0:3], v[172:175], v[212:215], v[0:3]
	s_setprio 0
	s_add_i32 s73, s73, 2
	s_add_u32 s6, s6, 0x100
	s_addc_u32 s7, s7, 0
	s_add_u32 s71, s71, 0x100
	s_addc_u32 s72, s72, 0
	s_cmp_gt_u32 s73, 13
	s_cbranch_scc0 .LBB0_952

.LBB0_1145:
	s_ashr_i32 s23, s22, 31
	s_lshl_b64 s[26:27], s[22:23], 19
	s_add_u32 s26, s45, s26
	s_addc_u32 s27, s46, s27
	s_and_b64 s[28:29], s[4:5], exec
	s_cselect_b32 s23, s27, s39
	s_cselect_b32 s31, s26, s38
	s_ashr_i32 s25, s24, 31
	s_lshl_b64 s[28:29], s[24:25], 19
	s_add_u32 s28, s47, s28
	s_addc_u32 s29, s48, s29
	s_and_b64 s[42:43], s[4:5], exec
	s_cselect_b32 s25, s29, s41
	s_cselect_b32 s37, s28, s40
	s_add_u32 s38, s38, 0x40080
	s_addc_u32 s39, s39, 0
	s_add_u32 s64, s40, 0x100
	s_addc_u32 s65, s41, 0
	s_mov_b32 s66, -2
	ds_read_b128 v[120:123], v233
	ds_read_b128 v[132:135], v233 offset:1024
	ds_read_b128 v[136:139], v233 offset:2048
	ds_read_b128 v[140:143], v233 offset:3072
	ds_read_b128 v[144:147], v234
	ds_read_b128 v[148:151], v234 offset:1024
	ds_read_b128 v[152:155], v234 offset:2048
	ds_read_b128 v[156:159], v234 offset:3072
	s_add_u32 s40, s38, 0xfffc0080
	s_addc_u32 s41, s39, -1
	s_cmp_eq_u32 s66, 12
	s_cselect_b32 s43, s23, s41
	s_cselect_b32 s42, s31, s40
	s_cselect_b32 s41, s25, s65
	s_cselect_b32 s40, s37, s64
	v_lshl_add_u64 v[208:209], s[38:39], 0, v[192:193]
	s_add_i32 m0, s50, 0xc000
	ds_read_b128 v[160:163], v235
	ds_read_b128 v[164:167], v235 offset:1024
	ds_read_b128 v[168:171], v235 offset:2048
	ds_read_b128 v[172:175], v235 offset:3072
	ds_read_b128 v[176:179], v235 offset:4096
	ds_read_b128 v[180:183], v235 offset:5120
	ds_read_b128 v[200:203], v235 offset:6144
	ds_read_b128 v[204:207], v235 offset:7168
	global_load_lds_dwordx4 v[208:209], off
	s_add_i32 m0, s50, 0xe000
	v_lshl_add_u64 v[208:209], s[38:39], 0, v[194:195]
	global_load_lds_dwordx4 v[208:209], off
	s_waitcnt vmcnt(8) lgkmcnt(0)
	s_barrier
	s_setprio 1
	v_mfma_f32_16x16x32_bf16 v[128:131], v[120:123], v[160:163], 0
	v_mfma_f32_16x16x32_bf16 v[128:131], v[132:135], v[164:167], v[128:131]
	v_mfma_f32_16x16x32_bf16 v[108:111], v[120:123], v[168:171], 0
	v_mfma_f32_16x16x32_bf16 v[108:111], v[132:135], v[172:175], v[108:111]
	v_mfma_f32_16x16x32_bf16 v[92:95], v[120:123], v[176:179], 0
	v_mfma_f32_16x16x32_bf16 v[92:95], v[132:135], v[180:183], v[92:95]
	v_mfma_f32_16x16x32_bf16 v[76:79], v[120:123], v[200:203], 0
	v_mfma_f32_16x16x32_bf16 v[76:79], v[132:135], v[204:207], v[76:79]
	v_mfma_f32_16x16x32_bf16 v[124:127], v[136:139], v[160:163], 0
	v_mfma_f32_16x16x32_bf16 v[124:127], v[140:143], v[164:167], v[124:127]
	v_mfma_f32_16x16x32_bf16 v[104:107], v[136:139], v[168:171], 0
	v_mfma_f32_16x16x32_bf16 v[104:107], v[140:143], v[172:175], v[104:107]
	v_mfma_f32_16x16x32_bf16 v[88:91], v[136:139], v[176:179], 0
	v_mfma_f32_16x16x32_bf16 v[88:91], v[140:143], v[180:183], v[88:91]
	v_mfma_f32_16x16x32_bf16 v[72:75], v[136:139], v[200:203], 0
	v_mfma_f32_16x16x32_bf16 v[72:75], v[140:143], v[204:207], v[72:75]
	v_mfma_f32_16x16x32_bf16 v[116:119], v[144:147], v[160:163], 0
	v_mfma_f32_16x16x32_bf16 v[116:119], v[148:151], v[164:167], v[116:119]
	v_mfma_f32_16x16x32_bf16 v[100:103], v[144:147], v[168:171], 0
	v_mfma_f32_16x16x32_bf16 v[100:103], v[148:151], v[172:175], v[100:103]
	v_mfma_f32_16x16x32_bf16 v[84:87], v[144:147], v[176:179], 0
	v_mfma_f32_16x16x32_bf16 v[84:87], v[148:151], v[180:183], v[84:87]
	v_mfma_f32_16x16x32_bf16 v[68:71], v[144:147], v[200:203], 0
	v_mfma_f32_16x16x32_bf16 v[68:71], v[148:151], v[204:207], v[68:71]
	v_mfma_f32_16x16x32_bf16 v[112:115], v[152:155], v[160:163], 0
	v_mfma_f32_16x16x32_bf16 v[112:115], v[156:159], v[164:167], v[112:115]
	v_mfma_f32_16x16x32_bf16 v[96:99], v[152:155], v[168:171], 0
	v_mfma_f32_16x16x32_bf16 v[96:99], v[156:159], v[172:175], v[96:99]
	s_setprio 2
	s_barrier
	v_mfma_f32_16x16x32_bf16 v[80:83], v[152:155], v[176:179], 0
	v_mfma_f32_16x16x32_bf16 v[80:83], v[156:159], v[180:183], v[80:83]
	v_mfma_f32_16x16x32_bf16 v[64:67], v[152:155], v[200:203], 0
	v_mfma_f32_16x16x32_bf16 v[64:67], v[156:159], v[204:207], v[64:67]
	s_setprio 2
	s_add_i32 s67, s62, s49
	v_lshl_add_u64 v[208:209], s[40:41], 0, v[186:187]
	s_mov_b32 m0, s67
	ds_read_b128 v[160:163], v235 offset:16384
	ds_read_b128 v[164:167], v235 offset:17408
	ds_read_b128 v[168:171], v235 offset:18432
	ds_read_b128 v[172:175], v235 offset:19456
	ds_read_b128 v[176:179], v235 offset:20480
	ds_read_b128 v[180:183], v235 offset:21504
	ds_read_b128 v[200:203], v235 offset:22528
	ds_read_b128 v[204:207], v235 offset:23552
	global_load_lds_dwordx4 v[208:209], off
	s_add_i32 m0, s67, 0x2000
	s_add_u32 s68, s40, 0x40000
	v_lshl_add_u64 v[210:211], s[40:41], 0, v[190:191]
	s_addc_u32 s69, s41, 0
	s_add_i32 s67, s63, s49
	global_load_lds_dwordx4 v[210:211], off
	v_lshl_add_u64 v[212:213], s[68:69], 0, v[186:187]
	s_mov_b32 m0, s67
	v_lshl_add_u64 v[214:215], s[42:43], 0, v[188:189]
	global_load_lds_dwordx4 v[212:213], off
	s_add_i32 m0, s67, 0x2000
	v_lshl_add_u64 v[212:213], s[68:69], 0, v[190:191]
	global_load_lds_dwordx4 v[212:213], off
	s_mov_b32 m0, s50
	v_lshl_add_u64 v[212:213], s[42:43], 0, v[184:185]
	global_load_lds_dwordx4 v[212:213], off
	s_mov_b32 m0, s51
	s_nop 0
	global_load_lds_dwordx4 v[214:215], off
	s_waitcnt vmcnt(8) lgkmcnt(0)
	s_barrier
	s_setprio 1
	v_mfma_f32_16x16x32_bf16 v[60:63], v[120:123], v[160:163], 0
	v_mfma_f32_16x16x32_bf16 v[60:63], v[132:135], v[164:167], v[60:63]
	v_mfma_f32_16x16x32_bf16 v[44:47], v[120:123], v[168:171], 0
	v_mfma_f32_16x16x32_bf16 v[44:47], v[132:135], v[172:175], v[44:47]
	v_mfma_f32_16x16x32_bf16 v[28:31], v[120:123], v[176:179], 0
	v_mfma_f32_16x16x32_bf16 v[28:31], v[132:135], v[180:183], v[28:31]
	v_mfma_f32_16x16x32_bf16 v[12:15], v[120:123], v[200:203], 0
	v_mfma_f32_16x16x32_bf16 v[12:15], v[132:135], v[204:207], v[12:15]
	v_mfma_f32_16x16x32_bf16 v[56:59], v[136:139], v[160:163], 0
	v_mfma_f32_16x16x32_bf16 v[56:59], v[140:143], v[164:167], v[56:59]
	v_mfma_f32_16x16x32_bf16 v[40:43], v[136:139], v[168:171], 0
	v_mfma_f32_16x16x32_bf16 v[40:43], v[140:143], v[172:175], v[40:43]
	v_mfma_f32_16x16x32_bf16 v[24:27], v[136:139], v[176:179], 0
	v_mfma_f32_16x16x32_bf16 v[24:27], v[140:143], v[180:183], v[24:27]
	v_mfma_f32_16x16x32_bf16 v[8:11], v[136:139], v[200:203], 0
	v_mfma_f32_16x16x32_bf16 v[8:11], v[140:143], v[204:207], v[8:11]
	v_mfma_f32_16x16x32_bf16 v[52:55], v[144:147], v[160:163], 0
	v_mfma_f32_16x16x32_bf16 v[52:55], v[148:151], v[164:167], v[52:55]
	v_mfma_f32_16x16x32_bf16 v[36:39], v[144:147], v[168:171], 0
	v_mfma_f32_16x16x32_bf16 v[36:39], v[148:151], v[172:175], v[36:39]
	v_mfma_f32_16x16x32_bf16 v[20:23], v[144:147], v[176:179], 0
	v_mfma_f32_16x16x32_bf16 v[20:23], v[148:151], v[180:183], v[20:23]
	v_mfma_f32_16x16x32_bf16 v[4:7], v[144:147], v[200:203], 0
	v_mfma_f32_16x16x32_bf16 v[4:7], v[148:151], v[204:207], v[4:7]
	v_mfma_f32_16x16x32_bf16 v[48:51], v[152:155], v[160:163], 0
	v_mfma_f32_16x16x32_bf16 v[48:51], v[156:159], v[164:167], v[48:51]
	v_mfma_f32_16x16x32_bf16 v[32:35], v[152:155], v[168:171], 0
	v_mfma_f32_16x16x32_bf16 v[32:35], v[156:159], v[172:175], v[32:35]
	s_setprio 2
	s_barrier
	v_mfma_f32_16x16x32_bf16 v[16:19], v[152:155], v[176:179], 0
	v_mfma_f32_16x16x32_bf16 v[16:19], v[156:159], v[180:183], v[16:19]
	v_mfma_f32_16x16x32_bf16 v[0:3], v[152:155], v[200:203], 0
	v_mfma_f32_16x16x32_bf16 v[0:3], v[156:159], v[204:207], v[0:3]
	s_setprio 0
	s_add_i32 s67, 0, 0x18000
	s_add_i32 s68, 0, 0x1c000
	v_add_u32_e32 v140, s67, v232
	v_add_u32_e32 v156, s68, v232
	ds_read_b128 v[120:123], v140
	ds_read_b128 v[132:135], v140 offset:1024
	ds_read_b128 v[136:139], v140 offset:2048
	ds_read_b128 v[140:143], v140 offset:3072
	ds_read_b128 v[144:147], v156
	ds_read_b128 v[148:151], v156 offset:1024
	ds_read_b128 v[152:155], v156 offset:2048
	ds_read_b128 v[156:159], v156 offset:3072
	s_add_u32 s42, s42, 0x40000
	s_addc_u32 s43, s43, 0
	s_mov_b32 m0, s54
	v_lshl_add_u64 v[216:217], s[42:43], 0, v[184:185]
	ds_read_b128 v[160:163], v235 offset:32768
	ds_read_b128 v[164:167], v235 offset:33792
	ds_read_b128 v[168:171], v235 offset:34816
	ds_read_b128 v[172:175], v235 offset:35840
	ds_read_b128 v[176:179], v235 offset:36864
	ds_read_b128 v[180:183], v235 offset:37888
	ds_read_b128 v[200:203], v235 offset:38912
	ds_read_b128 v[204:207], v235 offset:39936
	global_load_lds_dwordx4 v[216:217], off
	s_mov_b32 m0, s55
	v_lshl_add_u64 v[216:217], s[42:43], 0, v[188:189]
	global_load_lds_dwordx4 v[216:217], off
	s_waitcnt vmcnt(8) lgkmcnt(0)
	s_barrier
	s_setprio 1
	v_mfma_f32_16x16x32_bf16 v[128:131], v[120:123], v[160:163], v[128:131]
	v_mfma_f32_16x16x32_bf16 v[128:131], v[132:135], v[164:167], v[128:131]
	v_mfma_f32_16x16x32_bf16 v[108:111], v[120:123], v[168:171], v[108:111]
	v_mfma_f32_16x16x32_bf16 v[108:111], v[132:135], v[172:175], v[108:111]
	v_mfma_f32_16x16x32_bf16 v[92:95], v[120:123], v[176:179], v[92:95]
	v_mfma_f32_16x16x32_bf16 v[92:95], v[132:135], v[180:183], v[92:95]
	v_mfma_f32_16x16x32_bf16 v[76:79], v[120:123], v[200:203], v[76:79]
	v_mfma_f32_16x16x32_bf16 v[76:79], v[132:135], v[204:207], v[76:79]
	v_mfma_f32_16x16x32_bf16 v[124:127], v[136:139], v[160:163], v[124:127]
	v_mfma_f32_16x16x32_bf16 v[124:127], v[140:143], v[164:167], v[124:127]
	v_mfma_f32_16x16x32_bf16 v[104:107], v[136:139], v[168:171], v[104:107]
	v_mfma_f32_16x16x32_bf16 v[104:107], v[140:143], v[172:175], v[104:107]
	v_mfma_f32_16x16x32_bf16 v[88:91], v[136:139], v[176:179], v[88:91]
	v_mfma_f32_16x16x32_bf16 v[88:91], v[140:143], v[180:183], v[88:91]
	v_mfma_f32_16x16x32_bf16 v[72:75], v[136:139], v[200:203], v[72:75]
	v_mfma_f32_16x16x32_bf16 v[72:75], v[140:143], v[204:207], v[72:75]
	v_mfma_f32_16x16x32_bf16 v[116:119], v[144:147], v[160:163], v[116:119]
	v_mfma_f32_16x16x32_bf16 v[116:119], v[148:151], v[164:167], v[116:119]
	v_mfma_f32_16x16x32_bf16 v[100:103], v[144:147], v[168:171], v[100:103]
	v_mfma_f32_16x16x32_bf16 v[100:103], v[148:151], v[172:175], v[100:103]
	v_mfma_f32_16x16x32_bf16 v[84:87], v[144:147], v[176:179], v[84:87]
	v_mfma_f32_16x16x32_bf16 v[84:87], v[148:151], v[180:183], v[84:87]
	v_mfma_f32_16x16x32_bf16 v[68:71], v[144:147], v[200:203], v[68:71]
	v_mfma_f32_16x16x32_bf16 v[68:71], v[148:151], v[204:207], v[68:71]
	v_mfma_f32_16x16x32_bf16 v[112:115], v[152:155], v[160:163], v[112:115]
	v_mfma_f32_16x16x32_bf16 v[112:115], v[156:159], v[164:167], v[112:115]
	v_mfma_f32_16x16x32_bf16 v[96:99], v[152:155], v[168:171], v[96:99]
	v_mfma_f32_16x16x32_bf16 v[96:99], v[156:159], v[172:175], v[96:99]
	s_setprio 2
	s_barrier
	v_mfma_f32_16x16x32_bf16 v[80:83], v[152:155], v[176:179], v[80:83]
	v_mfma_f32_16x16x32_bf16 v[80:83], v[156:159], v[180:183], v[80:83]
	v_mfma_f32_16x16x32_bf16 v[64:67], v[152:155], v[200:203], v[64:67]
	v_mfma_f32_16x16x32_bf16 v[64:67], v[156:159], v[204:207], v[64:67]
	s_setprio 2
	s_add_i32 s42, s67, s49
	v_lshl_add_u64 v[208:209], v[208:209], 0, s[18:19]
	s_mov_b32 m0, s42
	ds_read_b128 v[160:163], v235 offset:49152
	ds_read_b128 v[164:167], v235 offset:50176
	ds_read_b128 v[168:171], v235 offset:51200
	ds_read_b128 v[172:175], v235 offset:52224
	ds_read_b128 v[176:179], v235 offset:53248
	ds_read_b128 v[180:183], v235 offset:54272
	ds_read_b128 v[200:203], v235 offset:55296
	ds_read_b128 v[204:207], v235 offset:56320
	global_load_lds_dwordx4 v[208:209], off
	s_add_i32 m0, s42, 0x2000
	s_add_u32 s40, s40, 0x40080
	v_lshl_add_u64 v[208:209], v[210:211], 0, s[18:19]
	s_addc_u32 s41, s41, 0
	s_add_i32 s42, s68, s49
	global_load_lds_dwordx4 v[208:209], off
	s_mov_b32 m0, s42
	v_lshl_add_u64 v[208:209], s[40:41], 0, v[186:187]
	global_load_lds_dwordx4 v[208:209], off
	s_add_i32 m0, s42, 0x2000
	v_lshl_add_u64 v[208:209], s[40:41], 0, v[190:191]
	global_load_lds_dwordx4 v[208:209], off
	s_mov_b32 m0, s57
	v_lshl_add_u64 v[208:209], v[212:213], 0, s[18:19]
	global_load_lds_dwordx4 v[208:209], off
	s_mov_b32 m0, s58
	v_lshl_add_u64 v[208:209], v[214:215], 0, s[18:19]
	global_load_lds_dwordx4 v[208:209], off
	s_waitcnt vmcnt(8) lgkmcnt(0)
	s_barrier
	s_setprio 1
	v_mfma_f32_16x16x32_bf16 v[60:63], v[120:123], v[160:163], v[60:63]
	v_mfma_f32_16x16x32_bf16 v[60:63], v[132:135], v[164:167], v[60:63]
	v_mfma_f32_16x16x32_bf16 v[44:47], v[120:123], v[168:171], v[44:47]
	v_mfma_f32_16x16x32_bf16 v[44:47], v[132:135], v[172:175], v[44:47]
	v_mfma_f32_16x16x32_bf16 v[28:31], v[120:123], v[176:179], v[28:31]
	v_mfma_f32_16x16x32_bf16 v[28:31], v[132:135], v[180:183], v[28:31]
	v_mfma_f32_16x16x32_bf16 v[12:15], v[120:123], v[200:203], v[12:15]
	v_mfma_f32_16x16x32_bf16 v[12:15], v[132:135], v[204:207], v[12:15]
	v_mfma_f32_16x16x32_bf16 v[56:59], v[136:139], v[160:163], v[56:59]
	v_mfma_f32_16x16x32_bf16 v[56:59], v[140:143], v[164:167], v[56:59]
	v_mfma_f32_16x16x32_bf16 v[40:43], v[136:139], v[168:171], v[40:43]
	v_mfma_f32_16x16x32_bf16 v[40:43], v[140:143], v[172:175], v[40:43]
	v_mfma_f32_16x16x32_bf16 v[24:27], v[136:139], v[176:179], v[24:27]
	v_mfma_f32_16x16x32_bf16 v[24:27], v[140:143], v[180:183], v[24:27]
	v_mfma_f32_16x16x32_bf16 v[8:11], v[136:139], v[200:203], v[8:11]
	v_mfma_f32_16x16x32_bf16 v[8:11], v[140:143], v[204:207], v[8:11]
	v_mfma_f32_16x16x32_bf16 v[52:55], v[144:147], v[160:163], v[52:55]
	v_mfma_f32_16x16x32_bf16 v[52:55], v[148:151], v[164:167], v[52:55]
	v_mfma_f32_16x16x32_bf16 v[36:39], v[144:147], v[168:171], v[36:39]
	v_mfma_f32_16x16x32_bf16 v[36:39], v[148:151], v[172:175], v[36:39]
	v_mfma_f32_16x16x32_bf16 v[20:23], v[144:147], v[176:179], v[20:23]
	v_mfma_f32_16x16x32_bf16 v[20:23], v[148:151], v[180:183], v[20:23]
	v_mfma_f32_16x16x32_bf16 v[4:7], v[144:147], v[200:203], v[4:7]
	v_mfma_f32_16x16x32_bf16 v[4:7], v[148:151], v[204:207], v[4:7]
	v_mfma_f32_16x16x32_bf16 v[48:51], v[152:155], v[160:163], v[48:51]
	v_mfma_f32_16x16x32_bf16 v[48:51], v[156:159], v[164:167], v[48:51]
	v_mfma_f32_16x16x32_bf16 v[32:35], v[152:155], v[168:171], v[32:35]
	v_mfma_f32_16x16x32_bf16 v[32:35], v[156:159], v[172:175], v[32:35]
	s_setprio 2
	s_barrier
	v_mfma_f32_16x16x32_bf16 v[16:19], v[152:155], v[176:179], v[16:19]
	v_mfma_f32_16x16x32_bf16 v[16:19], v[156:159], v[180:183], v[16:19]
	v_mfma_f32_16x16x32_bf16 v[0:3], v[152:155], v[200:203], v[0:3]
	v_mfma_f32_16x16x32_bf16 v[0:3], v[156:159], v[204:207], v[0:3]
	s_setprio 0
	s_add_i32 s66, s66, 2
	s_add_u32 s38, s38, 0x100
	s_addc_u32 s39, s39, 0
	s_add_u32 s64, s64, 0x100
	s_addc_u32 s65, s65, 0
	s_cmp_gt_u32 s66, 13
.LBB0_1146:
	ds_read_b128 v[120:123], v233
	ds_read_b128 v[132:135], v233 offset:1024
	ds_read_b128 v[136:139], v233 offset:2048
	ds_read_b128 v[140:143], v233 offset:3072
	ds_read_b128 v[144:147], v234
	ds_read_b128 v[148:151], v234 offset:1024
	ds_read_b128 v[152:155], v234 offset:2048
	ds_read_b128 v[156:159], v234 offset:3072
	s_add_u32 s40, s38, 0xfffc0080
	s_addc_u32 s41, s39, -1
	s_cmp_eq_u32 s66, 12
	s_cselect_b32 s43, s23, s41
	s_cselect_b32 s42, s31, s40
	s_cselect_b32 s41, s25, s65
	s_cselect_b32 s40, s37, s64
	v_lshl_add_u64 v[208:209], s[38:39], 0, v[192:193]
	s_add_i32 m0, s50, 0xc000
	ds_read_b128 v[160:163], v235
	ds_read_b128 v[164:167], v235 offset:1024
	ds_read_b128 v[168:171], v235 offset:2048
	ds_read_b128 v[172:175], v235 offset:3072
	ds_read_b128 v[176:179], v235 offset:4096
	ds_read_b128 v[180:183], v235 offset:5120
	ds_read_b128 v[200:203], v235 offset:6144
	ds_read_b128 v[204:207], v235 offset:7168
	global_load_lds_dwordx4 v[208:209], off
	s_add_i32 m0, s50, 0xe000
	v_lshl_add_u64 v[208:209], s[38:39], 0, v[194:195]
	global_load_lds_dwordx4 v[208:209], off
	s_waitcnt vmcnt(8) lgkmcnt(0)
	s_barrier
	s_setprio 1
	v_mfma_f32_16x16x32_bf16 v[128:131], v[120:123], v[160:163], v[128:131]
	v_mfma_f32_16x16x32_bf16 v[128:131], v[132:135], v[164:167], v[128:131]
	v_mfma_f32_16x16x32_bf16 v[108:111], v[120:123], v[168:171], v[108:111]
	v_mfma_f32_16x16x32_bf16 v[108:111], v[132:135], v[172:175], v[108:111]
	v_mfma_f32_16x16x32_bf16 v[92:95], v[120:123], v[176:179], v[92:95]
	v_mfma_f32_16x16x32_bf16 v[92:95], v[132:135], v[180:183], v[92:95]
	v_mfma_f32_16x16x32_bf16 v[76:79], v[120:123], v[200:203], v[76:79]
	v_mfma_f32_16x16x32_bf16 v[76:79], v[132:135], v[204:207], v[76:79]
	v_mfma_f32_16x16x32_bf16 v[124:127], v[136:139], v[160:163], v[124:127]
	v_mfma_f32_16x16x32_bf16 v[124:127], v[140:143], v[164:167], v[124:127]
	v_mfma_f32_16x16x32_bf16 v[104:107], v[136:139], v[168:171], v[104:107]
	v_mfma_f32_16x16x32_bf16 v[104:107], v[140:143], v[172:175], v[104:107]
	v_mfma_f32_16x16x32_bf16 v[88:91], v[136:139], v[176:179], v[88:91]
	v_mfma_f32_16x16x32_bf16 v[88:91], v[140:143], v[180:183], v[88:91]
	v_mfma_f32_16x16x32_bf16 v[72:75], v[136:139], v[200:203], v[72:75]
	v_mfma_f32_16x16x32_bf16 v[72:75], v[140:143], v[204:207], v[72:75]
	v_mfma_f32_16x16x32_bf16 v[116:119], v[144:147], v[160:163], v[116:119]
	v_mfma_f32_16x16x32_bf16 v[116:119], v[148:151], v[164:167], v[116:119]
	v_mfma_f32_16x16x32_bf16 v[100:103], v[144:147], v[168:171], v[100:103]
	v_mfma_f32_16x16x32_bf16 v[100:103], v[148:151], v[172:175], v[100:103]
	v_mfma_f32_16x16x32_bf16 v[84:87], v[144:147], v[176:179], v[84:87]
	v_mfma_f32_16x16x32_bf16 v[84:87], v[148:151], v[180:183], v[84:87]
	v_mfma_f32_16x16x32_bf16 v[68:71], v[144:147], v[200:203], v[68:71]
	v_mfma_f32_16x16x32_bf16 v[68:71], v[148:151], v[204:207], v[68:71]
	v_mfma_f32_16x16x32_bf16 v[112:115], v[152:155], v[160:163], v[112:115]
	v_mfma_f32_16x16x32_bf16 v[112:115], v[156:159], v[164:167], v[112:115]
	v_mfma_f32_16x16x32_bf16 v[96:99], v[152:155], v[168:171], v[96:99]
	v_mfma_f32_16x16x32_bf16 v[96:99], v[156:159], v[172:175], v[96:99]
	s_setprio 2
	s_barrier
	v_mfma_f32_16x16x32_bf16 v[80:83], v[152:155], v[176:179], v[80:83]
	v_mfma_f32_16x16x32_bf16 v[80:83], v[156:159], v[180:183], v[80:83]
	v_mfma_f32_16x16x32_bf16 v[64:67], v[152:155], v[200:203], v[64:67]
	v_mfma_f32_16x16x32_bf16 v[64:67], v[156:159], v[204:207], v[64:67]
	s_setprio 2
	s_add_i32 s67, s62, s49
	v_lshl_add_u64 v[208:209], s[40:41], 0, v[186:187]
	s_mov_b32 m0, s67
	ds_read_b128 v[160:163], v235 offset:16384
	ds_read_b128 v[164:167], v235 offset:17408
	ds_read_b128 v[168:171], v235 offset:18432
	ds_read_b128 v[172:175], v235 offset:19456
	ds_read_b128 v[176:179], v235 offset:20480
	ds_read_b128 v[180:183], v235 offset:21504
	ds_read_b128 v[200:203], v235 offset:22528
	ds_read_b128 v[204:207], v235 offset:23552
	global_load_lds_dwordx4 v[208:209], off
	s_add_i32 m0, s67, 0x2000
	s_add_u32 s68, s40, 0x40000
	v_lshl_add_u64 v[210:211], s[40:41], 0, v[190:191]
	s_addc_u32 s69, s41, 0
	s_add_i32 s67, s63, s49
	global_load_lds_dwordx4 v[210:211], off
	v_lshl_add_u64 v[212:213], s[68:69], 0, v[186:187]
	s_mov_b32 m0, s67
	v_lshl_add_u64 v[214:215], s[42:43], 0, v[188:189]
	global_load_lds_dwordx4 v[212:213], off
	s_add_i32 m0, s67, 0x2000
	v_lshl_add_u64 v[212:213], s[68:69], 0, v[190:191]
	global_load_lds_dwordx4 v[212:213], off
	s_mov_b32 m0, s50
	v_lshl_add_u64 v[212:213], s[42:43], 0, v[184:185]
	global_load_lds_dwordx4 v[212:213], off
	s_mov_b32 m0, s51
	s_nop 0
	global_load_lds_dwordx4 v[214:215], off
	s_waitcnt vmcnt(8) lgkmcnt(0)
	s_barrier
	s_setprio 1
	v_mfma_f32_16x16x32_bf16 v[60:63], v[120:123], v[160:163], v[60:63]
	v_mfma_f32_16x16x32_bf16 v[60:63], v[132:135], v[164:167], v[60:63]
	v_mfma_f32_16x16x32_bf16 v[44:47], v[120:123], v[168:171], v[44:47]
	v_mfma_f32_16x16x32_bf16 v[44:47], v[132:135], v[172:175], v[44:47]
	v_mfma_f32_16x16x32_bf16 v[28:31], v[120:123], v[176:179], v[28:31]
	v_mfma_f32_16x16x32_bf16 v[28:31], v[132:135], v[180:183], v[28:31]
	v_mfma_f32_16x16x32_bf16 v[12:15], v[120:123], v[200:203], v[12:15]
	v_mfma_f32_16x16x32_bf16 v[12:15], v[132:135], v[204:207], v[12:15]
	v_mfma_f32_16x16x32_bf16 v[56:59], v[136:139], v[160:163], v[56:59]
	v_mfma_f32_16x16x32_bf16 v[56:59], v[140:143], v[164:167], v[56:59]
	v_mfma_f32_16x16x32_bf16 v[40:43], v[136:139], v[168:171], v[40:43]
	v_mfma_f32_16x16x32_bf16 v[40:43], v[140:143], v[172:175], v[40:43]
	v_mfma_f32_16x16x32_bf16 v[24:27], v[136:139], v[176:179], v[24:27]
	v_mfma_f32_16x16x32_bf16 v[24:27], v[140:143], v[180:183], v[24:27]
	v_mfma_f32_16x16x32_bf16 v[8:11], v[136:139], v[200:203], v[8:11]
	v_mfma_f32_16x16x32_bf16 v[8:11], v[140:143], v[204:207], v[8:11]
	v_mfma_f32_16x16x32_bf16 v[52:55], v[144:147], v[160:163], v[52:55]
	v_mfma_f32_16x16x32_bf16 v[52:55], v[148:151], v[164:167], v[52:55]
	v_mfma_f32_16x16x32_bf16 v[36:39], v[144:147], v[168:171], v[36:39]
	v_mfma_f32_16x16x32_bf16 v[36:39], v[148:151], v[172:175], v[36:39]
	v_mfma_f32_16x16x32_bf16 v[20:23], v[144:147], v[176:179], v[20:23]
	v_mfma_f32_16x16x32_bf16 v[20:23], v[148:151], v[180:183], v[20:23]
	v_mfma_f32_16x16x32_bf16 v[4:7], v[144:147], v[200:203], v[4:7]
	v_mfma_f32_16x16x32_bf16 v[4:7], v[148:151], v[204:207], v[4:7]
	v_mfma_f32_16x16x32_bf16 v[48:51], v[152:155], v[160:163], v[48:51]
	v_mfma_f32_16x16x32_bf16 v[48:51], v[156:159], v[164:167], v[48:51]
	v_mfma_f32_16x16x32_bf16 v[32:35], v[152:155], v[168:171], v[32:35]
	v_mfma_f32_16x16x32_bf16 v[32:35], v[156:159], v[172:175], v[32:35]
	s_setprio 2
	s_barrier
	v_mfma_f32_16x16x32_bf16 v[16:19], v[152:155], v[176:179], v[16:19]
	v_mfma_f32_16x16x32_bf16 v[16:19], v[156:159], v[180:183], v[16:19]
	v_mfma_f32_16x16x32_bf16 v[0:3], v[152:155], v[200:203], v[0:3]
	v_mfma_f32_16x16x32_bf16 v[0:3], v[156:159], v[204:207], v[0:3]
	s_setprio 0
	s_add_i32 s67, 0, 0x18000
	s_add_i32 s68, 0, 0x1c000
	v_add_u32_e32 v140, s67, v232
	v_add_u32_e32 v156, s68, v232
	ds_read_b128 v[120:123], v140
	ds_read_b128 v[132:135], v140 offset:1024
	ds_read_b128 v[136:139], v140 offset:2048
	ds_read_b128 v[140:143], v140 offset:3072
	ds_read_b128 v[144:147], v156
	ds_read_b128 v[148:151], v156 offset:1024
	ds_read_b128 v[152:155], v156 offset:2048
	ds_read_b128 v[156:159], v156 offset:3072
	s_add_u32 s42, s42, 0x40000
	s_addc_u32 s43, s43, 0
	s_mov_b32 m0, s54
	v_lshl_add_u64 v[216:217], s[42:43], 0, v[184:185]
	ds_read_b128 v[160:163], v235 offset:32768
	ds_read_b128 v[164:167], v235 offset:33792
	ds_read_b128 v[168:171], v235 offset:34816
	ds_read_b128 v[172:175], v235 offset:35840
	ds_read_b128 v[176:179], v235 offset:36864
	ds_read_b128 v[180:183], v235 offset:37888
	ds_read_b128 v[200:203], v235 offset:38912
	ds_read_b128 v[204:207], v235 offset:39936
	global_load_lds_dwordx4 v[216:217], off
	s_mov_b32 m0, s55
	v_lshl_add_u64 v[216:217], s[42:43], 0, v[188:189]
	global_load_lds_dwordx4 v[216:217], off
	s_waitcnt vmcnt(8) lgkmcnt(0)
	s_barrier
	s_setprio 1
	v_mfma_f32_16x16x32_bf16 v[128:131], v[120:123], v[160:163], v[128:131]
	v_mfma_f32_16x16x32_bf16 v[128:131], v[132:135], v[164:167], v[128:131]
	v_mfma_f32_16x16x32_bf16 v[108:111], v[120:123], v[168:171], v[108:111]
	v_mfma_f32_16x16x32_bf16 v[108:111], v[132:135], v[172:175], v[108:111]
	v_mfma_f32_16x16x32_bf16 v[92:95], v[120:123], v[176:179], v[92:95]
	v_mfma_f32_16x16x32_bf16 v[92:95], v[132:135], v[180:183], v[92:95]
	v_mfma_f32_16x16x32_bf16 v[76:79], v[120:123], v[200:203], v[76:79]
	v_mfma_f32_16x16x32_bf16 v[76:79], v[132:135], v[204:207], v[76:79]
	v_mfma_f32_16x16x32_bf16 v[124:127], v[136:139], v[160:163], v[124:127]
	v_mfma_f32_16x16x32_bf16 v[124:127], v[140:143], v[164:167], v[124:127]
	v_mfma_f32_16x16x32_bf16 v[104:107], v[136:139], v[168:171], v[104:107]
	v_mfma_f32_16x16x32_bf16 v[104:107], v[140:143], v[172:175], v[104:107]
	v_mfma_f32_16x16x32_bf16 v[88:91], v[136:139], v[176:179], v[88:91]
	v_mfma_f32_16x16x32_bf16 v[88:91], v[140:143], v[180:183], v[88:91]
	v_mfma_f32_16x16x32_bf16 v[72:75], v[136:139], v[200:203], v[72:75]
	v_mfma_f32_16x16x32_bf16 v[72:75], v[140:143], v[204:207], v[72:75]
	v_mfma_f32_16x16x32_bf16 v[116:119], v[144:147], v[160:163], v[116:119]
	v_mfma_f32_16x16x32_bf16 v[116:119], v[148:151], v[164:167], v[116:119]
	v_mfma_f32_16x16x32_bf16 v[100:103], v[144:147], v[168:171], v[100:103]
	v_mfma_f32_16x16x32_bf16 v[100:103], v[148:151], v[172:175], v[100:103]
	v_mfma_f32_16x16x32_bf16 v[84:87], v[144:147], v[176:179], v[84:87]
	v_mfma_f32_16x16x32_bf16 v[84:87], v[148:151], v[180:183], v[84:87]
	v_mfma_f32_16x16x32_bf16 v[68:71], v[144:147], v[200:203], v[68:71]
	v_mfma_f32_16x16x32_bf16 v[68:71], v[148:151], v[204:207], v[68:71]
	v_mfma_f32_16x16x32_bf16 v[112:115], v[152:155], v[160:163], v[112:115]
	v_mfma_f32_16x16x32_bf16 v[112:115], v[156:159], v[164:167], v[112:115]
	v_mfma_f32_16x16x32_bf16 v[96:99], v[152:155], v[168:171], v[96:99]
	v_mfma_f32_16x16x32_bf16 v[96:99], v[156:159], v[172:175], v[96:99]
	s_setprio 2
	s_barrier
	v_mfma_f32_16x16x32_bf16 v[80:83], v[152:155], v[176:179], v[80:83]
	v_mfma_f32_16x16x32_bf16 v[80:83], v[156:159], v[180:183], v[80:83]
	v_mfma_f32_16x16x32_bf16 v[64:67], v[152:155], v[200:203], v[64:67]
	v_mfma_f32_16x16x32_bf16 v[64:67], v[156:159], v[204:207], v[64:67]
	s_setprio 2
	s_add_i32 s42, s67, s49
	v_lshl_add_u64 v[208:209], v[208:209], 0, s[18:19]
	s_mov_b32 m0, s42
	ds_read_b128 v[160:163], v235 offset:49152
	ds_read_b128 v[164:167], v235 offset:50176
	ds_read_b128 v[168:171], v235 offset:51200
	ds_read_b128 v[172:175], v235 offset:52224
	ds_read_b128 v[176:179], v235 offset:53248
	ds_read_b128 v[180:183], v235 offset:54272
	ds_read_b128 v[200:203], v235 offset:55296
	ds_read_b128 v[204:207], v235 offset:56320
	global_load_lds_dwordx4 v[208:209], off
	s_add_i32 m0, s42, 0x2000
	s_add_u32 s40, s40, 0x40080
	v_lshl_add_u64 v[208:209], v[210:211], 0, s[18:19]
	s_addc_u32 s41, s41, 0
	s_add_i32 s42, s68, s49
	global_load_lds_dwordx4 v[208:209], off
	s_mov_b32 m0, s42
	v_lshl_add_u64 v[208:209], s[40:41], 0, v[186:187]
	global_load_lds_dwordx4 v[208:209], off
	s_add_i32 m0, s42, 0x2000
	v_lshl_add_u64 v[208:209], s[40:41], 0, v[190:191]
	global_load_lds_dwordx4 v[208:209], off
	s_mov_b32 m0, s57
	v_lshl_add_u64 v[208:209], v[212:213], 0, s[18:19]
	global_load_lds_dwordx4 v[208:209], off
	s_mov_b32 m0, s58
	v_lshl_add_u64 v[208:209], v[214:215], 0, s[18:19]
	global_load_lds_dwordx4 v[208:209], off
	s_waitcnt vmcnt(8) lgkmcnt(0)
	s_barrier
	s_setprio 1
	v_mfma_f32_16x16x32_bf16 v[60:63], v[120:123], v[160:163], v[60:63]
	v_mfma_f32_16x16x32_bf16 v[60:63], v[132:135], v[164:167], v[60:63]
	v_mfma_f32_16x16x32_bf16 v[44:47], v[120:123], v[168:171], v[44:47]
	v_mfma_f32_16x16x32_bf16 v[44:47], v[132:135], v[172:175], v[44:47]
	v_mfma_f32_16x16x32_bf16 v[28:31], v[120:123], v[176:179], v[28:31]
	v_mfma_f32_16x16x32_bf16 v[28:31], v[132:135], v[180:183], v[28:31]
	v_mfma_f32_16x16x32_bf16 v[12:15], v[120:123], v[200:203], v[12:15]
	v_mfma_f32_16x16x32_bf16 v[12:15], v[132:135], v[204:207], v[12:15]
	v_mfma_f32_16x16x32_bf16 v[56:59], v[136:139], v[160:163], v[56:59]
	v_mfma_f32_16x16x32_bf16 v[56:59], v[140:143], v[164:167], v[56:59]
	v_mfma_f32_16x16x32_bf16 v[40:43], v[136:139], v[168:171], v[40:43]
	v_mfma_f32_16x16x32_bf16 v[40:43], v[140:143], v[172:175], v[40:43]
	v_mfma_f32_16x16x32_bf16 v[24:27], v[136:139], v[176:179], v[24:27]
	v_mfma_f32_16x16x32_bf16 v[24:27], v[140:143], v[180:183], v[24:27]
	v_mfma_f32_16x16x32_bf16 v[8:11], v[136:139], v[200:203], v[8:11]
	v_mfma_f32_16x16x32_bf16 v[8:11], v[140:143], v[204:207], v[8:11]
	v_mfma_f32_16x16x32_bf16 v[52:55], v[144:147], v[160:163], v[52:55]
	v_mfma_f32_16x16x32_bf16 v[52:55], v[148:151], v[164:167], v[52:55]
	v_mfma_f32_16x16x32_bf16 v[36:39], v[144:147], v[168:171], v[36:39]
	v_mfma_f32_16x16x32_bf16 v[36:39], v[148:151], v[172:175], v[36:39]
	v_mfma_f32_16x16x32_bf16 v[20:23], v[144:147], v[176:179], v[20:23]
	v_mfma_f32_16x16x32_bf16 v[20:23], v[148:151], v[180:183], v[20:23]
	v_mfma_f32_16x16x32_bf16 v[4:7], v[144:147], v[200:203], v[4:7]
	v_mfma_f32_16x16x32_bf16 v[4:7], v[148:151], v[204:207], v[4:7]
	v_mfma_f32_16x16x32_bf16 v[48:51], v[152:155], v[160:163], v[48:51]
	v_mfma_f32_16x16x32_bf16 v[48:51], v[156:159], v[164:167], v[48:51]
	v_mfma_f32_16x16x32_bf16 v[32:35], v[152:155], v[168:171], v[32:35]
	v_mfma_f32_16x16x32_bf16 v[32:35], v[156:159], v[172:175], v[32:35]
	s_setprio 2
	s_barrier
	v_mfma_f32_16x16x32_bf16 v[16:19], v[152:155], v[176:179], v[16:19]
	v_mfma_f32_16x16x32_bf16 v[16:19], v[156:159], v[180:183], v[16:19]
	v_mfma_f32_16x16x32_bf16 v[0:3], v[152:155], v[200:203], v[0:3]
	v_mfma_f32_16x16x32_bf16 v[0:3], v[156:159], v[204:207], v[0:3]
	s_setprio 0
	s_add_i32 s66, s66, 2
	s_add_u32 s38, s38, 0x100
	s_addc_u32 s39, s39, 0
	s_add_u32 s64, s64, 0x100
	s_addc_u32 s65, s65, 0
	s_cmp_gt_u32 s66, 13
	s_cbranch_scc0 .LBB0_1146

.LBB0_1309:
	s_add_u32 s51, s26, 0x100
	s_addc_u32 s52, s27, 0
	s_mov_b32 s53, -2
	ds_read_b128 v[128:131], v197
	ds_read_b128 v[132:135], v197 offset:1024
	ds_read_b128 v[136:139], v197 offset:2048
	ds_read_b128 v[140:143], v197 offset:3072
	ds_read_b128 v[144:147], v198
	ds_read_b128 v[148:151], v198 offset:1024
	ds_read_b128 v[152:155], v198 offset:2048
	ds_read_b128 v[156:159], v198 offset:3072
	s_add_u32 s4, s24, 0x100
	s_addc_u32 s5, s25, 0
	s_cmp_eq_u32 s53, 40
	s_cselect_b32 s29, s21, s5
	s_cselect_b32 s28, s20, s4
	s_cselect_b32 s27, s23, s52
	s_cselect_b32 s26, s22, s51
	v_lshl_add_u64 v[212:213], s[24:25], 0, v[172:173]
	s_add_i32 m0, s36, 0xc000
	ds_read_b128 v[160:163], v199
	ds_read_b128 v[180:183], v199 offset:1024
	ds_read_b128 v[184:187], v199 offset:2048
	ds_read_b128 v[188:191], v199 offset:3072
	ds_read_b128 v[192:195], v199 offset:4096
	ds_read_b128 v[200:203], v199 offset:5120
	ds_read_b128 v[204:207], v199 offset:6144
	ds_read_b128 v[208:211], v199 offset:7168
	global_load_lds_dwordx4 v[212:213], off
	s_add_i32 m0, s36, 0xe000
	v_lshl_add_u64 v[212:213], s[24:25], 0, v[174:175]
	global_load_lds_dwordx4 v[212:213], off
	s_waitcnt vmcnt(8) lgkmcnt(0)
	s_barrier
	s_setprio 1
	v_mfma_f32_16x16x32_bf16 v[124:127], v[128:131], v[160:163], 0
	v_mfma_f32_16x16x32_bf16 v[124:127], v[132:135], v[180:183], v[124:127]
	v_mfma_f32_16x16x32_bf16 v[116:119], v[128:131], v[184:187], 0
	v_mfma_f32_16x16x32_bf16 v[116:119], v[132:135], v[188:191], v[116:119]
	v_mfma_f32_16x16x32_bf16 v[88:91], v[128:131], v[192:195], 0
	v_mfma_f32_16x16x32_bf16 v[88:91], v[132:135], v[200:203], v[88:91]
	v_mfma_f32_16x16x32_bf16 v[72:75], v[128:131], v[204:207], 0
	v_mfma_f32_16x16x32_bf16 v[72:75], v[132:135], v[208:211], v[72:75]
	v_mfma_f32_16x16x32_bf16 v[120:123], v[136:139], v[160:163], 0
	v_mfma_f32_16x16x32_bf16 v[120:123], v[140:143], v[180:183], v[120:123]
	v_mfma_f32_16x16x32_bf16 v[108:111], v[136:139], v[184:187], 0
	v_mfma_f32_16x16x32_bf16 v[108:111], v[140:143], v[188:191], v[108:111]
	v_mfma_f32_16x16x32_bf16 v[100:103], v[136:139], v[192:195], 0
	v_mfma_f32_16x16x32_bf16 v[100:103], v[140:143], v[200:203], v[100:103]
	v_mfma_f32_16x16x32_bf16 v[76:79], v[136:139], v[204:207], 0
	v_mfma_f32_16x16x32_bf16 v[76:79], v[140:143], v[208:211], v[76:79]
	v_mfma_f32_16x16x32_bf16 v[112:115], v[144:147], v[160:163], 0
	v_mfma_f32_16x16x32_bf16 v[112:115], v[148:151], v[180:183], v[112:115]
	v_mfma_f32_16x16x32_bf16 v[96:99], v[144:147], v[184:187], 0
	v_mfma_f32_16x16x32_bf16 v[96:99], v[148:151], v[188:191], v[96:99]
	v_mfma_f32_16x16x32_bf16 v[80:83], v[144:147], v[192:195], 0
	v_mfma_f32_16x16x32_bf16 v[80:83], v[148:151], v[200:203], v[80:83]
	v_mfma_f32_16x16x32_bf16 v[64:67], v[144:147], v[204:207], 0
	v_mfma_f32_16x16x32_bf16 v[64:67], v[148:151], v[208:211], v[64:67]
	v_mfma_f32_16x16x32_bf16 v[104:107], v[152:155], v[160:163], 0
	v_mfma_f32_16x16x32_bf16 v[104:107], v[156:159], v[180:183], v[104:107]
	v_mfma_f32_16x16x32_bf16 v[92:95], v[152:155], v[184:187], 0
	v_mfma_f32_16x16x32_bf16 v[92:95], v[156:159], v[188:191], v[92:95]
	s_setprio 2
	s_barrier
	v_mfma_f32_16x16x32_bf16 v[84:87], v[152:155], v[192:195], 0
	v_mfma_f32_16x16x32_bf16 v[84:87], v[156:159], v[200:203], v[84:87]
	v_mfma_f32_16x16x32_bf16 v[68:71], v[152:155], v[204:207], 0
	v_mfma_f32_16x16x32_bf16 v[68:71], v[156:159], v[208:211], v[68:71]
	s_setprio 2
	s_add_i32 s24, s45, s35
	v_lshl_add_u64 v[212:213], s[26:27], 0, v[166:167]
	s_mov_b32 m0, s24
	ds_read_b128 v[160:163], v199 offset:16384
	ds_read_b128 v[180:183], v199 offset:17408
	ds_read_b128 v[184:187], v199 offset:18432
	ds_read_b128 v[188:191], v199 offset:19456
	ds_read_b128 v[192:195], v199 offset:20480
	ds_read_b128 v[200:203], v199 offset:21504
	ds_read_b128 v[204:207], v199 offset:22528
	ds_read_b128 v[208:211], v199 offset:23552
	global_load_lds_dwordx4 v[212:213], off
	s_add_i32 m0, s24, 0x2000
	s_add_u32 s24, s26, 0xb0000
	v_lshl_add_u64 v[214:215], s[26:27], 0, v[170:171]
	s_addc_u32 s25, s27, 0
	s_add_i32 s54, s46, s35
	global_load_lds_dwordx4 v[214:215], off
	v_lshl_add_u64 v[216:217], s[24:25], 0, v[166:167]
	s_mov_b32 m0, s54
	v_lshl_add_u64 v[218:219], s[28:29], 0, v[168:169]
	global_load_lds_dwordx4 v[216:217], off
	s_add_i32 m0, s54, 0x2000
	v_lshl_add_u64 v[216:217], s[24:25], 0, v[170:171]
	global_load_lds_dwordx4 v[216:217], off
	s_mov_b32 m0, s36
	v_lshl_add_u64 v[216:217], s[28:29], 0, v[164:165]
	global_load_lds_dwordx4 v[216:217], off
	s_mov_b32 m0, s37
	s_nop 0
	global_load_lds_dwordx4 v[218:219], off
	s_waitcnt vmcnt(8) lgkmcnt(0)
	s_barrier
	s_setprio 1
	v_mfma_f32_16x16x32_bf16 v[56:59], v[128:131], v[160:163], 0
	v_mfma_f32_16x16x32_bf16 v[56:59], v[132:135], v[180:183], v[56:59]
	v_mfma_f32_16x16x32_bf16 v[40:43], v[128:131], v[184:187], 0
	v_mfma_f32_16x16x32_bf16 v[40:43], v[132:135], v[188:191], v[40:43]
	v_mfma_f32_16x16x32_bf16 v[24:27], v[128:131], v[192:195], 0
	v_mfma_f32_16x16x32_bf16 v[24:27], v[132:135], v[200:203], v[24:27]
	v_mfma_f32_16x16x32_bf16 v[8:11], v[128:131], v[204:207], 0
	v_mfma_f32_16x16x32_bf16 v[8:11], v[132:135], v[208:211], v[8:11]
	v_mfma_f32_16x16x32_bf16 v[60:63], v[136:139], v[160:163], 0
	v_mfma_f32_16x16x32_bf16 v[60:63], v[140:143], v[180:183], v[60:63]
	v_mfma_f32_16x16x32_bf16 v[44:47], v[136:139], v[184:187], 0
	v_mfma_f32_16x16x32_bf16 v[44:47], v[140:143], v[188:191], v[44:47]
	v_mfma_f32_16x16x32_bf16 v[28:31], v[136:139], v[192:195], 0
	v_mfma_f32_16x16x32_bf16 v[28:31], v[140:143], v[200:203], v[28:31]
	v_mfma_f32_16x16x32_bf16 v[12:15], v[136:139], v[204:207], 0
	v_mfma_f32_16x16x32_bf16 v[12:15], v[140:143], v[208:211], v[12:15]
	v_mfma_f32_16x16x32_bf16 v[48:51], v[144:147], v[160:163], 0
	v_mfma_f32_16x16x32_bf16 v[48:51], v[148:151], v[180:183], v[48:51]
	v_mfma_f32_16x16x32_bf16 v[32:35], v[144:147], v[184:187], 0
	v_mfma_f32_16x16x32_bf16 v[32:35], v[148:151], v[188:191], v[32:35]
	v_mfma_f32_16x16x32_bf16 v[16:19], v[144:147], v[192:195], 0
	v_mfma_f32_16x16x32_bf16 v[16:19], v[148:151], v[200:203], v[16:19]
	v_mfma_f32_16x16x32_bf16 v[0:3], v[144:147], v[204:207], 0
	v_mfma_f32_16x16x32_bf16 v[0:3], v[148:151], v[208:211], v[0:3]
	v_mfma_f32_16x16x32_bf16 v[52:55], v[152:155], v[160:163], 0
	v_mfma_f32_16x16x32_bf16 v[52:55], v[156:159], v[180:183], v[52:55]
	v_mfma_f32_16x16x32_bf16 v[36:39], v[152:155], v[184:187], 0
	v_mfma_f32_16x16x32_bf16 v[36:39], v[156:159], v[188:191], v[36:39]
	s_setprio 2
	s_barrier
	v_mfma_f32_16x16x32_bf16 v[20:23], v[152:155], v[192:195], 0
	v_mfma_f32_16x16x32_bf16 v[20:23], v[156:159], v[200:203], v[20:23]
	v_mfma_f32_16x16x32_bf16 v[4:7], v[152:155], v[204:207], 0
	v_mfma_f32_16x16x32_bf16 v[4:7], v[156:159], v[208:211], v[4:7]
	s_setprio 0
	s_add_i32 s54, 0, 0x18000
	s_add_i32 s55, 0, 0x1c000
	v_add_u32_e32 v140, s54, v196
	v_add_u32_e32 v156, s55, v196
	ds_read_b128 v[128:131], v140
	ds_read_b128 v[132:135], v140 offset:1024
	ds_read_b128 v[136:139], v140 offset:2048
	ds_read_b128 v[140:143], v140 offset:3072
	ds_read_b128 v[144:147], v156
	ds_read_b128 v[148:151], v156 offset:1024
	ds_read_b128 v[152:155], v156 offset:2048
	ds_read_b128 v[156:159], v156 offset:3072
	s_add_u32 s24, s28, 0xb0000
	s_addc_u32 s25, s29, 0
	s_mov_b32 m0, s38
	v_lshl_add_u64 v[220:221], s[24:25], 0, v[164:165]
	ds_read_b128 v[160:163], v199 offset:32768
	ds_read_b128 v[180:183], v199 offset:33792
	ds_read_b128 v[184:187], v199 offset:34816
	ds_read_b128 v[188:191], v199 offset:35840
	ds_read_b128 v[192:195], v199 offset:36864
	ds_read_b128 v[200:203], v199 offset:37888
	ds_read_b128 v[204:207], v199 offset:38912
	ds_read_b128 v[208:211], v199 offset:39936
	global_load_lds_dwordx4 v[220:221], off
	s_mov_b32 m0, s39
	v_lshl_add_u64 v[220:221], s[24:25], 0, v[168:169]
	global_load_lds_dwordx4 v[220:221], off
	s_waitcnt vmcnt(8) lgkmcnt(0)
	s_barrier
	s_setprio 1
	v_mfma_f32_16x16x32_bf16 v[124:127], v[128:131], v[160:163], v[124:127]
	v_mfma_f32_16x16x32_bf16 v[124:127], v[132:135], v[180:183], v[124:127]
	v_mfma_f32_16x16x32_bf16 v[116:119], v[128:131], v[184:187], v[116:119]
	v_mfma_f32_16x16x32_bf16 v[116:119], v[132:135], v[188:191], v[116:119]
	v_mfma_f32_16x16x32_bf16 v[88:91], v[128:131], v[192:195], v[88:91]
	v_mfma_f32_16x16x32_bf16 v[88:91], v[132:135], v[200:203], v[88:91]
	v_mfma_f32_16x16x32_bf16 v[72:75], v[128:131], v[204:207], v[72:75]
	v_mfma_f32_16x16x32_bf16 v[72:75], v[132:135], v[208:211], v[72:75]
	v_mfma_f32_16x16x32_bf16 v[120:123], v[136:139], v[160:163], v[120:123]
	v_mfma_f32_16x16x32_bf16 v[120:123], v[140:143], v[180:183], v[120:123]
	v_mfma_f32_16x16x32_bf16 v[108:111], v[136:139], v[184:187], v[108:111]
	v_mfma_f32_16x16x32_bf16 v[108:111], v[140:143], v[188:191], v[108:111]
	v_mfma_f32_16x16x32_bf16 v[100:103], v[136:139], v[192:195], v[100:103]
	v_mfma_f32_16x16x32_bf16 v[100:103], v[140:143], v[200:203], v[100:103]
	v_mfma_f32_16x16x32_bf16 v[76:79], v[136:139], v[204:207], v[76:79]
	v_mfma_f32_16x16x32_bf16 v[76:79], v[140:143], v[208:211], v[76:79]
	v_mfma_f32_16x16x32_bf16 v[112:115], v[144:147], v[160:163], v[112:115]
	v_mfma_f32_16x16x32_bf16 v[112:115], v[148:151], v[180:183], v[112:115]
	v_mfma_f32_16x16x32_bf16 v[96:99], v[144:147], v[184:187], v[96:99]
	v_mfma_f32_16x16x32_bf16 v[96:99], v[148:151], v[188:191], v[96:99]
	v_mfma_f32_16x16x32_bf16 v[80:83], v[144:147], v[192:195], v[80:83]
	v_mfma_f32_16x16x32_bf16 v[80:83], v[148:151], v[200:203], v[80:83]
	v_mfma_f32_16x16x32_bf16 v[64:67], v[144:147], v[204:207], v[64:67]
	v_mfma_f32_16x16x32_bf16 v[64:67], v[148:151], v[208:211], v[64:67]
	v_mfma_f32_16x16x32_bf16 v[104:107], v[152:155], v[160:163], v[104:107]
	v_mfma_f32_16x16x32_bf16 v[104:107], v[156:159], v[180:183], v[104:107]
	v_mfma_f32_16x16x32_bf16 v[92:95], v[152:155], v[184:187], v[92:95]
	v_mfma_f32_16x16x32_bf16 v[92:95], v[156:159], v[188:191], v[92:95]
	s_setprio 2
	s_barrier
	v_mfma_f32_16x16x32_bf16 v[84:87], v[152:155], v[192:195], v[84:87]
	v_mfma_f32_16x16x32_bf16 v[84:87], v[156:159], v[200:203], v[84:87]
	v_mfma_f32_16x16x32_bf16 v[68:71], v[152:155], v[204:207], v[68:71]
	v_mfma_f32_16x16x32_bf16 v[68:71], v[156:159], v[208:211], v[68:71]
	s_setprio 2
	s_add_i32 s24, s54, s35
	v_lshl_add_u64 v[212:213], v[212:213], 0, s[16:17]
	s_mov_b32 m0, s24
	ds_read_b128 v[160:163], v199 offset:49152
	ds_read_b128 v[180:183], v199 offset:50176
	ds_read_b128 v[184:187], v199 offset:51200
	ds_read_b128 v[188:191], v199 offset:52224
	ds_read_b128 v[192:195], v199 offset:53248
	ds_read_b128 v[200:203], v199 offset:54272
	ds_read_b128 v[204:207], v199 offset:55296
	ds_read_b128 v[208:211], v199 offset:56320
	global_load_lds_dwordx4 v[212:213], off
	s_add_i32 m0, s24, 0x2000
	s_add_u32 s24, s26, 0xb0080
	v_lshl_add_u64 v[212:213], v[214:215], 0, s[16:17]
	s_addc_u32 s25, s27, 0
	s_add_i32 s26, s55, s35
	global_load_lds_dwordx4 v[212:213], off
	s_mov_b32 m0, s26
	v_lshl_add_u64 v[212:213], s[24:25], 0, v[166:167]
	global_load_lds_dwordx4 v[212:213], off
	s_add_i32 m0, s26, 0x2000
	v_lshl_add_u64 v[212:213], s[24:25], 0, v[170:171]
	global_load_lds_dwordx4 v[212:213], off
	s_mov_b32 m0, s41
	v_lshl_add_u64 v[212:213], v[216:217], 0, s[16:17]
	global_load_lds_dwordx4 v[212:213], off
	s_mov_b32 m0, s42
	v_lshl_add_u64 v[212:213], v[218:219], 0, s[16:17]
	global_load_lds_dwordx4 v[212:213], off
	s_waitcnt vmcnt(8) lgkmcnt(0)
	s_barrier
	s_setprio 1
	v_mfma_f32_16x16x32_bf16 v[56:59], v[128:131], v[160:163], v[56:59]
	v_mfma_f32_16x16x32_bf16 v[56:59], v[132:135], v[180:183], v[56:59]
	v_mfma_f32_16x16x32_bf16 v[40:43], v[128:131], v[184:187], v[40:43]
	v_mfma_f32_16x16x32_bf16 v[40:43], v[132:135], v[188:191], v[40:43]
	v_mfma_f32_16x16x32_bf16 v[24:27], v[128:131], v[192:195], v[24:27]
	v_mfma_f32_16x16x32_bf16 v[24:27], v[132:135], v[200:203], v[24:27]
	v_mfma_f32_16x16x32_bf16 v[8:11], v[128:131], v[204:207], v[8:11]
	v_mfma_f32_16x16x32_bf16 v[8:11], v[132:135], v[208:211], v[8:11]
	v_mfma_f32_16x16x32_bf16 v[60:63], v[136:139], v[160:163], v[60:63]
	v_mfma_f32_16x16x32_bf16 v[60:63], v[140:143], v[180:183], v[60:63]
	v_mfma_f32_16x16x32_bf16 v[44:47], v[136:139], v[184:187], v[44:47]
	v_mfma_f32_16x16x32_bf16 v[44:47], v[140:143], v[188:191], v[44:47]
	v_mfma_f32_16x16x32_bf16 v[28:31], v[136:139], v[192:195], v[28:31]
	v_mfma_f32_16x16x32_bf16 v[28:31], v[140:143], v[200:203], v[28:31]
	v_mfma_f32_16x16x32_bf16 v[12:15], v[136:139], v[204:207], v[12:15]
	v_mfma_f32_16x16x32_bf16 v[12:15], v[140:143], v[208:211], v[12:15]
	v_mfma_f32_16x16x32_bf16 v[48:51], v[144:147], v[160:163], v[48:51]
	v_mfma_f32_16x16x32_bf16 v[48:51], v[148:151], v[180:183], v[48:51]
	v_mfma_f32_16x16x32_bf16 v[32:35], v[144:147], v[184:187], v[32:35]
	v_mfma_f32_16x16x32_bf16 v[32:35], v[148:151], v[188:191], v[32:35]
	v_mfma_f32_16x16x32_bf16 v[16:19], v[144:147], v[192:195], v[16:19]
	v_mfma_f32_16x16x32_bf16 v[16:19], v[148:151], v[200:203], v[16:19]
	v_mfma_f32_16x16x32_bf16 v[0:3], v[144:147], v[204:207], v[0:3]
	v_mfma_f32_16x16x32_bf16 v[0:3], v[148:151], v[208:211], v[0:3]
	v_mfma_f32_16x16x32_bf16 v[52:55], v[152:155], v[160:163], v[52:55]
	v_mfma_f32_16x16x32_bf16 v[52:55], v[156:159], v[180:183], v[52:55]
	v_mfma_f32_16x16x32_bf16 v[36:39], v[152:155], v[184:187], v[36:39]
	v_mfma_f32_16x16x32_bf16 v[36:39], v[156:159], v[188:191], v[36:39]
	s_setprio 2
	s_barrier
	v_mfma_f32_16x16x32_bf16 v[20:23], v[152:155], v[192:195], v[20:23]
	v_mfma_f32_16x16x32_bf16 v[20:23], v[156:159], v[200:203], v[20:23]
	v_mfma_f32_16x16x32_bf16 v[4:7], v[152:155], v[204:207], v[4:7]
	v_mfma_f32_16x16x32_bf16 v[4:7], v[156:159], v[208:211], v[4:7]
	s_setprio 0
	s_add_i32 s53, s53, 2
	s_add_u32 s51, s51, 0x100
	s_addc_u32 s52, s52, 0
	s_cmp_gt_u32 s53, 41
	s_mov_b64 s[24:25], s[4:5]
.LBB0_1310:
	ds_read_b128 v[128:131], v197
	ds_read_b128 v[132:135], v197 offset:1024
	ds_read_b128 v[136:139], v197 offset:2048
	ds_read_b128 v[140:143], v197 offset:3072
	ds_read_b128 v[144:147], v198
	ds_read_b128 v[148:151], v198 offset:1024
	ds_read_b128 v[152:155], v198 offset:2048
	ds_read_b128 v[156:159], v198 offset:3072
	s_add_u32 s4, s24, 0x100
	s_addc_u32 s5, s25, 0
	s_cmp_eq_u32 s53, 40
	s_cselect_b32 s29, s21, s5
	s_cselect_b32 s28, s20, s4
	s_cselect_b32 s27, s23, s52
	s_cselect_b32 s26, s22, s51
	v_lshl_add_u64 v[212:213], s[24:25], 0, v[172:173]
	s_add_i32 m0, s36, 0xc000
	ds_read_b128 v[160:163], v199
	ds_read_b128 v[180:183], v199 offset:1024
	ds_read_b128 v[184:187], v199 offset:2048
	ds_read_b128 v[188:191], v199 offset:3072
	ds_read_b128 v[192:195], v199 offset:4096
	ds_read_b128 v[200:203], v199 offset:5120
	ds_read_b128 v[204:207], v199 offset:6144
	ds_read_b128 v[208:211], v199 offset:7168
	global_load_lds_dwordx4 v[212:213], off
	s_add_i32 m0, s36, 0xe000
	v_lshl_add_u64 v[212:213], s[24:25], 0, v[174:175]
	global_load_lds_dwordx4 v[212:213], off
	s_waitcnt vmcnt(8) lgkmcnt(0)
	s_barrier
	s_setprio 1
	v_mfma_f32_16x16x32_bf16 v[124:127], v[128:131], v[160:163], v[124:127]
	v_mfma_f32_16x16x32_bf16 v[124:127], v[132:135], v[180:183], v[124:127]
	v_mfma_f32_16x16x32_bf16 v[116:119], v[128:131], v[184:187], v[116:119]
	v_mfma_f32_16x16x32_bf16 v[116:119], v[132:135], v[188:191], v[116:119]
	v_mfma_f32_16x16x32_bf16 v[88:91], v[128:131], v[192:195], v[88:91]
	v_mfma_f32_16x16x32_bf16 v[88:91], v[132:135], v[200:203], v[88:91]
	v_mfma_f32_16x16x32_bf16 v[72:75], v[128:131], v[204:207], v[72:75]
	v_mfma_f32_16x16x32_bf16 v[72:75], v[132:135], v[208:211], v[72:75]
	v_mfma_f32_16x16x32_bf16 v[120:123], v[136:139], v[160:163], v[120:123]
	v_mfma_f32_16x16x32_bf16 v[120:123], v[140:143], v[180:183], v[120:123]
	v_mfma_f32_16x16x32_bf16 v[108:111], v[136:139], v[184:187], v[108:111]
	v_mfma_f32_16x16x32_bf16 v[108:111], v[140:143], v[188:191], v[108:111]
	v_mfma_f32_16x16x32_bf16 v[100:103], v[136:139], v[192:195], v[100:103]
	v_mfma_f32_16x16x32_bf16 v[100:103], v[140:143], v[200:203], v[100:103]
	v_mfma_f32_16x16x32_bf16 v[76:79], v[136:139], v[204:207], v[76:79]
	v_mfma_f32_16x16x32_bf16 v[76:79], v[140:143], v[208:211], v[76:79]
	v_mfma_f32_16x16x32_bf16 v[112:115], v[144:147], v[160:163], v[112:115]
	v_mfma_f32_16x16x32_bf16 v[112:115], v[148:151], v[180:183], v[112:115]
	v_mfma_f32_16x16x32_bf16 v[96:99], v[144:147], v[184:187], v[96:99]
	v_mfma_f32_16x16x32_bf16 v[96:99], v[148:151], v[188:191], v[96:99]
	v_mfma_f32_16x16x32_bf16 v[80:83], v[144:147], v[192:195], v[80:83]
	v_mfma_f32_16x16x32_bf16 v[80:83], v[148:151], v[200:203], v[80:83]
	v_mfma_f32_16x16x32_bf16 v[64:67], v[144:147], v[204:207], v[64:67]
	v_mfma_f32_16x16x32_bf16 v[64:67], v[148:151], v[208:211], v[64:67]
	v_mfma_f32_16x16x32_bf16 v[104:107], v[152:155], v[160:163], v[104:107]
	v_mfma_f32_16x16x32_bf16 v[104:107], v[156:159], v[180:183], v[104:107]
	v_mfma_f32_16x16x32_bf16 v[92:95], v[152:155], v[184:187], v[92:95]
	v_mfma_f32_16x16x32_bf16 v[92:95], v[156:159], v[188:191], v[92:95]
	s_setprio 2
	s_barrier
	v_mfma_f32_16x16x32_bf16 v[84:87], v[152:155], v[192:195], v[84:87]
	v_mfma_f32_16x16x32_bf16 v[84:87], v[156:159], v[200:203], v[84:87]
	v_mfma_f32_16x16x32_bf16 v[68:71], v[152:155], v[204:207], v[68:71]
	v_mfma_f32_16x16x32_bf16 v[68:71], v[156:159], v[208:211], v[68:71]
	s_setprio 2
	s_add_i32 s24, s45, s35
	v_lshl_add_u64 v[212:213], s[26:27], 0, v[166:167]
	s_mov_b32 m0, s24
	ds_read_b128 v[160:163], v199 offset:16384
	ds_read_b128 v[180:183], v199 offset:17408
	ds_read_b128 v[184:187], v199 offset:18432
	ds_read_b128 v[188:191], v199 offset:19456
	ds_read_b128 v[192:195], v199 offset:20480
	ds_read_b128 v[200:203], v199 offset:21504
	ds_read_b128 v[204:207], v199 offset:22528
	ds_read_b128 v[208:211], v199 offset:23552
	global_load_lds_dwordx4 v[212:213], off
	s_add_i32 m0, s24, 0x2000
	s_add_u32 s24, s26, 0xb0000
	v_lshl_add_u64 v[214:215], s[26:27], 0, v[170:171]
	s_addc_u32 s25, s27, 0
	s_add_i32 s54, s46, s35
	global_load_lds_dwordx4 v[214:215], off
	v_lshl_add_u64 v[216:217], s[24:25], 0, v[166:167]
	s_mov_b32 m0, s54
	v_lshl_add_u64 v[218:219], s[28:29], 0, v[168:169]
	global_load_lds_dwordx4 v[216:217], off
	s_add_i32 m0, s54, 0x2000
	v_lshl_add_u64 v[216:217], s[24:25], 0, v[170:171]
	global_load_lds_dwordx4 v[216:217], off
	s_mov_b32 m0, s36
	v_lshl_add_u64 v[216:217], s[28:29], 0, v[164:165]
	global_load_lds_dwordx4 v[216:217], off
	s_mov_b32 m0, s37
	s_nop 0
	global_load_lds_dwordx4 v[218:219], off
	s_waitcnt vmcnt(8) lgkmcnt(0)
	s_barrier
	s_setprio 1
	v_mfma_f32_16x16x32_bf16 v[56:59], v[128:131], v[160:163], v[56:59]
	v_mfma_f32_16x16x32_bf16 v[56:59], v[132:135], v[180:183], v[56:59]
	v_mfma_f32_16x16x32_bf16 v[40:43], v[128:131], v[184:187], v[40:43]
	v_mfma_f32_16x16x32_bf16 v[40:43], v[132:135], v[188:191], v[40:43]
	v_mfma_f32_16x16x32_bf16 v[24:27], v[128:131], v[192:195], v[24:27]
	v_mfma_f32_16x16x32_bf16 v[24:27], v[132:135], v[200:203], v[24:27]
	v_mfma_f32_16x16x32_bf16 v[8:11], v[128:131], v[204:207], v[8:11]
	v_mfma_f32_16x16x32_bf16 v[8:11], v[132:135], v[208:211], v[8:11]
	v_mfma_f32_16x16x32_bf16 v[60:63], v[136:139], v[160:163], v[60:63]
	v_mfma_f32_16x16x32_bf16 v[60:63], v[140:143], v[180:183], v[60:63]
	v_mfma_f32_16x16x32_bf16 v[44:47], v[136:139], v[184:187], v[44:47]
	v_mfma_f32_16x16x32_bf16 v[44:47], v[140:143], v[188:191], v[44:47]
	v_mfma_f32_16x16x32_bf16 v[28:31], v[136:139], v[192:195], v[28:31]
	v_mfma_f32_16x16x32_bf16 v[28:31], v[140:143], v[200:203], v[28:31]
	v_mfma_f32_16x16x32_bf16 v[12:15], v[136:139], v[204:207], v[12:15]
	v_mfma_f32_16x16x32_bf16 v[12:15], v[140:143], v[208:211], v[12:15]
	v_mfma_f32_16x16x32_bf16 v[48:51], v[144:147], v[160:163], v[48:51]
	v_mfma_f32_16x16x32_bf16 v[48:51], v[148:151], v[180:183], v[48:51]
	v_mfma_f32_16x16x32_bf16 v[32:35], v[144:147], v[184:187], v[32:35]
	v_mfma_f32_16x16x32_bf16 v[32:35], v[148:151], v[188:191], v[32:35]
	v_mfma_f32_16x16x32_bf16 v[16:19], v[144:147], v[192:195], v[16:19]
	v_mfma_f32_16x16x32_bf16 v[16:19], v[148:151], v[200:203], v[16:19]
	v_mfma_f32_16x16x32_bf16 v[0:3], v[144:147], v[204:207], v[0:3]
	v_mfma_f32_16x16x32_bf16 v[0:3], v[148:151], v[208:211], v[0:3]
	v_mfma_f32_16x16x32_bf16 v[52:55], v[152:155], v[160:163], v[52:55]
	v_mfma_f32_16x16x32_bf16 v[52:55], v[156:159], v[180:183], v[52:55]
	v_mfma_f32_16x16x32_bf16 v[36:39], v[152:155], v[184:187], v[36:39]
	v_mfma_f32_16x16x32_bf16 v[36:39], v[156:159], v[188:191], v[36:39]
	s_setprio 2
	s_barrier
	v_mfma_f32_16x16x32_bf16 v[20:23], v[152:155], v[192:195], v[20:23]
	v_mfma_f32_16x16x32_bf16 v[20:23], v[156:159], v[200:203], v[20:23]
	v_mfma_f32_16x16x32_bf16 v[4:7], v[152:155], v[204:207], v[4:7]
	v_mfma_f32_16x16x32_bf16 v[4:7], v[156:159], v[208:211], v[4:7]
	s_setprio 0
	s_add_i32 s54, 0, 0x18000
	s_add_i32 s55, 0, 0x1c000
	v_add_u32_e32 v140, s54, v196
	v_add_u32_e32 v156, s55, v196
	ds_read_b128 v[128:131], v140
	ds_read_b128 v[132:135], v140 offset:1024
	ds_read_b128 v[136:139], v140 offset:2048
	ds_read_b128 v[140:143], v140 offset:3072
	ds_read_b128 v[144:147], v156
	ds_read_b128 v[148:151], v156 offset:1024
	ds_read_b128 v[152:155], v156 offset:2048
	ds_read_b128 v[156:159], v156 offset:3072
	s_add_u32 s24, s28, 0xb0000
	s_addc_u32 s25, s29, 0
	s_mov_b32 m0, s38
	v_lshl_add_u64 v[220:221], s[24:25], 0, v[164:165]
	ds_read_b128 v[160:163], v199 offset:32768
	ds_read_b128 v[180:183], v199 offset:33792
	ds_read_b128 v[184:187], v199 offset:34816
	ds_read_b128 v[188:191], v199 offset:35840
	ds_read_b128 v[192:195], v199 offset:36864
	ds_read_b128 v[200:203], v199 offset:37888
	ds_read_b128 v[204:207], v199 offset:38912
	ds_read_b128 v[208:211], v199 offset:39936
	global_load_lds_dwordx4 v[220:221], off
	s_mov_b32 m0, s39
	v_lshl_add_u64 v[220:221], s[24:25], 0, v[168:169]
	global_load_lds_dwordx4 v[220:221], off
	s_waitcnt vmcnt(8) lgkmcnt(0)
	s_barrier
	s_setprio 1
	v_mfma_f32_16x16x32_bf16 v[124:127], v[128:131], v[160:163], v[124:127]
	v_mfma_f32_16x16x32_bf16 v[124:127], v[132:135], v[180:183], v[124:127]
	v_mfma_f32_16x16x32_bf16 v[116:119], v[128:131], v[184:187], v[116:119]
	v_mfma_f32_16x16x32_bf16 v[116:119], v[132:135], v[188:191], v[116:119]
	v_mfma_f32_16x16x32_bf16 v[88:91], v[128:131], v[192:195], v[88:91]
	v_mfma_f32_16x16x32_bf16 v[88:91], v[132:135], v[200:203], v[88:91]
	v_mfma_f32_16x16x32_bf16 v[72:75], v[128:131], v[204:207], v[72:75]
	v_mfma_f32_16x16x32_bf16 v[72:75], v[132:135], v[208:211], v[72:75]
	v_mfma_f32_16x16x32_bf16 v[120:123], v[136:139], v[160:163], v[120:123]
	v_mfma_f32_16x16x32_bf16 v[120:123], v[140:143], v[180:183], v[120:123]
	v_mfma_f32_16x16x32_bf16 v[108:111], v[136:139], v[184:187], v[108:111]
	v_mfma_f32_16x16x32_bf16 v[108:111], v[140:143], v[188:191], v[108:111]
	v_mfma_f32_16x16x32_bf16 v[100:103], v[136:139], v[192:195], v[100:103]
	v_mfma_f32_16x16x32_bf16 v[100:103], v[140:143], v[200:203], v[100:103]
	v_mfma_f32_16x16x32_bf16 v[76:79], v[136:139], v[204:207], v[76:79]
	v_mfma_f32_16x16x32_bf16 v[76:79], v[140:143], v[208:211], v[76:79]
	v_mfma_f32_16x16x32_bf16 v[112:115], v[144:147], v[160:163], v[112:115]
	v_mfma_f32_16x16x32_bf16 v[112:115], v[148:151], v[180:183], v[112:115]
	v_mfma_f32_16x16x32_bf16 v[96:99], v[144:147], v[184:187], v[96:99]
	v_mfma_f32_16x16x32_bf16 v[96:99], v[148:151], v[188:191], v[96:99]
	v_mfma_f32_16x16x32_bf16 v[80:83], v[144:147], v[192:195], v[80:83]
	v_mfma_f32_16x16x32_bf16 v[80:83], v[148:151], v[200:203], v[80:83]
	v_mfma_f32_16x16x32_bf16 v[64:67], v[144:147], v[204:207], v[64:67]
	v_mfma_f32_16x16x32_bf16 v[64:67], v[148:151], v[208:211], v[64:67]
	v_mfma_f32_16x16x32_bf16 v[104:107], v[152:155], v[160:163], v[104:107]
	v_mfma_f32_16x16x32_bf16 v[104:107], v[156:159], v[180:183], v[104:107]
	v_mfma_f32_16x16x32_bf16 v[92:95], v[152:155], v[184:187], v[92:95]
	v_mfma_f32_16x16x32_bf16 v[92:95], v[156:159], v[188:191], v[92:95]
	s_setprio 2
	s_barrier
	v_mfma_f32_16x16x32_bf16 v[84:87], v[152:155], v[192:195], v[84:87]
	v_mfma_f32_16x16x32_bf16 v[84:87], v[156:159], v[200:203], v[84:87]
	v_mfma_f32_16x16x32_bf16 v[68:71], v[152:155], v[204:207], v[68:71]
	v_mfma_f32_16x16x32_bf16 v[68:71], v[156:159], v[208:211], v[68:71]
	s_setprio 2
	s_add_i32 s24, s54, s35
	v_lshl_add_u64 v[212:213], v[212:213], 0, s[16:17]
	s_mov_b32 m0, s24
	ds_read_b128 v[160:163], v199 offset:49152
	ds_read_b128 v[180:183], v199 offset:50176
	ds_read_b128 v[184:187], v199 offset:51200
	ds_read_b128 v[188:191], v199 offset:52224
	ds_read_b128 v[192:195], v199 offset:53248
	ds_read_b128 v[200:203], v199 offset:54272
	ds_read_b128 v[204:207], v199 offset:55296
	ds_read_b128 v[208:211], v199 offset:56320
	global_load_lds_dwordx4 v[212:213], off
	s_add_i32 m0, s24, 0x2000
	s_add_u32 s24, s26, 0xb0080
	v_lshl_add_u64 v[212:213], v[214:215], 0, s[16:17]
	s_addc_u32 s25, s27, 0
	s_add_i32 s26, s55, s35
	global_load_lds_dwordx4 v[212:213], off
	s_mov_b32 m0, s26
	v_lshl_add_u64 v[212:213], s[24:25], 0, v[166:167]
	global_load_lds_dwordx4 v[212:213], off
	s_add_i32 m0, s26, 0x2000
	v_lshl_add_u64 v[212:213], s[24:25], 0, v[170:171]
	global_load_lds_dwordx4 v[212:213], off
	s_mov_b32 m0, s41
	v_lshl_add_u64 v[212:213], v[216:217], 0, s[16:17]
	global_load_lds_dwordx4 v[212:213], off
	s_mov_b32 m0, s42
	v_lshl_add_u64 v[212:213], v[218:219], 0, s[16:17]
	global_load_lds_dwordx4 v[212:213], off
	s_waitcnt vmcnt(8) lgkmcnt(0)
	s_barrier
	s_setprio 1
	v_mfma_f32_16x16x32_bf16 v[56:59], v[128:131], v[160:163], v[56:59]
	v_mfma_f32_16x16x32_bf16 v[56:59], v[132:135], v[180:183], v[56:59]
	v_mfma_f32_16x16x32_bf16 v[40:43], v[128:131], v[184:187], v[40:43]
	v_mfma_f32_16x16x32_bf16 v[40:43], v[132:135], v[188:191], v[40:43]
	v_mfma_f32_16x16x32_bf16 v[24:27], v[128:131], v[192:195], v[24:27]
	v_mfma_f32_16x16x32_bf16 v[24:27], v[132:135], v[200:203], v[24:27]
	v_mfma_f32_16x16x32_bf16 v[8:11], v[128:131], v[204:207], v[8:11]
	v_mfma_f32_16x16x32_bf16 v[8:11], v[132:135], v[208:211], v[8:11]
	v_mfma_f32_16x16x32_bf16 v[60:63], v[136:139], v[160:163], v[60:63]
	v_mfma_f32_16x16x32_bf16 v[60:63], v[140:143], v[180:183], v[60:63]
	v_mfma_f32_16x16x32_bf16 v[44:47], v[136:139], v[184:187], v[44:47]
	v_mfma_f32_16x16x32_bf16 v[44:47], v[140:143], v[188:191], v[44:47]
	v_mfma_f32_16x16x32_bf16 v[28:31], v[136:139], v[192:195], v[28:31]
	v_mfma_f32_16x16x32_bf16 v[28:31], v[140:143], v[200:203], v[28:31]
	v_mfma_f32_16x16x32_bf16 v[12:15], v[136:139], v[204:207], v[12:15]
	v_mfma_f32_16x16x32_bf16 v[12:15], v[140:143], v[208:211], v[12:15]
	v_mfma_f32_16x16x32_bf16 v[48:51], v[144:147], v[160:163], v[48:51]
	v_mfma_f32_16x16x32_bf16 v[48:51], v[148:151], v[180:183], v[48:51]
	v_mfma_f32_16x16x32_bf16 v[32:35], v[144:147], v[184:187], v[32:35]
	v_mfma_f32_16x16x32_bf16 v[32:35], v[148:151], v[188:191], v[32:35]
	v_mfma_f32_16x16x32_bf16 v[16:19], v[144:147], v[192:195], v[16:19]
	v_mfma_f32_16x16x32_bf16 v[16:19], v[148:151], v[200:203], v[16:19]
	v_mfma_f32_16x16x32_bf16 v[0:3], v[144:147], v[204:207], v[0:3]
	v_mfma_f32_16x16x32_bf16 v[0:3], v[148:151], v[208:211], v[0:3]
	v_mfma_f32_16x16x32_bf16 v[52:55], v[152:155], v[160:163], v[52:55]
	v_mfma_f32_16x16x32_bf16 v[52:55], v[156:159], v[180:183], v[52:55]
	v_mfma_f32_16x16x32_bf16 v[36:39], v[152:155], v[184:187], v[36:39]
	v_mfma_f32_16x16x32_bf16 v[36:39], v[156:159], v[188:191], v[36:39]
	s_setprio 2
	s_barrier
	v_mfma_f32_16x16x32_bf16 v[20:23], v[152:155], v[192:195], v[20:23]
	v_mfma_f32_16x16x32_bf16 v[20:23], v[156:159], v[200:203], v[20:23]
	v_mfma_f32_16x16x32_bf16 v[4:7], v[152:155], v[204:207], v[4:7]
	v_mfma_f32_16x16x32_bf16 v[4:7], v[156:159], v[208:211], v[4:7]
	s_setprio 0
	s_add_i32 s53, s53, 2
	s_add_u32 s51, s51, 0x100
	s_addc_u32 s52, s52, 0
	s_cmp_gt_u32 s53, 41
	s_mov_b64 s[24:25], s[4:5]
	s_cbranch_scc0 .LBB0_1310
